# P1 epilogue fully hand-written for all five output kinds (gla k second output from register-resident ke, no second decay-table pass); replaced compiler epilogues removed
# speedup vs baseline: 1.0257x; 1.0145x over previous
; DEV u32x2 pk4(f32x4 v) { u32x2 r = {pk_bf16(v[0], v[1]), pk_bf16(v[2], v[3])}; return r; }
; DEV f32x4 unpk4(u32x2 u) { f32x4 r = {bf_lo(u[0]), bf_hi(u[0]), bf_lo(u[1]), bf_hi(u[1])}; return r; }
;   DEV void operator()(f32x4 (&acc)[2][2][4][2], int brow, int bcol, int wr, int wc, int fr, int fq) const {
;     ...
;             const int cl = bj * 128 + wc * 32 + n * 16 + fq * 4, col = bcol + cl;
;             const int f = ((ai * 4 + m) * 2 + bj) * 2 + n;
;             const f32x4 g = unpk4(tile_get4(rl, cl));
;             f32x4 v = acc[ai][bj][m][n] * g;
;             if (step == 0) sp[(size_t)f * 512] = pk4(v);
;             else if (step == 1) sp[(size_t)f * 512] = pk4(unpk4(sp[(size_t)f * 512]) + v);
;             else tile_put4(rl, cl, pk4(unpk4(sp[(size_t)f * 512]) + v));
.Lp3l_step2:
	ds_read_b64 v[244:245], v134
	ds_read_b64 v[246:247], v135
	ds_read_b64 v[248:249], v134 offset:256
	ds_read_b64 v[250:251], v135 offset:256
	s_waitcnt lgkmcnt(3)
	v_lshlrev_b32_e32 v146, 16, v244
	v_and_b32_e32 v147, 0xffff0000, v244
	v_lshlrev_b32_e32 v148, 16, v245
	v_and_b32_e32 v149, 0xffff0000, v245
	v_pk_mul_f32 v[124:125], v[124:125], v[146:147]
	v_pk_mul_f32 v[126:127], v[126:127], v[148:149]
	v_lshlrev_b32_e32 v150, 16, v160
	v_and_b32_e32 v151, 0xffff0000, v160
	v_lshlrev_b32_e32 v152, 16, v161
	v_and_b32_e32 v153, 0xffff0000, v161
	v_pk_add_f32 v[124:125], v[124:125], v[150:151]
	v_pk_add_f32 v[126:127], v[126:127], v[152:153]
	v_cvt_pk_bf16_f32 v124, v124, v125
	v_cvt_pk_bf16_f32 v125, v126, v127
	ds_write_b64 v134, v[124:125]
	s_waitcnt lgkmcnt(2)
	v_lshlrev_b32_e32 v146, 16, v246
	v_and_b32_e32 v147, 0xffff0000, v246
	v_lshlrev_b32_e32 v148, 16, v247
	v_and_b32_e32 v149, 0xffff0000, v247
	v_pk_mul_f32 v[120:121], v[120:121], v[146:147]
	v_pk_mul_f32 v[122:123], v[122:123], v[148:149]
	v_lshlrev_b32_e32 v150, 16, v162
	v_and_b32_e32 v151, 0xffff0000, v162
	v_lshlrev_b32_e32 v152, 16, v163
	v_and_b32_e32 v153, 0xffff0000, v163
	v_pk_add_f32 v[120:121], v[120:121], v[150:151]
	v_pk_add_f32 v[122:123], v[122:123], v[152:153]
	v_cvt_pk_bf16_f32 v126, v120, v121
	v_cvt_pk_bf16_f32 v127, v122, v123
	ds_write_b64 v135, v[126:127]
	s_waitcnt lgkmcnt(1)
	v_lshlrev_b32_e32 v146, 16, v248
	v_and_b32_e32 v147, 0xffff0000, v248
	v_lshlrev_b32_e32 v148, 16, v249
	v_and_b32_e32 v149, 0xffff0000, v249
	v_pk_mul_f32 v[116:117], v[116:117], v[146:147]
	v_pk_mul_f32 v[118:119], v[118:119], v[148:149]
	v_lshlrev_b32_e32 v150, 16, v164
	v_and_b32_e32 v151, 0xffff0000, v164
	v_lshlrev_b32_e32 v152, 16, v165
	v_and_b32_e32 v153, 0xffff0000, v165
	v_pk_add_f32 v[116:117], v[116:117], v[150:151]
	v_pk_add_f32 v[118:119], v[118:119], v[152:153]
	v_cvt_pk_bf16_f32 v116, v116, v117
	v_cvt_pk_bf16_f32 v117, v118, v119
	ds_write_b64 v134, v[116:117] offset:256
	s_waitcnt lgkmcnt(0)
	v_lshlrev_b32_e32 v146, 16, v250
	v_and_b32_e32 v147, 0xffff0000, v250
	v_lshlrev_b32_e32 v148, 16, v251
	v_and_b32_e32 v149, 0xffff0000, v251
	v_pk_mul_f32 v[112:113], v[112:113], v[146:147]
	v_pk_mul_f32 v[114:115], v[114:115], v[148:149]
	v_lshlrev_b32_e32 v150, 16, v166
	v_and_b32_e32 v151, 0xffff0000, v166
	v_lshlrev_b32_e32 v152, 16, v167
	v_and_b32_e32 v153, 0xffff0000, v167
	v_pk_add_f32 v[112:113], v[112:113], v[150:151]
	v_pk_add_f32 v[114:115], v[114:115], v[152:153]
	v_cvt_pk_bf16_f32 v118, v112, v113
	v_cvt_pk_bf16_f32 v119, v114, v115
	ds_write_b64 v135, v[118:119] offset:256
	ds_read_b64 v[244:245], v134 offset:8448
	ds_read_b64 v[246:247], v135 offset:8448
	ds_read_b64 v[248:249], v134 offset:8192
	ds_read_b64 v[250:251], v135 offset:8192
	s_waitcnt lgkmcnt(3)
	v_lshlrev_b32_e32 v146, 16, v244
	v_and_b32_e32 v147, 0xffff0000, v244
	v_lshlrev_b32_e32 v148, 16, v245
	v_and_b32_e32 v149, 0xffff0000, v245
	v_pk_mul_f32 v[108:109], v[108:109], v[146:147]
	v_pk_mul_f32 v[110:111], v[110:111], v[148:149]
	v_lshlrev_b32_e32 v150, 16, v168
	v_and_b32_e32 v151, 0xffff0000, v168
	v_lshlrev_b32_e32 v152, 16, v169
	v_and_b32_e32 v153, 0xffff0000, v169
	v_pk_add_f32 v[108:109], v[108:109], v[150:151]
	v_pk_add_f32 v[110:111], v[110:111], v[152:153]
	v_cvt_pk_bf16_f32 v108, v108, v109
	v_cvt_pk_bf16_f32 v109, v110, v111
	ds_write_b64 v134, v[108:109] offset:8448
	s_waitcnt lgkmcnt(2)
	v_lshlrev_b32_e32 v146, 16, v246
	v_and_b32_e32 v147, 0xffff0000, v246
	v_lshlrev_b32_e32 v148, 16, v247
	v_and_b32_e32 v149, 0xffff0000, v247
	v_pk_mul_f32 v[104:105], v[104:105], v[146:147]
	v_pk_mul_f32 v[106:107], v[106:107], v[148:149]
	v_lshlrev_b32_e32 v150, 16, v170
	v_and_b32_e32 v151, 0xffff0000, v170
	v_lshlrev_b32_e32 v152, 16, v171
	v_and_b32_e32 v153, 0xffff0000, v171
	v_pk_add_f32 v[104:105], v[104:105], v[150:151]
	v_pk_add_f32 v[106:107], v[106:107], v[152:153]
	v_cvt_pk_bf16_f32 v110, v104, v105
	v_cvt_pk_bf16_f32 v111, v106, v107
	ds_write_b64 v135, v[110:111] offset:8448
	s_waitcnt lgkmcnt(1)
	v_lshlrev_b32_e32 v146, 16, v248
	v_and_b32_e32 v147, 0xffff0000, v248
	v_lshlrev_b32_e32 v148, 16, v249
	v_and_b32_e32 v149, 0xffff0000, v249
	v_pk_mul_f32 v[100:101], v[100:101], v[146:147]
	v_pk_mul_f32 v[102:103], v[102:103], v[148:149]
	v_lshlrev_b32_e32 v150, 16, v172
	v_and_b32_e32 v151, 0xffff0000, v172
	v_lshlrev_b32_e32 v152, 16, v173
	v_and_b32_e32 v153, 0xffff0000, v173
	v_pk_add_f32 v[100:101], v[100:101], v[150:151]
	v_pk_add_f32 v[102:103], v[102:103], v[152:153]
	v_cvt_pk_bf16_f32 v100, v100, v101
	v_cvt_pk_bf16_f32 v101, v102, v103
	ds_write_b64 v134, v[100:101] offset:8192
	s_waitcnt lgkmcnt(0)
	v_lshlrev_b32_e32 v146, 16, v250
	v_and_b32_e32 v147, 0xffff0000, v250
	v_lshlrev_b32_e32 v148, 16, v251
	v_and_b32_e32 v149, 0xffff0000, v251
	v_pk_mul_f32 v[96:97], v[96:97], v[146:147]
	v_pk_mul_f32 v[98:99], v[98:99], v[148:149]
	v_lshlrev_b32_e32 v150, 16, v174
	v_and_b32_e32 v151, 0xffff0000, v174
	v_lshlrev_b32_e32 v152, 16, v175
	v_and_b32_e32 v153, 0xffff0000, v175
	v_pk_add_f32 v[96:97], v[96:97], v[150:151]
	v_pk_add_f32 v[98:99], v[98:99], v[152:153]
	v_cvt_pk_bf16_f32 v102, v96, v97
	v_cvt_pk_bf16_f32 v103, v98, v99
	ds_write_b64 v135, v[102:103] offset:8192
	ds_read_b64 v[244:245], v134 offset:16384
	ds_read_b64 v[246:247], v135 offset:16384
	ds_read_b64 v[248:249], v134 offset:16640
	ds_read_b64 v[250:251], v135 offset:16640
	s_waitcnt lgkmcnt(3)
; DEV u32x2 pk4(f32x4 v) { u32x2 r = {pk_bf16(v[0], v[1]), pk_bf16(v[2], v[3])}; return r; }
; DEV f32x4 unpk4(u32x2 u) { f32x4 r = {bf_lo(u[0]), bf_hi(u[0]), bf_lo(u[1]), bf_hi(u[1])}; return r; }
;   DEV void operator()(f32x4 (&acc)[2][2][4][2], int brow, int bcol, int wr, int wc, int fr, int fq) const {
;     ...
;             const int cl = bj * 128 + wc * 32 + n * 16 + fq * 4, col = bcol + cl;
;             const int f = ((ai * 4 + m) * 2 + bj) * 2 + n;
;             const f32x4 g = unpk4(tile_get4(rl, cl));
;             f32x4 v = acc[ai][bj][m][n] * g;
;             if (step == 0) sp[(size_t)f * 512] = pk4(v);
;             else if (step == 1) sp[(size_t)f * 512] = pk4(unpk4(sp[(size_t)f * 512]) + v);
;             else tile_put4(rl, cl, pk4(unpk4(sp[(size_t)f * 512]) + v));
	v_lshlrev_b32_e32 v146, 16, v244
	v_and_b32_e32 v147, 0xffff0000, v244
	v_lshlrev_b32_e32 v148, 16, v245
	v_and_b32_e32 v149, 0xffff0000, v245
	v_pk_mul_f32 v[92:93], v[92:93], v[146:147]
	v_pk_mul_f32 v[94:95], v[94:95], v[148:149]
	v_lshlrev_b32_e32 v150, 16, v184
	v_and_b32_e32 v151, 0xffff0000, v184
	v_lshlrev_b32_e32 v152, 16, v185
	v_and_b32_e32 v153, 0xffff0000, v185
	v_pk_add_f32 v[92:93], v[92:93], v[150:151]
	v_pk_add_f32 v[94:95], v[94:95], v[152:153]
	v_cvt_pk_bf16_f32 v92, v92, v93
	v_cvt_pk_bf16_f32 v93, v94, v95
	ds_write_b64 v134, v[92:93] offset:16384
	s_waitcnt lgkmcnt(2)
	v_lshlrev_b32_e32 v146, 16, v246
	v_and_b32_e32 v147, 0xffff0000, v246
	v_lshlrev_b32_e32 v148, 16, v247
	v_and_b32_e32 v149, 0xffff0000, v247
	v_pk_mul_f32 v[88:89], v[88:89], v[146:147]
	v_pk_mul_f32 v[90:91], v[90:91], v[148:149]
	v_lshlrev_b32_e32 v150, 16, v186
	v_and_b32_e32 v151, 0xffff0000, v186
	v_lshlrev_b32_e32 v152, 16, v187
	v_and_b32_e32 v153, 0xffff0000, v187
	v_pk_add_f32 v[88:89], v[88:89], v[150:151]
	v_pk_add_f32 v[90:91], v[90:91], v[152:153]
	v_cvt_pk_bf16_f32 v94, v88, v89
	v_cvt_pk_bf16_f32 v95, v90, v91
	ds_write_b64 v135, v[94:95] offset:16384
	s_waitcnt lgkmcnt(1)
	v_lshlrev_b32_e32 v146, 16, v248
	v_and_b32_e32 v147, 0xffff0000, v248
	v_lshlrev_b32_e32 v148, 16, v249
	v_and_b32_e32 v149, 0xffff0000, v249
	v_pk_mul_f32 v[84:85], v[84:85], v[146:147]
	v_pk_mul_f32 v[86:87], v[86:87], v[148:149]
	v_lshlrev_b32_e32 v150, 16, v188
	v_and_b32_e32 v151, 0xffff0000, v188
	v_lshlrev_b32_e32 v152, 16, v189
	v_and_b32_e32 v153, 0xffff0000, v189
	v_pk_add_f32 v[84:85], v[84:85], v[150:151]
	v_pk_add_f32 v[86:87], v[86:87], v[152:153]
	v_cvt_pk_bf16_f32 v84, v84, v85
	v_cvt_pk_bf16_f32 v85, v86, v87
	ds_write_b64 v134, v[84:85] offset:16640
	s_waitcnt lgkmcnt(0)
	v_lshlrev_b32_e32 v146, 16, v250
	v_and_b32_e32 v147, 0xffff0000, v250
	v_lshlrev_b32_e32 v148, 16, v251
	v_and_b32_e32 v149, 0xffff0000, v251
	v_pk_mul_f32 v[80:81], v[80:81], v[146:147]
	v_pk_mul_f32 v[82:83], v[82:83], v[148:149]
	v_lshlrev_b32_e32 v150, 16, v190
	v_and_b32_e32 v151, 0xffff0000, v190
	v_lshlrev_b32_e32 v152, 16, v191
	v_and_b32_e32 v153, 0xffff0000, v191
	v_pk_add_f32 v[80:81], v[80:81], v[150:151]
	v_pk_add_f32 v[82:83], v[82:83], v[152:153]
	v_cvt_pk_bf16_f32 v86, v80, v81
	v_cvt_pk_bf16_f32 v87, v82, v83
	ds_write_b64 v135, v[86:87] offset:16640
	ds_read_b64 v[244:245], v134 offset:24832
	ds_read_b64 v[246:247], v135 offset:24832
	ds_read_b64 v[248:249], v134 offset:24576
	ds_read_b64 v[250:251], v135 offset:24576
	s_waitcnt lgkmcnt(3)
	v_lshlrev_b32_e32 v146, 16, v244
	v_and_b32_e32 v147, 0xffff0000, v244
	v_lshlrev_b32_e32 v148, 16, v245
	v_and_b32_e32 v149, 0xffff0000, v245
	v_pk_mul_f32 v[76:77], v[76:77], v[146:147]
	v_pk_mul_f32 v[78:79], v[78:79], v[148:149]
	v_lshlrev_b32_e32 v150, 16, v192
	v_and_b32_e32 v151, 0xffff0000, v192
	v_lshlrev_b32_e32 v152, 16, v193
	v_and_b32_e32 v153, 0xffff0000, v193
	v_pk_add_f32 v[76:77], v[76:77], v[150:151]
	v_pk_add_f32 v[78:79], v[78:79], v[152:153]
	v_cvt_pk_bf16_f32 v76, v76, v77
	v_cvt_pk_bf16_f32 v77, v78, v79
	ds_write_b64 v134, v[76:77] offset:24832
	s_waitcnt lgkmcnt(2)
	v_lshlrev_b32_e32 v146, 16, v246
	v_and_b32_e32 v147, 0xffff0000, v246
	v_lshlrev_b32_e32 v148, 16, v247
	v_and_b32_e32 v149, 0xffff0000, v247
	v_pk_mul_f32 v[72:73], v[72:73], v[146:147]
	v_pk_mul_f32 v[74:75], v[74:75], v[148:149]
	v_lshlrev_b32_e32 v150, 16, v194
	v_and_b32_e32 v151, 0xffff0000, v194
	v_lshlrev_b32_e32 v152, 16, v195
	v_and_b32_e32 v153, 0xffff0000, v195
	v_pk_add_f32 v[72:73], v[72:73], v[150:151]
	v_pk_add_f32 v[74:75], v[74:75], v[152:153]
	v_cvt_pk_bf16_f32 v78, v72, v73
	v_cvt_pk_bf16_f32 v79, v74, v75
	ds_write_b64 v135, v[78:79] offset:24832
	s_waitcnt lgkmcnt(1)
	v_lshlrev_b32_e32 v146, 16, v248
	v_and_b32_e32 v147, 0xffff0000, v248
	v_lshlrev_b32_e32 v148, 16, v249
	v_and_b32_e32 v149, 0xffff0000, v249
	v_pk_mul_f32 v[68:69], v[68:69], v[146:147]
	v_pk_mul_f32 v[70:71], v[70:71], v[148:149]
	v_lshlrev_b32_e32 v150, 16, v200
	v_and_b32_e32 v151, 0xffff0000, v200
	v_lshlrev_b32_e32 v152, 16, v201
	v_and_b32_e32 v153, 0xffff0000, v201
	v_pk_add_f32 v[68:69], v[68:69], v[150:151]
	v_pk_add_f32 v[70:71], v[70:71], v[152:153]
	v_cvt_pk_bf16_f32 v68, v68, v69
	v_cvt_pk_bf16_f32 v69, v70, v71
	ds_write_b64 v134, v[68:69] offset:24576
	s_waitcnt lgkmcnt(0)
	v_lshlrev_b32_e32 v146, 16, v250
	v_and_b32_e32 v147, 0xffff0000, v250
	v_lshlrev_b32_e32 v148, 16, v251
	v_and_b32_e32 v149, 0xffff0000, v251
	v_pk_mul_f32 v[64:65], v[64:65], v[146:147]
	v_pk_mul_f32 v[66:67], v[66:67], v[148:149]
	v_lshlrev_b32_e32 v150, 16, v202
	v_and_b32_e32 v151, 0xffff0000, v202
	v_lshlrev_b32_e32 v152, 16, v203
	v_and_b32_e32 v153, 0xffff0000, v203
	v_pk_add_f32 v[64:65], v[64:65], v[150:151]
	v_pk_add_f32 v[66:67], v[66:67], v[152:153]
	v_cvt_pk_bf16_f32 v70, v64, v65
	v_cvt_pk_bf16_f32 v71, v66, v67
	ds_write_b64 v135, v[70:71] offset:24576
	ds_read_b64 v[244:245], v136
	ds_read_b64 v[246:247], v137
	ds_read_b64 v[248:249], v136 offset:256
	ds_read_b64 v[250:251], v137 offset:256
	s_waitcnt lgkmcnt(3)
	v_lshlrev_b32_e32 v146, 16, v244
	v_and_b32_e32 v147, 0xffff0000, v244
	v_lshlrev_b32_e32 v148, 16, v245
	v_and_b32_e32 v149, 0xffff0000, v245
	v_pk_mul_f32 v[60:61], v[60:61], v[146:147]
	v_pk_mul_f32 v[62:63], v[62:63], v[148:149]
	v_lshlrev_b32_e32 v150, 16, v204
	v_and_b32_e32 v151, 0xffff0000, v204
	v_lshlrev_b32_e32 v152, 16, v205
	v_and_b32_e32 v153, 0xffff0000, v205
	v_pk_add_f32 v[60:61], v[60:61], v[150:151]
	v_pk_add_f32 v[62:63], v[62:63], v[152:153]
	v_cvt_pk_bf16_f32 v60, v60, v61
	v_cvt_pk_bf16_f32 v61, v62, v63
	ds_write_b64 v136, v[60:61]
	s_waitcnt lgkmcnt(2)
; DEV u32x2 pk4(f32x4 v) { u32x2 r = {pk_bf16(v[0], v[1]), pk_bf16(v[2], v[3])}; return r; }
; DEV f32x4 unpk4(u32x2 u) { f32x4 r = {bf_lo(u[0]), bf_hi(u[0]), bf_lo(u[1]), bf_hi(u[1])}; return r; }
;   DEV void operator()(f32x4 (&acc)[2][2][4][2], int brow, int bcol, int wr, int wc, int fr, int fq) const {
;     ...
;             const int cl = bj * 128 + wc * 32 + n * 16 + fq * 4, col = bcol + cl;
;             const int f = ((ai * 4 + m) * 2 + bj) * 2 + n;
;             const f32x4 g = unpk4(tile_get4(rl, cl));
;             f32x4 v = acc[ai][bj][m][n] * g;
;             if (step == 0) sp[(size_t)f * 512] = pk4(v);
;             else if (step == 1) sp[(size_t)f * 512] = pk4(unpk4(sp[(size_t)f * 512]) + v);
;             else tile_put4(rl, cl, pk4(unpk4(sp[(size_t)f * 512]) + v));
	v_lshlrev_b32_e32 v146, 16, v246
	v_and_b32_e32 v147, 0xffff0000, v246
	v_lshlrev_b32_e32 v148, 16, v247
	v_and_b32_e32 v149, 0xffff0000, v247
	v_pk_mul_f32 v[56:57], v[56:57], v[146:147]
	v_pk_mul_f32 v[58:59], v[58:59], v[148:149]
	v_lshlrev_b32_e32 v150, 16, v206
	v_and_b32_e32 v151, 0xffff0000, v206
	v_lshlrev_b32_e32 v152, 16, v207
	v_and_b32_e32 v153, 0xffff0000, v207
	v_pk_add_f32 v[56:57], v[56:57], v[150:151]
	v_pk_add_f32 v[58:59], v[58:59], v[152:153]
	v_cvt_pk_bf16_f32 v62, v56, v57
	v_cvt_pk_bf16_f32 v63, v58, v59
	ds_write_b64 v137, v[62:63]
	s_waitcnt lgkmcnt(1)
	v_lshlrev_b32_e32 v146, 16, v248
	v_and_b32_e32 v147, 0xffff0000, v248
	v_lshlrev_b32_e32 v148, 16, v249
	v_and_b32_e32 v149, 0xffff0000, v249
	v_pk_mul_f32 v[52:53], v[52:53], v[146:147]
	v_pk_mul_f32 v[54:55], v[54:55], v[148:149]
	v_lshlrev_b32_e32 v150, 16, v208
	v_and_b32_e32 v151, 0xffff0000, v208
	v_lshlrev_b32_e32 v152, 16, v209
	v_and_b32_e32 v153, 0xffff0000, v209
	v_pk_add_f32 v[52:53], v[52:53], v[150:151]
	v_pk_add_f32 v[54:55], v[54:55], v[152:153]
	v_cvt_pk_bf16_f32 v52, v52, v53
	v_cvt_pk_bf16_f32 v53, v54, v55
	ds_write_b64 v136, v[52:53] offset:256
	s_waitcnt lgkmcnt(0)
	v_lshlrev_b32_e32 v146, 16, v250
	v_and_b32_e32 v147, 0xffff0000, v250
	v_lshlrev_b32_e32 v148, 16, v251
	v_and_b32_e32 v149, 0xffff0000, v251
	v_pk_mul_f32 v[48:49], v[48:49], v[146:147]
	v_pk_mul_f32 v[50:51], v[50:51], v[148:149]
	v_lshlrev_b32_e32 v150, 16, v210
	v_and_b32_e32 v151, 0xffff0000, v210
	v_lshlrev_b32_e32 v152, 16, v211
	v_and_b32_e32 v153, 0xffff0000, v211
	v_pk_add_f32 v[48:49], v[48:49], v[150:151]
	v_pk_add_f32 v[50:51], v[50:51], v[152:153]
	v_cvt_pk_bf16_f32 v54, v48, v49
	v_cvt_pk_bf16_f32 v55, v50, v51
	ds_write_b64 v137, v[54:55] offset:256
	ds_read_b64 v[244:245], v136 offset:8448
	ds_read_b64 v[246:247], v137 offset:8448
	ds_read_b64 v[248:249], v136 offset:8192
	ds_read_b64 v[250:251], v137 offset:8192
	s_waitcnt lgkmcnt(3)
	v_lshlrev_b32_e32 v146, 16, v244
	v_and_b32_e32 v147, 0xffff0000, v244
	v_lshlrev_b32_e32 v148, 16, v245
	v_and_b32_e32 v149, 0xffff0000, v245
	v_pk_mul_f32 v[44:45], v[44:45], v[146:147]
	v_pk_mul_f32 v[46:47], v[46:47], v[148:149]
	v_lshlrev_b32_e32 v150, 16, v212
	v_and_b32_e32 v151, 0xffff0000, v212
	v_lshlrev_b32_e32 v152, 16, v213
	v_and_b32_e32 v153, 0xffff0000, v213
	v_pk_add_f32 v[44:45], v[44:45], v[150:151]
	v_pk_add_f32 v[46:47], v[46:47], v[152:153]
	v_cvt_pk_bf16_f32 v44, v44, v45
	v_cvt_pk_bf16_f32 v45, v46, v47
	ds_write_b64 v136, v[44:45] offset:8448
	s_waitcnt lgkmcnt(2)
	v_lshlrev_b32_e32 v146, 16, v246
	v_and_b32_e32 v147, 0xffff0000, v246
	v_lshlrev_b32_e32 v148, 16, v247
	v_and_b32_e32 v149, 0xffff0000, v247
	v_pk_mul_f32 v[40:41], v[40:41], v[146:147]
	v_pk_mul_f32 v[42:43], v[42:43], v[148:149]
	v_lshlrev_b32_e32 v150, 16, v214
	v_and_b32_e32 v151, 0xffff0000, v214
	v_lshlrev_b32_e32 v152, 16, v215
	v_and_b32_e32 v153, 0xffff0000, v215
	v_pk_add_f32 v[40:41], v[40:41], v[150:151]
	v_pk_add_f32 v[42:43], v[42:43], v[152:153]
	v_cvt_pk_bf16_f32 v46, v40, v41
	v_cvt_pk_bf16_f32 v47, v42, v43
	ds_write_b64 v137, v[46:47] offset:8448
	s_waitcnt lgkmcnt(1)
	v_lshlrev_b32_e32 v146, 16, v248
	v_and_b32_e32 v147, 0xffff0000, v248
	v_lshlrev_b32_e32 v148, 16, v249
	v_and_b32_e32 v149, 0xffff0000, v249
	v_pk_mul_f32 v[36:37], v[36:37], v[146:147]
	v_pk_mul_f32 v[38:39], v[38:39], v[148:149]
	v_lshlrev_b32_e32 v150, 16, v224
	v_and_b32_e32 v151, 0xffff0000, v224
	v_lshlrev_b32_e32 v152, 16, v225
	v_and_b32_e32 v153, 0xffff0000, v225
	v_pk_add_f32 v[36:37], v[36:37], v[150:151]
	v_pk_add_f32 v[38:39], v[38:39], v[152:153]
	v_cvt_pk_bf16_f32 v36, v36, v37
	v_cvt_pk_bf16_f32 v37, v38, v39
	ds_write_b64 v136, v[36:37] offset:8192
	s_waitcnt lgkmcnt(0)
	v_lshlrev_b32_e32 v146, 16, v250
	v_and_b32_e32 v147, 0xffff0000, v250
	v_lshlrev_b32_e32 v148, 16, v251
	v_and_b32_e32 v149, 0xffff0000, v251
	v_pk_mul_f32 v[32:33], v[32:33], v[146:147]
	v_pk_mul_f32 v[34:35], v[34:35], v[148:149]
	v_lshlrev_b32_e32 v150, 16, v226
	v_and_b32_e32 v151, 0xffff0000, v226
	v_lshlrev_b32_e32 v152, 16, v227
	v_and_b32_e32 v153, 0xffff0000, v227
	v_pk_add_f32 v[32:33], v[32:33], v[150:151]
	v_pk_add_f32 v[34:35], v[34:35], v[152:153]
	v_cvt_pk_bf16_f32 v38, v32, v33
	v_cvt_pk_bf16_f32 v39, v34, v35
	ds_write_b64 v137, v[38:39] offset:8192
	ds_read_b64 v[244:245], v136 offset:16384
	ds_read_b64 v[246:247], v137 offset:16384
	ds_read_b64 v[248:249], v136 offset:16640
	ds_read_b64 v[250:251], v137 offset:16640
	s_waitcnt lgkmcnt(3)
	v_lshlrev_b32_e32 v146, 16, v244
	v_and_b32_e32 v147, 0xffff0000, v244
	v_lshlrev_b32_e32 v148, 16, v245
	v_and_b32_e32 v149, 0xffff0000, v245
	v_pk_mul_f32 v[28:29], v[28:29], v[146:147]
	v_pk_mul_f32 v[30:31], v[30:31], v[148:149]
	v_lshlrev_b32_e32 v150, 16, v228
	v_and_b32_e32 v151, 0xffff0000, v228
	v_lshlrev_b32_e32 v152, 16, v229
	v_and_b32_e32 v153, 0xffff0000, v229
	v_pk_add_f32 v[28:29], v[28:29], v[150:151]
	v_pk_add_f32 v[30:31], v[30:31], v[152:153]
	v_cvt_pk_bf16_f32 v28, v28, v29
	v_cvt_pk_bf16_f32 v29, v30, v31
	ds_write_b64 v136, v[28:29] offset:16384
	s_waitcnt lgkmcnt(2)
	v_lshlrev_b32_e32 v146, 16, v246
	v_and_b32_e32 v147, 0xffff0000, v246
	v_lshlrev_b32_e32 v148, 16, v247
	v_and_b32_e32 v149, 0xffff0000, v247
	v_pk_mul_f32 v[24:25], v[24:25], v[146:147]
	v_pk_mul_f32 v[26:27], v[26:27], v[148:149]
	v_lshlrev_b32_e32 v150, 16, v230
	v_and_b32_e32 v151, 0xffff0000, v230
	v_lshlrev_b32_e32 v152, 16, v231
	v_and_b32_e32 v153, 0xffff0000, v231
	v_pk_add_f32 v[24:25], v[24:25], v[150:151]
	v_pk_add_f32 v[26:27], v[26:27], v[152:153]
	v_cvt_pk_bf16_f32 v30, v24, v25
	v_cvt_pk_bf16_f32 v31, v26, v27
	ds_write_b64 v137, v[30:31] offset:16384
	s_waitcnt lgkmcnt(1)
; DEV u32x2 pk4(f32x4 v) { u32x2 r = {pk_bf16(v[0], v[1]), pk_bf16(v[2], v[3])}; return r; }
; DEV f32x4 unpk4(u32x2 u) { f32x4 r = {bf_lo(u[0]), bf_hi(u[0]), bf_lo(u[1]), bf_hi(u[1])}; return r; }
; template <bool NT = false>
; DEV void tile_rows_out(bf16_t* __restrict__ out0, const size_t ld, const int tid) {
; #pragma unroll
;   for (int i = 0; i < 16; ++i) {
;     const int id = i * 512 + tid, r = id >> 5, pos = id & 31, c = pos ^ (r & 31);
;     const u32x4 v = *(const u32x4*)(smem + r * 512 + pos * 16);
;     if (NT) __builtin_nontemporal_store(v, (u32x4*)(out0 + (size_t)r * ld + 8 * c)); else *(u32x4*)(out0 + (size_t)r * ld + 8 * c) = v;
;   }
;   DEV void operator()(f32x4 (&acc)[2][2][4][2], int brow, int bcol, int wr, int wc, int fr, int fq) const {
;     ...
;             const f32x4 g = unpk4(tile_get4(rl, cl));
;             f32x4 v = acc[ai][bj][m][n] * g;
;             if (step == 0) sp[(size_t)f * 512] = pk4(v);
;             else if (step == 1) sp[(size_t)f * 512] = pk4(unpk4(sp[(size_t)f * 512]) + v);
;             else tile_put4(rl, cl, pk4(unpk4(sp[(size_t)f * 512]) + v));
;           }
;       }
;     if (step == 2) {
;       __syncthreads();
;       tile_rows_out(mbf + (size_t)brow * 2048 + bcol, 2048, tid);
	v_lshlrev_b32_e32 v146, 16, v248
	v_and_b32_e32 v147, 0xffff0000, v248
	v_lshlrev_b32_e32 v148, 16, v249
	v_and_b32_e32 v149, 0xffff0000, v249
	v_pk_mul_f32 v[20:21], v[20:21], v[146:147]
	v_pk_mul_f32 v[22:23], v[22:23], v[148:149]
	v_lshlrev_b32_e32 v150, 16, v232
	v_and_b32_e32 v151, 0xffff0000, v232
	v_lshlrev_b32_e32 v152, 16, v233
	v_and_b32_e32 v153, 0xffff0000, v233
	v_pk_add_f32 v[20:21], v[20:21], v[150:151]
	v_pk_add_f32 v[22:23], v[22:23], v[152:153]
	v_cvt_pk_bf16_f32 v20, v20, v21
	v_cvt_pk_bf16_f32 v21, v22, v23
	ds_write_b64 v136, v[20:21] offset:16640
	s_waitcnt lgkmcnt(0)
	v_lshlrev_b32_e32 v146, 16, v250
	v_and_b32_e32 v147, 0xffff0000, v250
	v_lshlrev_b32_e32 v148, 16, v251
	v_and_b32_e32 v149, 0xffff0000, v251
	v_pk_mul_f32 v[16:17], v[16:17], v[146:147]
	v_pk_mul_f32 v[18:19], v[18:19], v[148:149]
	v_lshlrev_b32_e32 v150, 16, v234
	v_and_b32_e32 v151, 0xffff0000, v234
	v_lshlrev_b32_e32 v152, 16, v235
	v_and_b32_e32 v153, 0xffff0000, v235
	v_pk_add_f32 v[16:17], v[16:17], v[150:151]
	v_pk_add_f32 v[18:19], v[18:19], v[152:153]
	v_cvt_pk_bf16_f32 v22, v16, v17
	v_cvt_pk_bf16_f32 v23, v18, v19
	ds_write_b64 v137, v[22:23] offset:16640
	ds_read_b64 v[244:245], v136 offset:24832
	ds_read_b64 v[246:247], v137 offset:24832
	ds_read_b64 v[248:249], v136 offset:24576
	ds_read_b64 v[250:251], v137 offset:24576
	s_waitcnt lgkmcnt(3)
	v_lshlrev_b32_e32 v146, 16, v244
	v_and_b32_e32 v147, 0xffff0000, v244
	v_lshlrev_b32_e32 v148, 16, v245
	v_and_b32_e32 v149, 0xffff0000, v245
	v_pk_mul_f32 v[12:13], v[12:13], v[146:147]
	v_pk_mul_f32 v[14:15], v[14:15], v[148:149]
	v_lshlrev_b32_e32 v150, 16, v236
	v_and_b32_e32 v151, 0xffff0000, v236
	v_lshlrev_b32_e32 v152, 16, v237
	v_and_b32_e32 v153, 0xffff0000, v237
	v_pk_add_f32 v[12:13], v[12:13], v[150:151]
	v_pk_add_f32 v[14:15], v[14:15], v[152:153]
	v_cvt_pk_bf16_f32 v12, v12, v13
	v_cvt_pk_bf16_f32 v13, v14, v15
	ds_write_b64 v136, v[12:13] offset:24832
	s_waitcnt lgkmcnt(2)
	v_lshlrev_b32_e32 v146, 16, v246
	v_and_b32_e32 v147, 0xffff0000, v246
	v_lshlrev_b32_e32 v148, 16, v247
	v_and_b32_e32 v149, 0xffff0000, v247
	v_pk_mul_f32 v[8:9], v[8:9], v[146:147]
	v_pk_mul_f32 v[10:11], v[10:11], v[148:149]
	v_lshlrev_b32_e32 v150, 16, v238
	v_and_b32_e32 v151, 0xffff0000, v238
	v_lshlrev_b32_e32 v152, 16, v239
	v_and_b32_e32 v153, 0xffff0000, v239
	v_pk_add_f32 v[8:9], v[8:9], v[150:151]
	v_pk_add_f32 v[10:11], v[10:11], v[152:153]
	v_cvt_pk_bf16_f32 v14, v8, v9
	v_cvt_pk_bf16_f32 v15, v10, v11
	ds_write_b64 v137, v[14:15] offset:24832
	s_waitcnt lgkmcnt(1)
	v_lshlrev_b32_e32 v146, 16, v248
	v_and_b32_e32 v147, 0xffff0000, v248
	v_lshlrev_b32_e32 v148, 16, v249
	v_and_b32_e32 v149, 0xffff0000, v249
	v_pk_mul_f32 v[4:5], v[4:5], v[146:147]
	v_pk_mul_f32 v[6:7], v[6:7], v[148:149]
	v_lshlrev_b32_e32 v150, 16, v240
	v_and_b32_e32 v151, 0xffff0000, v240
	v_lshlrev_b32_e32 v152, 16, v241
	v_and_b32_e32 v153, 0xffff0000, v241
	v_pk_add_f32 v[4:5], v[4:5], v[150:151]
	v_pk_add_f32 v[6:7], v[6:7], v[152:153]
	v_cvt_pk_bf16_f32 v4, v4, v5
	v_cvt_pk_bf16_f32 v5, v6, v7
	ds_write_b64 v136, v[4:5] offset:24576
	s_waitcnt lgkmcnt(0)
	v_lshlrev_b32_e32 v146, 16, v250
	v_and_b32_e32 v147, 0xffff0000, v250
	v_lshlrev_b32_e32 v148, 16, v251
	v_and_b32_e32 v149, 0xffff0000, v251
	v_pk_mul_f32 v[0:1], v[0:1], v[146:147]
	v_pk_mul_f32 v[2:3], v[2:3], v[148:149]
	v_lshlrev_b32_e32 v150, 16, v242
	v_and_b32_e32 v151, 0xffff0000, v242
	v_lshlrev_b32_e32 v152, 16, v243
	v_and_b32_e32 v153, 0xffff0000, v243
	v_pk_add_f32 v[0:1], v[0:1], v[150:151]
	v_pk_add_f32 v[2:3], v[2:3], v[152:153]
	v_cvt_pk_bf16_f32 v6, v0, v1
	v_cvt_pk_bf16_f32 v7, v2, v3
	ds_write_b64 v137, v[6:7] offset:24576
	s_lshl_b32 s16, s4, 12
	s_lshl_b32 s17, s34, 1
	s_add_i32 s16, s16, s17
	s_add_u32 s14, s79, s16
	s_addc_u32 s15, s89, 0
	v_lshrrev_b32_e32 v144, 5, v140
	v_and_b32_e32 v145, 31, v140
	v_xor_b32_e32 v145, v145, v144
	v_lshlrev_b32_e32 v156, 12, v144
	v_mov_b32_e32 v157, v156
	v_lshl_add_u32 v156, v145, 4, v156
	v_xor_b32_e32 v145, 16, v145
	v_lshl_add_u32 v157, v145, 4, v157
	v_add_u32_e32 v157, 0x10000, v157
	v_lshlrev_b32_e32 v154, 4, v140
	v_add_u32_e32 v155, 0x10000, v154
	s_waitcnt lgkmcnt(0)
	s_barrier
	ds_read_b128 v[0:3], v154
	ds_read_b128 v[4:7], v154 offset:8192
	ds_read_b128 v[8:11], v154 offset:16384
	ds_read_b128 v[12:15], v154 offset:24576
	ds_read_b128 v[16:19], v154 offset:32768
	ds_read_b128 v[20:23], v154 offset:40960
	ds_read_b128 v[24:27], v154 offset:49152
	ds_read_b128 v[28:31], v154 offset:57344
	ds_read_b128 v[32:35], v155
	ds_read_b128 v[36:39], v155 offset:8192
	ds_read_b128 v[40:43], v155 offset:16384
	ds_read_b128 v[44:47], v155 offset:24576
	ds_read_b128 v[48:51], v155 offset:32768
	ds_read_b128 v[52:55], v155 offset:40960
	ds_read_b128 v[56:59], v155 offset:49152
	ds_read_b128 v[60:63], v155 offset:57344
	s_waitcnt lgkmcnt(15)
	global_store_dwordx4 v156, v[0:3], s[14:15] sc1
	v_add_u32_e32 v156, 0x20000, v156
	s_waitcnt lgkmcnt(14)
	global_store_dwordx4 v157, v[4:7], s[14:15] sc1
	v_add_u32_e32 v157, 0x20000, v157
	s_waitcnt lgkmcnt(13)
	global_store_dwordx4 v156, v[8:11], s[14:15] sc1
	v_add_u32_e32 v156, 0x20000, v156
	s_waitcnt lgkmcnt(12)
	global_store_dwordx4 v157, v[12:15], s[14:15] sc1
	v_add_u32_e32 v157, 0x20000, v157
	s_waitcnt lgkmcnt(11)
	global_store_dwordx4 v156, v[16:19], s[14:15] sc1
	v_add_u32_e32 v156, 0x20000, v156
	s_waitcnt lgkmcnt(10)
	global_store_dwordx4 v157, v[20:23], s[14:15] sc1
	v_add_u32_e32 v157, 0x20000, v157
	s_waitcnt lgkmcnt(9)
	global_store_dwordx4 v156, v[24:27], s[14:15] sc1
	v_add_u32_e32 v156, 0x20000, v156
	s_waitcnt lgkmcnt(8)
	global_store_dwordx4 v157, v[28:31], s[14:15] sc1
	v_add_u32_e32 v157, 0x20000, v157
	s_waitcnt lgkmcnt(7)
	global_store_dwordx4 v156, v[32:35], s[14:15] sc1
	v_add_u32_e32 v156, 0x20000, v156
	s_waitcnt lgkmcnt(6)
	global_store_dwordx4 v157, v[36:39], s[14:15] sc1
	v_add_u32_e32 v157, 0x20000, v157
	s_waitcnt lgkmcnt(5)
	global_store_dwordx4 v156, v[40:43], s[14:15] sc1
	v_add_u32_e32 v156, 0x20000, v156
	s_waitcnt lgkmcnt(4)
	global_store_dwordx4 v157, v[44:47], s[14:15] sc1
	v_add_u32_e32 v157, 0x20000, v157
	s_waitcnt lgkmcnt(3)
	global_store_dwordx4 v156, v[48:51], s[14:15] sc1
	v_add_u32_e32 v156, 0x20000, v156
	s_waitcnt lgkmcnt(2)
	global_store_dwordx4 v157, v[52:55], s[14:15] sc1
	v_add_u32_e32 v157, 0x20000, v157
	s_waitcnt lgkmcnt(1)
	global_store_dwordx4 v156, v[56:59], s[14:15] sc1
	s_waitcnt lgkmcnt(0)
	global_store_dwordx4 v157, v[60:63], s[14:15] sc1
	s_branch .LBB0_1551
; DEV void panel_publish(unsigned* cnt, const int tidx) {
;   asm volatile("s_waitcnt vmcnt(0)" ::: "memory");
;   __syncthreads();
;   if (tidx == 0) {
;     __builtin_amdgcn_fence(__ATOMIC_RELEASE, "agent");
;     asm volatile("s_waitcnt vmcnt(0)" ::: "memory");
;     __hip_atomic_fetch_add(cnt, 1u, __ATOMIC_RELAXED, __HIP_MEMORY_SCOPE_AGENT);
;   }
; }
.LBB0_1551:
	v_mov_b32_e32 v0, v179
	s_waitcnt vmcnt(0)
	s_waitcnt lgkmcnt(0)
	v_cmp_eq_u32_e32 vcc, 0, v0
	s_barrier
	s_and_saveexec_b64 s[4:5], vcc
	s_cbranch_execz .LBB0_1270
	s_mov_b64 s[6:7], exec
	v_mbcnt_lo_u32_b32 v0, s6, 0
	s_waitcnt vmcnt(0)
	s_waitcnt vmcnt(0)
	v_mbcnt_hi_u32_b32 v0, s7, v0
	v_cmp_eq_u32_e32 vcc, 0, v0
	s_and_b64 s[8:9], exec, vcc
	s_mov_b64 exec, s[8:9]
	s_cbranch_execz .LBB0_1270
	v_readlane_b32 s8, v254, 0
	s_add_u32 s0, s8, s0
	v_readlane_b32 s8, v254, 1
	s_addc_u32 s1, s8, s1
	s_bcnt1_i32_b64 s6, s[6:7]
	v_mov_b32_e32 v0, s6
	global_atomic_add v177, v0, s[0:1]
	s_branch .LBB0_1270

; DEV u32x2 pk4(f32x4 v) { u32x2 r = {pk_bf16(v[0], v[1]), pk_bf16(v[2], v[3])}; return r; }
;   DEV void operator()(f32x4 (&acc)[2][2][4][2], int brow, int bcol, int wr, int wc, int fr, int fq) const {
; #pragma unroll
;     for (int ai = 0; ai < 2; ++ai)
; #pragma unroll
;       for (int m = 0; m < 4; ++m) {
;         const int rl = ai * 128 + wr * 64 + m * 16 + fr, tok = brow + rl;
; #pragma unroll
;         for (int bj = 0; bj < 2; ++bj)
; #pragma unroll
;           for (int n = 0; n < 2; ++n) {
;             const int cl = bj * 128 + wc * 32 + n * 16 + fq * 4, lc = bcol - segstart + cl;
;             f32x4 v = acc[ai][bj][m][n];
;             if (mode == 0) {
;               tile_put4(rl, cl, pk4(v * scale));
.LBB0_1580:
	s_or_b64 exec, exec, s[18:19]
	v_and_b32_e32 v128, 15, v198
	v_bfe_u32 v129, v198, 4, 2
	v_bfe_u32 v130, v198, 6, 2
	v_lshrrev_b32_e32 v131, 8, v198
	s_cmp_gt_i32 s37, 2
	s_cbranch_scc1 .Lepi_lean34
	v_and_b32_e32 v145, 1, v129
	v_lshrrev_b32_e32 v146, 1, v129
	v_lshl_add_u32 v132, v131, 6, v128
	v_lshlrev_b32_e32 v132, 9, v132
	v_lshl_add_u32 v132, v145, 3, v132
	v_lshl_add_u32 v133, v130, 2, v146
	v_xor_b32_e32 v133, v133, v128
	v_lshl_add_u32 v134, v133, 4, v132
	v_xor_b32_e32 v133, 2, v133
	v_lshl_add_u32 v135, v133, 4, v132
	v_add_u32_e32 v136, 0x10000, v134
	v_add_u32_e32 v137, 0x10000, v135
	s_mov_b32 s13, s12
	s_cmp_eq_u32 s37, 1
	s_cbranch_scc1 .Lepi_lean_silu
	s_cmp_eq_u32 s37, 2
	s_cbranch_scc1 .Lepi_lean_sigm
	v_pk_mul_f32 v[124:125], v[124:125], s[12:13]
	v_pk_mul_f32 v[126:127], v[126:127], s[12:13]
	v_cvt_pk_bf16_f32 v124, v124, v125
	v_cvt_pk_bf16_f32 v125, v126, v127
	ds_write_b64 v134, v[124:125]
	v_pk_mul_f32 v[120:121], v[120:121], s[12:13]
	v_pk_mul_f32 v[122:123], v[122:123], s[12:13]
	v_cvt_pk_bf16_f32 v120, v120, v121
	v_cvt_pk_bf16_f32 v121, v122, v123
	ds_write_b64 v135, v[120:121]
	v_pk_mul_f32 v[116:117], v[116:117], s[12:13]
	v_pk_mul_f32 v[118:119], v[118:119], s[12:13]
	v_cvt_pk_bf16_f32 v116, v116, v117
	v_cvt_pk_bf16_f32 v117, v118, v119
	ds_write_b64 v134, v[116:117] offset:256
	v_pk_mul_f32 v[112:113], v[112:113], s[12:13]
	v_pk_mul_f32 v[114:115], v[114:115], s[12:13]
	v_cvt_pk_bf16_f32 v112, v112, v113
	v_cvt_pk_bf16_f32 v113, v114, v115
	ds_write_b64 v135, v[112:113] offset:256
	v_pk_mul_f32 v[108:109], v[108:109], s[12:13]
	v_pk_mul_f32 v[110:111], v[110:111], s[12:13]
	v_cvt_pk_bf16_f32 v108, v108, v109
	v_cvt_pk_bf16_f32 v109, v110, v111
	ds_write_b64 v134, v[108:109] offset:8448
	v_pk_mul_f32 v[104:105], v[104:105], s[12:13]
	v_pk_mul_f32 v[106:107], v[106:107], s[12:13]
	v_cvt_pk_bf16_f32 v104, v104, v105
	v_cvt_pk_bf16_f32 v105, v106, v107
	ds_write_b64 v135, v[104:105] offset:8448
	v_pk_mul_f32 v[100:101], v[100:101], s[12:13]
	v_pk_mul_f32 v[102:103], v[102:103], s[12:13]
	v_cvt_pk_bf16_f32 v100, v100, v101
	v_cvt_pk_bf16_f32 v101, v102, v103
	ds_write_b64 v134, v[100:101] offset:8192
	v_pk_mul_f32 v[96:97], v[96:97], s[12:13]
	v_pk_mul_f32 v[98:99], v[98:99], s[12:13]
	v_cvt_pk_bf16_f32 v96, v96, v97
	v_cvt_pk_bf16_f32 v97, v98, v99
	ds_write_b64 v135, v[96:97] offset:8192
	v_pk_mul_f32 v[92:93], v[92:93], s[12:13]
	v_pk_mul_f32 v[94:95], v[94:95], s[12:13]
	v_cvt_pk_bf16_f32 v92, v92, v93
	v_cvt_pk_bf16_f32 v93, v94, v95
	ds_write_b64 v134, v[92:93] offset:16384
	v_pk_mul_f32 v[88:89], v[88:89], s[12:13]
	v_pk_mul_f32 v[90:91], v[90:91], s[12:13]
	v_cvt_pk_bf16_f32 v88, v88, v89
	v_cvt_pk_bf16_f32 v89, v90, v91
	ds_write_b64 v135, v[88:89] offset:16384
	v_pk_mul_f32 v[84:85], v[84:85], s[12:13]
	v_pk_mul_f32 v[86:87], v[86:87], s[12:13]
	v_cvt_pk_bf16_f32 v84, v84, v85
	v_cvt_pk_bf16_f32 v85, v86, v87
	ds_write_b64 v134, v[84:85] offset:16640
	v_pk_mul_f32 v[80:81], v[80:81], s[12:13]
	v_pk_mul_f32 v[82:83], v[82:83], s[12:13]
	v_cvt_pk_bf16_f32 v80, v80, v81
	v_cvt_pk_bf16_f32 v81, v82, v83
	ds_write_b64 v135, v[80:81] offset:16640
	v_pk_mul_f32 v[76:77], v[76:77], s[12:13]
	v_pk_mul_f32 v[78:79], v[78:79], s[12:13]
	v_cvt_pk_bf16_f32 v76, v76, v77
	v_cvt_pk_bf16_f32 v77, v78, v79
	ds_write_b64 v134, v[76:77] offset:24832
	v_pk_mul_f32 v[72:73], v[72:73], s[12:13]
	v_pk_mul_f32 v[74:75], v[74:75], s[12:13]
	v_cvt_pk_bf16_f32 v72, v72, v73
	v_cvt_pk_bf16_f32 v73, v74, v75
	ds_write_b64 v135, v[72:73] offset:24832
	v_pk_mul_f32 v[68:69], v[68:69], s[12:13]
	v_pk_mul_f32 v[70:71], v[70:71], s[12:13]
	v_cvt_pk_bf16_f32 v68, v68, v69
	v_cvt_pk_bf16_f32 v69, v70, v71
	ds_write_b64 v134, v[68:69] offset:24576
	v_pk_mul_f32 v[64:65], v[64:65], s[12:13]
	v_pk_mul_f32 v[66:67], v[66:67], s[12:13]
	v_cvt_pk_bf16_f32 v64, v64, v65
	v_cvt_pk_bf16_f32 v65, v66, v67
	ds_write_b64 v135, v[64:65] offset:24576
	v_pk_mul_f32 v[60:61], v[60:61], s[12:13]
	v_pk_mul_f32 v[62:63], v[62:63], s[12:13]
	v_cvt_pk_bf16_f32 v60, v60, v61
	v_cvt_pk_bf16_f32 v61, v62, v63
	ds_write_b64 v136, v[60:61]
	v_pk_mul_f32 v[56:57], v[56:57], s[12:13]
	v_pk_mul_f32 v[58:59], v[58:59], s[12:13]
	v_cvt_pk_bf16_f32 v56, v56, v57
	v_cvt_pk_bf16_f32 v57, v58, v59
	ds_write_b64 v137, v[56:57]
	v_pk_mul_f32 v[52:53], v[52:53], s[12:13]
	v_pk_mul_f32 v[54:55], v[54:55], s[12:13]
	v_cvt_pk_bf16_f32 v52, v52, v53
	v_cvt_pk_bf16_f32 v53, v54, v55
	ds_write_b64 v136, v[52:53] offset:256
	v_pk_mul_f32 v[48:49], v[48:49], s[12:13]
	v_pk_mul_f32 v[50:51], v[50:51], s[12:13]
	v_cvt_pk_bf16_f32 v48, v48, v49
	v_cvt_pk_bf16_f32 v49, v50, v51
	ds_write_b64 v137, v[48:49] offset:256
	v_pk_mul_f32 v[44:45], v[44:45], s[12:13]
	v_pk_mul_f32 v[46:47], v[46:47], s[12:13]
	v_cvt_pk_bf16_f32 v44, v44, v45
	v_cvt_pk_bf16_f32 v45, v46, v47
	ds_write_b64 v136, v[44:45] offset:8448
	v_pk_mul_f32 v[40:41], v[40:41], s[12:13]
	v_pk_mul_f32 v[42:43], v[42:43], s[12:13]
	v_cvt_pk_bf16_f32 v40, v40, v41
	v_cvt_pk_bf16_f32 v41, v42, v43
	ds_write_b64 v137, v[40:41] offset:8448
	v_pk_mul_f32 v[36:37], v[36:37], s[12:13]
	v_pk_mul_f32 v[38:39], v[38:39], s[12:13]
	v_cvt_pk_bf16_f32 v36, v36, v37
	v_cvt_pk_bf16_f32 v37, v38, v39
	ds_write_b64 v136, v[36:37] offset:8192
	v_pk_mul_f32 v[32:33], v[32:33], s[12:13]
	v_pk_mul_f32 v[34:35], v[34:35], s[12:13]
	v_cvt_pk_bf16_f32 v32, v32, v33
	v_cvt_pk_bf16_f32 v33, v34, v35
	ds_write_b64 v137, v[32:33] offset:8192
	v_pk_mul_f32 v[28:29], v[28:29], s[12:13]
	v_pk_mul_f32 v[30:31], v[30:31], s[12:13]
	v_cvt_pk_bf16_f32 v28, v28, v29
	v_cvt_pk_bf16_f32 v29, v30, v31
	ds_write_b64 v136, v[28:29] offset:16384
	v_pk_mul_f32 v[24:25], v[24:25], s[12:13]
	v_pk_mul_f32 v[26:27], v[26:27], s[12:13]
	v_cvt_pk_bf16_f32 v24, v24, v25
	v_cvt_pk_bf16_f32 v25, v26, v27
	ds_write_b64 v137, v[24:25] offset:16384
	v_pk_mul_f32 v[20:21], v[20:21], s[12:13]
	v_pk_mul_f32 v[22:23], v[22:23], s[12:13]
	v_cvt_pk_bf16_f32 v20, v20, v21
	v_cvt_pk_bf16_f32 v21, v22, v23
	ds_write_b64 v136, v[20:21] offset:16640
	v_pk_mul_f32 v[16:17], v[16:17], s[12:13]
	v_pk_mul_f32 v[18:19], v[18:19], s[12:13]
	v_cvt_pk_bf16_f32 v16, v16, v17
	v_cvt_pk_bf16_f32 v17, v18, v19
	ds_write_b64 v137, v[16:17] offset:16640
	v_pk_mul_f32 v[12:13], v[12:13], s[12:13]
	v_pk_mul_f32 v[14:15], v[14:15], s[12:13]
	v_cvt_pk_bf16_f32 v12, v12, v13
	v_cvt_pk_bf16_f32 v13, v14, v15
	ds_write_b64 v136, v[12:13] offset:24832
	v_pk_mul_f32 v[8:9], v[8:9], s[12:13]
	v_pk_mul_f32 v[10:11], v[10:11], s[12:13]
	v_cvt_pk_bf16_f32 v8, v8, v9
	v_cvt_pk_bf16_f32 v9, v10, v11
	ds_write_b64 v137, v[8:9] offset:24832
	v_pk_mul_f32 v[4:5], v[4:5], s[12:13]
	v_pk_mul_f32 v[6:7], v[6:7], s[12:13]
	v_cvt_pk_bf16_f32 v4, v4, v5
	v_cvt_pk_bf16_f32 v5, v6, v7
	ds_write_b64 v136, v[4:5] offset:24576
	v_pk_mul_f32 v[0:1], v[0:1], s[12:13]
	v_pk_mul_f32 v[2:3], v[2:3], s[12:13]
	v_cvt_pk_bf16_f32 v0, v0, v1
	v_cvt_pk_bf16_f32 v1, v2, v3
	ds_write_b64 v137, v[0:1] offset:24576
	s_branch .Lepi_lean_rows

; DEV u32x2 pk4(f32x4 v) { u32x2 r = {pk_bf16(v[0], v[1]), pk_bf16(v[2], v[3])}; return r; }
; DEV float fsigmoid(float x) { return 1.f / (1.f + __expf(-x)); }
;   DEV void operator()(f32x4 (&acc)[2][2][4][2], int brow, int bcol, int wr, int wc, int fr, int fq) const {
;     ...
;             } else if (mode == 1) {
;               for (int j = 0; j < 4; ++j) v[j] = v[j] * fsigmoid(v[j]);
;               tile_put4(rl, cl, pk4(v));
.Lepi_lean_silu:
	v_mul_f32_e32 v148, 0xbfb8aa3b, v124
	v_mul_f32_e32 v149, 0xbfb8aa3b, v125
	v_mul_f32_e32 v150, 0xbfb8aa3b, v126
	v_mul_f32_e32 v151, 0xbfb8aa3b, v127
	v_exp_f32_e32 v148, v148
	v_exp_f32_e32 v149, v149
	v_exp_f32_e32 v150, v150
	v_exp_f32_e32 v151, v151
	v_pk_add_f32 v[148:149], v[148:149], 1.0 op_sel_hi:[1,0]
	v_pk_add_f32 v[150:151], v[150:151], 1.0 op_sel_hi:[1,0]
	v_rcp_f32_e32 v148, v148
	v_rcp_f32_e32 v149, v149
	v_rcp_f32_e32 v150, v150
	v_rcp_f32_e32 v151, v151
	v_pk_mul_f32 v[124:125], v[124:125], v[148:149]
	v_pk_mul_f32 v[126:127], v[126:127], v[150:151]
	v_cvt_pk_bf16_f32 v124, v124, v125
	v_cvt_pk_bf16_f32 v125, v126, v127
	ds_write_b64 v134, v[124:125]
	v_mul_f32_e32 v152, 0xbfb8aa3b, v120
	v_mul_f32_e32 v153, 0xbfb8aa3b, v121
	v_mul_f32_e32 v154, 0xbfb8aa3b, v122
	v_mul_f32_e32 v155, 0xbfb8aa3b, v123
	v_exp_f32_e32 v152, v152
	v_exp_f32_e32 v153, v153
	v_exp_f32_e32 v154, v154
	v_exp_f32_e32 v155, v155
	v_pk_add_f32 v[152:153], v[152:153], 1.0 op_sel_hi:[1,0]
	v_pk_add_f32 v[154:155], v[154:155], 1.0 op_sel_hi:[1,0]
	v_rcp_f32_e32 v152, v152
	v_rcp_f32_e32 v153, v153
	v_rcp_f32_e32 v154, v154
	v_rcp_f32_e32 v155, v155
	v_pk_mul_f32 v[120:121], v[120:121], v[152:153]
	v_pk_mul_f32 v[122:123], v[122:123], v[154:155]
	v_cvt_pk_bf16_f32 v120, v120, v121
	v_cvt_pk_bf16_f32 v121, v122, v123
	ds_write_b64 v135, v[120:121]
	v_mul_f32_e32 v148, 0xbfb8aa3b, v116
	v_mul_f32_e32 v149, 0xbfb8aa3b, v117
	v_mul_f32_e32 v150, 0xbfb8aa3b, v118
	v_mul_f32_e32 v151, 0xbfb8aa3b, v119
	v_exp_f32_e32 v148, v148
	v_exp_f32_e32 v149, v149
	v_exp_f32_e32 v150, v150
	v_exp_f32_e32 v151, v151
	v_pk_add_f32 v[148:149], v[148:149], 1.0 op_sel_hi:[1,0]
	v_pk_add_f32 v[150:151], v[150:151], 1.0 op_sel_hi:[1,0]
	v_rcp_f32_e32 v148, v148
	v_rcp_f32_e32 v149, v149
	v_rcp_f32_e32 v150, v150
	v_rcp_f32_e32 v151, v151
	v_pk_mul_f32 v[116:117], v[116:117], v[148:149]
	v_pk_mul_f32 v[118:119], v[118:119], v[150:151]
	v_cvt_pk_bf16_f32 v116, v116, v117
	v_cvt_pk_bf16_f32 v117, v118, v119
	ds_write_b64 v134, v[116:117] offset:256
	v_mul_f32_e32 v152, 0xbfb8aa3b, v112
	v_mul_f32_e32 v153, 0xbfb8aa3b, v113
	v_mul_f32_e32 v154, 0xbfb8aa3b, v114
	v_mul_f32_e32 v155, 0xbfb8aa3b, v115
	v_exp_f32_e32 v152, v152
	v_exp_f32_e32 v153, v153
	v_exp_f32_e32 v154, v154
	v_exp_f32_e32 v155, v155
	v_pk_add_f32 v[152:153], v[152:153], 1.0 op_sel_hi:[1,0]
	v_pk_add_f32 v[154:155], v[154:155], 1.0 op_sel_hi:[1,0]
	v_rcp_f32_e32 v152, v152
	v_rcp_f32_e32 v153, v153
	v_rcp_f32_e32 v154, v154
	v_rcp_f32_e32 v155, v155
	v_pk_mul_f32 v[112:113], v[112:113], v[152:153]
	v_pk_mul_f32 v[114:115], v[114:115], v[154:155]
	v_cvt_pk_bf16_f32 v112, v112, v113
	v_cvt_pk_bf16_f32 v113, v114, v115
	ds_write_b64 v135, v[112:113] offset:256
	v_mul_f32_e32 v148, 0xbfb8aa3b, v108
	v_mul_f32_e32 v149, 0xbfb8aa3b, v109
	v_mul_f32_e32 v150, 0xbfb8aa3b, v110
	v_mul_f32_e32 v151, 0xbfb8aa3b, v111
	v_exp_f32_e32 v148, v148
	v_exp_f32_e32 v149, v149
	v_exp_f32_e32 v150, v150
	v_exp_f32_e32 v151, v151
	v_pk_add_f32 v[148:149], v[148:149], 1.0 op_sel_hi:[1,0]
	v_pk_add_f32 v[150:151], v[150:151], 1.0 op_sel_hi:[1,0]
	v_rcp_f32_e32 v148, v148
	v_rcp_f32_e32 v149, v149
	v_rcp_f32_e32 v150, v150
	v_rcp_f32_e32 v151, v151
	v_pk_mul_f32 v[108:109], v[108:109], v[148:149]
	v_pk_mul_f32 v[110:111], v[110:111], v[150:151]
	v_cvt_pk_bf16_f32 v108, v108, v109
	v_cvt_pk_bf16_f32 v109, v110, v111
	ds_write_b64 v134, v[108:109] offset:8448
	v_mul_f32_e32 v152, 0xbfb8aa3b, v104
	v_mul_f32_e32 v153, 0xbfb8aa3b, v105
	v_mul_f32_e32 v154, 0xbfb8aa3b, v106
	v_mul_f32_e32 v155, 0xbfb8aa3b, v107
	v_exp_f32_e32 v152, v152
	v_exp_f32_e32 v153, v153
	v_exp_f32_e32 v154, v154
	v_exp_f32_e32 v155, v155
	v_pk_add_f32 v[152:153], v[152:153], 1.0 op_sel_hi:[1,0]
	v_pk_add_f32 v[154:155], v[154:155], 1.0 op_sel_hi:[1,0]
	v_rcp_f32_e32 v152, v152
	v_rcp_f32_e32 v153, v153
	v_rcp_f32_e32 v154, v154
	v_rcp_f32_e32 v155, v155
	v_pk_mul_f32 v[104:105], v[104:105], v[152:153]
	v_pk_mul_f32 v[106:107], v[106:107], v[154:155]
	v_cvt_pk_bf16_f32 v104, v104, v105
	v_cvt_pk_bf16_f32 v105, v106, v107
	ds_write_b64 v135, v[104:105] offset:8448
	v_mul_f32_e32 v148, 0xbfb8aa3b, v100
	v_mul_f32_e32 v149, 0xbfb8aa3b, v101
	v_mul_f32_e32 v150, 0xbfb8aa3b, v102
	v_mul_f32_e32 v151, 0xbfb8aa3b, v103
	v_exp_f32_e32 v148, v148
	v_exp_f32_e32 v149, v149
	v_exp_f32_e32 v150, v150
	v_exp_f32_e32 v151, v151
	v_pk_add_f32 v[148:149], v[148:149], 1.0 op_sel_hi:[1,0]
	v_pk_add_f32 v[150:151], v[150:151], 1.0 op_sel_hi:[1,0]
	v_rcp_f32_e32 v148, v148
	v_rcp_f32_e32 v149, v149
	v_rcp_f32_e32 v150, v150
	v_rcp_f32_e32 v151, v151
	v_pk_mul_f32 v[100:101], v[100:101], v[148:149]
	v_pk_mul_f32 v[102:103], v[102:103], v[150:151]
	v_cvt_pk_bf16_f32 v100, v100, v101
	v_cvt_pk_bf16_f32 v101, v102, v103
	ds_write_b64 v134, v[100:101] offset:8192
	v_mul_f32_e32 v152, 0xbfb8aa3b, v96
	v_mul_f32_e32 v153, 0xbfb8aa3b, v97
	v_mul_f32_e32 v154, 0xbfb8aa3b, v98
	v_mul_f32_e32 v155, 0xbfb8aa3b, v99
	v_exp_f32_e32 v152, v152
	v_exp_f32_e32 v153, v153
	v_exp_f32_e32 v154, v154
	v_exp_f32_e32 v155, v155
	v_pk_add_f32 v[152:153], v[152:153], 1.0 op_sel_hi:[1,0]
	v_pk_add_f32 v[154:155], v[154:155], 1.0 op_sel_hi:[1,0]
	v_rcp_f32_e32 v152, v152
	v_rcp_f32_e32 v153, v153
	v_rcp_f32_e32 v154, v154
	v_rcp_f32_e32 v155, v155
	v_pk_mul_f32 v[96:97], v[96:97], v[152:153]
	v_pk_mul_f32 v[98:99], v[98:99], v[154:155]
	v_cvt_pk_bf16_f32 v96, v96, v97
	v_cvt_pk_bf16_f32 v97, v98, v99
	ds_write_b64 v135, v[96:97] offset:8192
	v_mul_f32_e32 v148, 0xbfb8aa3b, v92
	v_mul_f32_e32 v149, 0xbfb8aa3b, v93
	v_mul_f32_e32 v150, 0xbfb8aa3b, v94
	v_mul_f32_e32 v151, 0xbfb8aa3b, v95
; DEV u32x2 pk4(f32x4 v) { u32x2 r = {pk_bf16(v[0], v[1]), pk_bf16(v[2], v[3])}; return r; }
; DEV float fsigmoid(float x) { return 1.f / (1.f + __expf(-x)); }
;   DEV void operator()(f32x4 (&acc)[2][2][4][2], int brow, int bcol, int wr, int wc, int fr, int fq) const {
;     ...
;             } else if (mode == 1) {
;               for (int j = 0; j < 4; ++j) v[j] = v[j] * fsigmoid(v[j]);
;               tile_put4(rl, cl, pk4(v));
	v_exp_f32_e32 v148, v148
	v_exp_f32_e32 v149, v149
	v_exp_f32_e32 v150, v150
	v_exp_f32_e32 v151, v151
	v_pk_add_f32 v[148:149], v[148:149], 1.0 op_sel_hi:[1,0]
	v_pk_add_f32 v[150:151], v[150:151], 1.0 op_sel_hi:[1,0]
	v_rcp_f32_e32 v148, v148
	v_rcp_f32_e32 v149, v149
	v_rcp_f32_e32 v150, v150
	v_rcp_f32_e32 v151, v151
	v_pk_mul_f32 v[92:93], v[92:93], v[148:149]
	v_pk_mul_f32 v[94:95], v[94:95], v[150:151]
	v_cvt_pk_bf16_f32 v92, v92, v93
	v_cvt_pk_bf16_f32 v93, v94, v95
	ds_write_b64 v134, v[92:93] offset:16384
	v_mul_f32_e32 v152, 0xbfb8aa3b, v88
	v_mul_f32_e32 v153, 0xbfb8aa3b, v89
	v_mul_f32_e32 v154, 0xbfb8aa3b, v90
	v_mul_f32_e32 v155, 0xbfb8aa3b, v91
	v_exp_f32_e32 v152, v152
	v_exp_f32_e32 v153, v153
	v_exp_f32_e32 v154, v154
	v_exp_f32_e32 v155, v155
	v_pk_add_f32 v[152:153], v[152:153], 1.0 op_sel_hi:[1,0]
	v_pk_add_f32 v[154:155], v[154:155], 1.0 op_sel_hi:[1,0]
	v_rcp_f32_e32 v152, v152
	v_rcp_f32_e32 v153, v153
	v_rcp_f32_e32 v154, v154
	v_rcp_f32_e32 v155, v155
	v_pk_mul_f32 v[88:89], v[88:89], v[152:153]
	v_pk_mul_f32 v[90:91], v[90:91], v[154:155]
	v_cvt_pk_bf16_f32 v88, v88, v89
	v_cvt_pk_bf16_f32 v89, v90, v91
	ds_write_b64 v135, v[88:89] offset:16384
	v_mul_f32_e32 v148, 0xbfb8aa3b, v84
	v_mul_f32_e32 v149, 0xbfb8aa3b, v85
	v_mul_f32_e32 v150, 0xbfb8aa3b, v86
	v_mul_f32_e32 v151, 0xbfb8aa3b, v87
	v_exp_f32_e32 v148, v148
	v_exp_f32_e32 v149, v149
	v_exp_f32_e32 v150, v150
	v_exp_f32_e32 v151, v151
	v_pk_add_f32 v[148:149], v[148:149], 1.0 op_sel_hi:[1,0]
	v_pk_add_f32 v[150:151], v[150:151], 1.0 op_sel_hi:[1,0]
	v_rcp_f32_e32 v148, v148
	v_rcp_f32_e32 v149, v149
	v_rcp_f32_e32 v150, v150
	v_rcp_f32_e32 v151, v151
	v_pk_mul_f32 v[84:85], v[84:85], v[148:149]
	v_pk_mul_f32 v[86:87], v[86:87], v[150:151]
	v_cvt_pk_bf16_f32 v84, v84, v85
	v_cvt_pk_bf16_f32 v85, v86, v87
	ds_write_b64 v134, v[84:85] offset:16640
	v_mul_f32_e32 v152, 0xbfb8aa3b, v80
	v_mul_f32_e32 v153, 0xbfb8aa3b, v81
	v_mul_f32_e32 v154, 0xbfb8aa3b, v82
	v_mul_f32_e32 v155, 0xbfb8aa3b, v83
	v_exp_f32_e32 v152, v152
	v_exp_f32_e32 v153, v153
	v_exp_f32_e32 v154, v154
	v_exp_f32_e32 v155, v155
	v_pk_add_f32 v[152:153], v[152:153], 1.0 op_sel_hi:[1,0]
	v_pk_add_f32 v[154:155], v[154:155], 1.0 op_sel_hi:[1,0]
	v_rcp_f32_e32 v152, v152
	v_rcp_f32_e32 v153, v153
	v_rcp_f32_e32 v154, v154
	v_rcp_f32_e32 v155, v155
	v_pk_mul_f32 v[80:81], v[80:81], v[152:153]
	v_pk_mul_f32 v[82:83], v[82:83], v[154:155]
	v_cvt_pk_bf16_f32 v80, v80, v81
	v_cvt_pk_bf16_f32 v81, v82, v83
	ds_write_b64 v135, v[80:81] offset:16640
	v_mul_f32_e32 v148, 0xbfb8aa3b, v76
	v_mul_f32_e32 v149, 0xbfb8aa3b, v77
	v_mul_f32_e32 v150, 0xbfb8aa3b, v78
	v_mul_f32_e32 v151, 0xbfb8aa3b, v79
	v_exp_f32_e32 v148, v148
	v_exp_f32_e32 v149, v149
	v_exp_f32_e32 v150, v150
	v_exp_f32_e32 v151, v151
	v_pk_add_f32 v[148:149], v[148:149], 1.0 op_sel_hi:[1,0]
	v_pk_add_f32 v[150:151], v[150:151], 1.0 op_sel_hi:[1,0]
	v_rcp_f32_e32 v148, v148
	v_rcp_f32_e32 v149, v149
	v_rcp_f32_e32 v150, v150
	v_rcp_f32_e32 v151, v151
	v_pk_mul_f32 v[76:77], v[76:77], v[148:149]
	v_pk_mul_f32 v[78:79], v[78:79], v[150:151]
	v_cvt_pk_bf16_f32 v76, v76, v77
	v_cvt_pk_bf16_f32 v77, v78, v79
	ds_write_b64 v134, v[76:77] offset:24832
	v_mul_f32_e32 v152, 0xbfb8aa3b, v72
	v_mul_f32_e32 v153, 0xbfb8aa3b, v73
	v_mul_f32_e32 v154, 0xbfb8aa3b, v74
	v_mul_f32_e32 v155, 0xbfb8aa3b, v75
	v_exp_f32_e32 v152, v152
	v_exp_f32_e32 v153, v153
	v_exp_f32_e32 v154, v154
	v_exp_f32_e32 v155, v155
	v_pk_add_f32 v[152:153], v[152:153], 1.0 op_sel_hi:[1,0]
	v_pk_add_f32 v[154:155], v[154:155], 1.0 op_sel_hi:[1,0]
	v_rcp_f32_e32 v152, v152
	v_rcp_f32_e32 v153, v153
	v_rcp_f32_e32 v154, v154
	v_rcp_f32_e32 v155, v155
	v_pk_mul_f32 v[72:73], v[72:73], v[152:153]
	v_pk_mul_f32 v[74:75], v[74:75], v[154:155]
	v_cvt_pk_bf16_f32 v72, v72, v73
	v_cvt_pk_bf16_f32 v73, v74, v75
	ds_write_b64 v135, v[72:73] offset:24832
	v_mul_f32_e32 v148, 0xbfb8aa3b, v68
	v_mul_f32_e32 v149, 0xbfb8aa3b, v69
	v_mul_f32_e32 v150, 0xbfb8aa3b, v70
	v_mul_f32_e32 v151, 0xbfb8aa3b, v71
	v_exp_f32_e32 v148, v148
	v_exp_f32_e32 v149, v149
	v_exp_f32_e32 v150, v150
	v_exp_f32_e32 v151, v151
	v_pk_add_f32 v[148:149], v[148:149], 1.0 op_sel_hi:[1,0]
	v_pk_add_f32 v[150:151], v[150:151], 1.0 op_sel_hi:[1,0]
	v_rcp_f32_e32 v148, v148
	v_rcp_f32_e32 v149, v149
	v_rcp_f32_e32 v150, v150
	v_rcp_f32_e32 v151, v151
	v_pk_mul_f32 v[68:69], v[68:69], v[148:149]
	v_pk_mul_f32 v[70:71], v[70:71], v[150:151]
	v_cvt_pk_bf16_f32 v68, v68, v69
	v_cvt_pk_bf16_f32 v69, v70, v71
	ds_write_b64 v134, v[68:69] offset:24576
	v_mul_f32_e32 v152, 0xbfb8aa3b, v64
	v_mul_f32_e32 v153, 0xbfb8aa3b, v65
	v_mul_f32_e32 v154, 0xbfb8aa3b, v66
	v_mul_f32_e32 v155, 0xbfb8aa3b, v67
	v_exp_f32_e32 v152, v152
	v_exp_f32_e32 v153, v153
	v_exp_f32_e32 v154, v154
	v_exp_f32_e32 v155, v155
	v_pk_add_f32 v[152:153], v[152:153], 1.0 op_sel_hi:[1,0]
	v_pk_add_f32 v[154:155], v[154:155], 1.0 op_sel_hi:[1,0]
	v_rcp_f32_e32 v152, v152
	v_rcp_f32_e32 v153, v153
	v_rcp_f32_e32 v154, v154
	v_rcp_f32_e32 v155, v155
	v_pk_mul_f32 v[64:65], v[64:65], v[152:153]
	v_pk_mul_f32 v[66:67], v[66:67], v[154:155]
	v_cvt_pk_bf16_f32 v64, v64, v65
	v_cvt_pk_bf16_f32 v65, v66, v67
	ds_write_b64 v135, v[64:65] offset:24576
	v_mul_f32_e32 v148, 0xbfb8aa3b, v60
	v_mul_f32_e32 v149, 0xbfb8aa3b, v61
	v_mul_f32_e32 v150, 0xbfb8aa3b, v62
	v_mul_f32_e32 v151, 0xbfb8aa3b, v63
	v_exp_f32_e32 v148, v148
	v_exp_f32_e32 v149, v149
	v_exp_f32_e32 v150, v150
	v_exp_f32_e32 v151, v151
	v_pk_add_f32 v[148:149], v[148:149], 1.0 op_sel_hi:[1,0]
	v_pk_add_f32 v[150:151], v[150:151], 1.0 op_sel_hi:[1,0]
	v_rcp_f32_e32 v148, v148
	v_rcp_f32_e32 v149, v149
; DEV u32x2 pk4(f32x4 v) { u32x2 r = {pk_bf16(v[0], v[1]), pk_bf16(v[2], v[3])}; return r; }
; DEV float fsigmoid(float x) { return 1.f / (1.f + __expf(-x)); }
;   DEV void operator()(f32x4 (&acc)[2][2][4][2], int brow, int bcol, int wr, int wc, int fr, int fq) const {
;     ...
;             } else if (mode == 1) {
;               for (int j = 0; j < 4; ++j) v[j] = v[j] * fsigmoid(v[j]);
;               tile_put4(rl, cl, pk4(v));
	v_rcp_f32_e32 v150, v150
	v_rcp_f32_e32 v151, v151
	v_pk_mul_f32 v[60:61], v[60:61], v[148:149]
	v_pk_mul_f32 v[62:63], v[62:63], v[150:151]
	v_cvt_pk_bf16_f32 v60, v60, v61
	v_cvt_pk_bf16_f32 v61, v62, v63
	ds_write_b64 v136, v[60:61]
	v_mul_f32_e32 v152, 0xbfb8aa3b, v56
	v_mul_f32_e32 v153, 0xbfb8aa3b, v57
	v_mul_f32_e32 v154, 0xbfb8aa3b, v58
	v_mul_f32_e32 v155, 0xbfb8aa3b, v59
	v_exp_f32_e32 v152, v152
	v_exp_f32_e32 v153, v153
	v_exp_f32_e32 v154, v154
	v_exp_f32_e32 v155, v155
	v_pk_add_f32 v[152:153], v[152:153], 1.0 op_sel_hi:[1,0]
	v_pk_add_f32 v[154:155], v[154:155], 1.0 op_sel_hi:[1,0]
	v_rcp_f32_e32 v152, v152
	v_rcp_f32_e32 v153, v153
	v_rcp_f32_e32 v154, v154
	v_rcp_f32_e32 v155, v155
	v_pk_mul_f32 v[56:57], v[56:57], v[152:153]
	v_pk_mul_f32 v[58:59], v[58:59], v[154:155]
	v_cvt_pk_bf16_f32 v56, v56, v57
	v_cvt_pk_bf16_f32 v57, v58, v59
	ds_write_b64 v137, v[56:57]
	v_mul_f32_e32 v148, 0xbfb8aa3b, v52
	v_mul_f32_e32 v149, 0xbfb8aa3b, v53
	v_mul_f32_e32 v150, 0xbfb8aa3b, v54
	v_mul_f32_e32 v151, 0xbfb8aa3b, v55
	v_exp_f32_e32 v148, v148
	v_exp_f32_e32 v149, v149
	v_exp_f32_e32 v150, v150
	v_exp_f32_e32 v151, v151
	v_pk_add_f32 v[148:149], v[148:149], 1.0 op_sel_hi:[1,0]
	v_pk_add_f32 v[150:151], v[150:151], 1.0 op_sel_hi:[1,0]
	v_rcp_f32_e32 v148, v148
	v_rcp_f32_e32 v149, v149
	v_rcp_f32_e32 v150, v150
	v_rcp_f32_e32 v151, v151
	v_pk_mul_f32 v[52:53], v[52:53], v[148:149]
	v_pk_mul_f32 v[54:55], v[54:55], v[150:151]
	v_cvt_pk_bf16_f32 v52, v52, v53
	v_cvt_pk_bf16_f32 v53, v54, v55
	ds_write_b64 v136, v[52:53] offset:256
	v_mul_f32_e32 v152, 0xbfb8aa3b, v48
	v_mul_f32_e32 v153, 0xbfb8aa3b, v49
	v_mul_f32_e32 v154, 0xbfb8aa3b, v50
	v_mul_f32_e32 v155, 0xbfb8aa3b, v51
	v_exp_f32_e32 v152, v152
	v_exp_f32_e32 v153, v153
	v_exp_f32_e32 v154, v154
	v_exp_f32_e32 v155, v155
	v_pk_add_f32 v[152:153], v[152:153], 1.0 op_sel_hi:[1,0]
	v_pk_add_f32 v[154:155], v[154:155], 1.0 op_sel_hi:[1,0]
	v_rcp_f32_e32 v152, v152
	v_rcp_f32_e32 v153, v153
	v_rcp_f32_e32 v154, v154
	v_rcp_f32_e32 v155, v155
	v_pk_mul_f32 v[48:49], v[48:49], v[152:153]
	v_pk_mul_f32 v[50:51], v[50:51], v[154:155]
	v_cvt_pk_bf16_f32 v48, v48, v49
	v_cvt_pk_bf16_f32 v49, v50, v51
	ds_write_b64 v137, v[48:49] offset:256
	v_mul_f32_e32 v148, 0xbfb8aa3b, v44
	v_mul_f32_e32 v149, 0xbfb8aa3b, v45
	v_mul_f32_e32 v150, 0xbfb8aa3b, v46
	v_mul_f32_e32 v151, 0xbfb8aa3b, v47
	v_exp_f32_e32 v148, v148
	v_exp_f32_e32 v149, v149
	v_exp_f32_e32 v150, v150
	v_exp_f32_e32 v151, v151
	v_pk_add_f32 v[148:149], v[148:149], 1.0 op_sel_hi:[1,0]
	v_pk_add_f32 v[150:151], v[150:151], 1.0 op_sel_hi:[1,0]
	v_rcp_f32_e32 v148, v148
	v_rcp_f32_e32 v149, v149
	v_rcp_f32_e32 v150, v150
	v_rcp_f32_e32 v151, v151
	v_pk_mul_f32 v[44:45], v[44:45], v[148:149]
	v_pk_mul_f32 v[46:47], v[46:47], v[150:151]
	v_cvt_pk_bf16_f32 v44, v44, v45
	v_cvt_pk_bf16_f32 v45, v46, v47
	ds_write_b64 v136, v[44:45] offset:8448
	v_mul_f32_e32 v152, 0xbfb8aa3b, v40
	v_mul_f32_e32 v153, 0xbfb8aa3b, v41
	v_mul_f32_e32 v154, 0xbfb8aa3b, v42
	v_mul_f32_e32 v155, 0xbfb8aa3b, v43
	v_exp_f32_e32 v152, v152
	v_exp_f32_e32 v153, v153
	v_exp_f32_e32 v154, v154
	v_exp_f32_e32 v155, v155
	v_pk_add_f32 v[152:153], v[152:153], 1.0 op_sel_hi:[1,0]
	v_pk_add_f32 v[154:155], v[154:155], 1.0 op_sel_hi:[1,0]
	v_rcp_f32_e32 v152, v152
	v_rcp_f32_e32 v153, v153
	v_rcp_f32_e32 v154, v154
	v_rcp_f32_e32 v155, v155
	v_pk_mul_f32 v[40:41], v[40:41], v[152:153]
	v_pk_mul_f32 v[42:43], v[42:43], v[154:155]
	v_cvt_pk_bf16_f32 v40, v40, v41
	v_cvt_pk_bf16_f32 v41, v42, v43
	ds_write_b64 v137, v[40:41] offset:8448
	v_mul_f32_e32 v148, 0xbfb8aa3b, v36
	v_mul_f32_e32 v149, 0xbfb8aa3b, v37
	v_mul_f32_e32 v150, 0xbfb8aa3b, v38
	v_mul_f32_e32 v151, 0xbfb8aa3b, v39
	v_exp_f32_e32 v148, v148
	v_exp_f32_e32 v149, v149
	v_exp_f32_e32 v150, v150
	v_exp_f32_e32 v151, v151
	v_pk_add_f32 v[148:149], v[148:149], 1.0 op_sel_hi:[1,0]
	v_pk_add_f32 v[150:151], v[150:151], 1.0 op_sel_hi:[1,0]
	v_rcp_f32_e32 v148, v148
	v_rcp_f32_e32 v149, v149
	v_rcp_f32_e32 v150, v150
	v_rcp_f32_e32 v151, v151
	v_pk_mul_f32 v[36:37], v[36:37], v[148:149]
	v_pk_mul_f32 v[38:39], v[38:39], v[150:151]
	v_cvt_pk_bf16_f32 v36, v36, v37
	v_cvt_pk_bf16_f32 v37, v38, v39
	ds_write_b64 v136, v[36:37] offset:8192
	v_mul_f32_e32 v152, 0xbfb8aa3b, v32
	v_mul_f32_e32 v153, 0xbfb8aa3b, v33
	v_mul_f32_e32 v154, 0xbfb8aa3b, v34
	v_mul_f32_e32 v155, 0xbfb8aa3b, v35
	v_exp_f32_e32 v152, v152
	v_exp_f32_e32 v153, v153
	v_exp_f32_e32 v154, v154
	v_exp_f32_e32 v155, v155
	v_pk_add_f32 v[152:153], v[152:153], 1.0 op_sel_hi:[1,0]
	v_pk_add_f32 v[154:155], v[154:155], 1.0 op_sel_hi:[1,0]
	v_rcp_f32_e32 v152, v152
	v_rcp_f32_e32 v153, v153
	v_rcp_f32_e32 v154, v154
	v_rcp_f32_e32 v155, v155
	v_pk_mul_f32 v[32:33], v[32:33], v[152:153]
	v_pk_mul_f32 v[34:35], v[34:35], v[154:155]
	v_cvt_pk_bf16_f32 v32, v32, v33
	v_cvt_pk_bf16_f32 v33, v34, v35
	ds_write_b64 v137, v[32:33] offset:8192
	v_mul_f32_e32 v148, 0xbfb8aa3b, v28
	v_mul_f32_e32 v149, 0xbfb8aa3b, v29
	v_mul_f32_e32 v150, 0xbfb8aa3b, v30
	v_mul_f32_e32 v151, 0xbfb8aa3b, v31
	v_exp_f32_e32 v148, v148
	v_exp_f32_e32 v149, v149
; DEV u32x2 pk4(f32x4 v) { u32x2 r = {pk_bf16(v[0], v[1]), pk_bf16(v[2], v[3])}; return r; }
; DEV float fsigmoid(float x) { return 1.f / (1.f + __expf(-x)); }
;   DEV void operator()(f32x4 (&acc)[2][2][4][2], int brow, int bcol, int wr, int wc, int fr, int fq) const {
;     ...
;             } else if (mode == 1) {
;               for (int j = 0; j < 4; ++j) v[j] = v[j] * fsigmoid(v[j]);
;               tile_put4(rl, cl, pk4(v));
	v_exp_f32_e32 v150, v150
	v_exp_f32_e32 v151, v151
	v_pk_add_f32 v[148:149], v[148:149], 1.0 op_sel_hi:[1,0]
	v_pk_add_f32 v[150:151], v[150:151], 1.0 op_sel_hi:[1,0]
	v_rcp_f32_e32 v148, v148
	v_rcp_f32_e32 v149, v149
	v_rcp_f32_e32 v150, v150
	v_rcp_f32_e32 v151, v151
	v_pk_mul_f32 v[28:29], v[28:29], v[148:149]
	v_pk_mul_f32 v[30:31], v[30:31], v[150:151]
	v_cvt_pk_bf16_f32 v28, v28, v29
	v_cvt_pk_bf16_f32 v29, v30, v31
	ds_write_b64 v136, v[28:29] offset:16384
	v_mul_f32_e32 v152, 0xbfb8aa3b, v24
	v_mul_f32_e32 v153, 0xbfb8aa3b, v25
	v_mul_f32_e32 v154, 0xbfb8aa3b, v26
	v_mul_f32_e32 v155, 0xbfb8aa3b, v27
	v_exp_f32_e32 v152, v152
	v_exp_f32_e32 v153, v153
	v_exp_f32_e32 v154, v154
	v_exp_f32_e32 v155, v155
	v_pk_add_f32 v[152:153], v[152:153], 1.0 op_sel_hi:[1,0]
	v_pk_add_f32 v[154:155], v[154:155], 1.0 op_sel_hi:[1,0]
	v_rcp_f32_e32 v152, v152
	v_rcp_f32_e32 v153, v153
	v_rcp_f32_e32 v154, v154
	v_rcp_f32_e32 v155, v155
	v_pk_mul_f32 v[24:25], v[24:25], v[152:153]
	v_pk_mul_f32 v[26:27], v[26:27], v[154:155]
	v_cvt_pk_bf16_f32 v24, v24, v25
	v_cvt_pk_bf16_f32 v25, v26, v27
	ds_write_b64 v137, v[24:25] offset:16384
	v_mul_f32_e32 v148, 0xbfb8aa3b, v20
	v_mul_f32_e32 v149, 0xbfb8aa3b, v21
	v_mul_f32_e32 v150, 0xbfb8aa3b, v22
	v_mul_f32_e32 v151, 0xbfb8aa3b, v23
	v_exp_f32_e32 v148, v148
	v_exp_f32_e32 v149, v149
	v_exp_f32_e32 v150, v150
	v_exp_f32_e32 v151, v151
	v_pk_add_f32 v[148:149], v[148:149], 1.0 op_sel_hi:[1,0]
	v_pk_add_f32 v[150:151], v[150:151], 1.0 op_sel_hi:[1,0]
	v_rcp_f32_e32 v148, v148
	v_rcp_f32_e32 v149, v149
	v_rcp_f32_e32 v150, v150
	v_rcp_f32_e32 v151, v151
	v_pk_mul_f32 v[20:21], v[20:21], v[148:149]
	v_pk_mul_f32 v[22:23], v[22:23], v[150:151]
	v_cvt_pk_bf16_f32 v20, v20, v21
	v_cvt_pk_bf16_f32 v21, v22, v23
	ds_write_b64 v136, v[20:21] offset:16640
	v_mul_f32_e32 v152, 0xbfb8aa3b, v16
	v_mul_f32_e32 v153, 0xbfb8aa3b, v17
	v_mul_f32_e32 v154, 0xbfb8aa3b, v18
	v_mul_f32_e32 v155, 0xbfb8aa3b, v19
	v_exp_f32_e32 v152, v152
	v_exp_f32_e32 v153, v153
	v_exp_f32_e32 v154, v154
	v_exp_f32_e32 v155, v155
	v_pk_add_f32 v[152:153], v[152:153], 1.0 op_sel_hi:[1,0]
	v_pk_add_f32 v[154:155], v[154:155], 1.0 op_sel_hi:[1,0]
	v_rcp_f32_e32 v152, v152
	v_rcp_f32_e32 v153, v153
	v_rcp_f32_e32 v154, v154
	v_rcp_f32_e32 v155, v155
	v_pk_mul_f32 v[16:17], v[16:17], v[152:153]
	v_pk_mul_f32 v[18:19], v[18:19], v[154:155]
	v_cvt_pk_bf16_f32 v16, v16, v17
	v_cvt_pk_bf16_f32 v17, v18, v19
	ds_write_b64 v137, v[16:17] offset:16640
	v_mul_f32_e32 v148, 0xbfb8aa3b, v12
	v_mul_f32_e32 v149, 0xbfb8aa3b, v13
	v_mul_f32_e32 v150, 0xbfb8aa3b, v14
	v_mul_f32_e32 v151, 0xbfb8aa3b, v15
	v_exp_f32_e32 v148, v148
	v_exp_f32_e32 v149, v149
	v_exp_f32_e32 v150, v150
	v_exp_f32_e32 v151, v151
	v_pk_add_f32 v[148:149], v[148:149], 1.0 op_sel_hi:[1,0]
	v_pk_add_f32 v[150:151], v[150:151], 1.0 op_sel_hi:[1,0]
	v_rcp_f32_e32 v148, v148
	v_rcp_f32_e32 v149, v149
	v_rcp_f32_e32 v150, v150
	v_rcp_f32_e32 v151, v151
	v_pk_mul_f32 v[12:13], v[12:13], v[148:149]
	v_pk_mul_f32 v[14:15], v[14:15], v[150:151]
	v_cvt_pk_bf16_f32 v12, v12, v13
	v_cvt_pk_bf16_f32 v13, v14, v15
	ds_write_b64 v136, v[12:13] offset:24832
	v_mul_f32_e32 v152, 0xbfb8aa3b, v8
	v_mul_f32_e32 v153, 0xbfb8aa3b, v9
	v_mul_f32_e32 v154, 0xbfb8aa3b, v10
	v_mul_f32_e32 v155, 0xbfb8aa3b, v11
	v_exp_f32_e32 v152, v152
	v_exp_f32_e32 v153, v153
	v_exp_f32_e32 v154, v154
	v_exp_f32_e32 v155, v155
	v_pk_add_f32 v[152:153], v[152:153], 1.0 op_sel_hi:[1,0]
	v_pk_add_f32 v[154:155], v[154:155], 1.0 op_sel_hi:[1,0]
	v_rcp_f32_e32 v152, v152
	v_rcp_f32_e32 v153, v153
	v_rcp_f32_e32 v154, v154
	v_rcp_f32_e32 v155, v155
	v_pk_mul_f32 v[8:9], v[8:9], v[152:153]
	v_pk_mul_f32 v[10:11], v[10:11], v[154:155]
	v_cvt_pk_bf16_f32 v8, v8, v9
	v_cvt_pk_bf16_f32 v9, v10, v11
	ds_write_b64 v137, v[8:9] offset:24832
	v_mul_f32_e32 v148, 0xbfb8aa3b, v4
	v_mul_f32_e32 v149, 0xbfb8aa3b, v5
	v_mul_f32_e32 v150, 0xbfb8aa3b, v6
	v_mul_f32_e32 v151, 0xbfb8aa3b, v7
	v_exp_f32_e32 v148, v148
	v_exp_f32_e32 v149, v149
	v_exp_f32_e32 v150, v150
	v_exp_f32_e32 v151, v151
	v_pk_add_f32 v[148:149], v[148:149], 1.0 op_sel_hi:[1,0]
	v_pk_add_f32 v[150:151], v[150:151], 1.0 op_sel_hi:[1,0]
	v_rcp_f32_e32 v148, v148
	v_rcp_f32_e32 v149, v149
	v_rcp_f32_e32 v150, v150
	v_rcp_f32_e32 v151, v151
	v_pk_mul_f32 v[4:5], v[4:5], v[148:149]
	v_pk_mul_f32 v[6:7], v[6:7], v[150:151]
	v_cvt_pk_bf16_f32 v4, v4, v5
	v_cvt_pk_bf16_f32 v5, v6, v7
	ds_write_b64 v136, v[4:5] offset:24576
	v_mul_f32_e32 v152, 0xbfb8aa3b, v0
	v_mul_f32_e32 v153, 0xbfb8aa3b, v1
	v_mul_f32_e32 v154, 0xbfb8aa3b, v2
	v_mul_f32_e32 v155, 0xbfb8aa3b, v3
	v_exp_f32_e32 v152, v152
	v_exp_f32_e32 v153, v153
	v_exp_f32_e32 v154, v154
	v_exp_f32_e32 v155, v155
	v_pk_add_f32 v[152:153], v[152:153], 1.0 op_sel_hi:[1,0]
	v_pk_add_f32 v[154:155], v[154:155], 1.0 op_sel_hi:[1,0]
	v_rcp_f32_e32 v152, v152
	v_rcp_f32_e32 v153, v153
	v_rcp_f32_e32 v154, v154
	v_rcp_f32_e32 v155, v155
	v_pk_mul_f32 v[0:1], v[0:1], v[152:153]
	v_pk_mul_f32 v[2:3], v[2:3], v[154:155]
	v_cvt_pk_bf16_f32 v0, v0, v1
	v_cvt_pk_bf16_f32 v1, v2, v3
	ds_write_b64 v137, v[0:1] offset:24576

; DEV u32x2 pk4(f32x4 v) { u32x2 r = {pk_bf16(v[0], v[1]), pk_bf16(v[2], v[3])}; return r; }
; DEV int sig4(int x) { return ((x & 1) << 1) | (x >> 1); }
;   DEV void operator()(f32x4 (&acc)[2][2][4][2], int brow, int bcol, int wr, int wc, int fr, int fq) const {
;     ...
;         const int rl = ai * 128 + wr * 64 + m * 16 + fr, tok = brow + rl;
; #pragma unroll
;         for (int bj = 0; bj < 2; ++bj)
; #pragma unroll
;           for (int n = 0; n < 2; ++n) {
;             const int cl = bj * 128 + wc * 32 + n * 16 + fq * 4, lc = bcol - segstart + cl;
;     ...
;               const f32x4 b4 = *(const f32x4*)(bmat + (size_t)tok * 1024 + lc);
;               const int pcl = (cl & ~15) + 4 * sig4((cl >> 2) & 3);
;               if (mode == 3) {
;                 for (int j = 0; j < 4; ++j) v[j] = v[j] * scale * __expf(b4[j]);
;                 tile_put4(rl, pcl, pk4(v));
.Lepi_lean34:
	v_lshrrev_b32_e32 v145, 1, v129
	v_and_b32_e32 v146, 1, v129
	v_lshl_add_u32 v132, v131, 6, v128
	v_lshlrev_b32_e32 v132, 9, v132
	v_lshl_add_u32 v132, v145, 3, v132
	v_lshl_add_u32 v133, v130, 2, v146
	v_xor_b32_e32 v133, v133, v128
	v_lshl_add_u32 v160, v133, 4, v132
	v_xor_b32_e32 v133, 2, v133
	v_lshl_add_u32 v161, v133, 4, v132
	v_add_u32_e32 v162, 0x10000, v160
	v_add_u32_e32 v163, 0x10000, v161
	v_readlane_b32 s20, v253, 54
	v_readlane_b32 s21, v253, 55
	v_lshl_add_u32 v164, v131, 6, v128
	v_add_u32_e32 v164, s4, v164
	v_lshlrev_b32_e32 v164, 12, v164
	v_lshlrev_b32_e32 v165, 5, v130
	v_add_u32_e32 v165, s6, v165
	v_subrev_u32_e32 v165, s36, v165
	v_lshl_add_u32 v165, v165, 2, 0
	v_lshl_add_u32 v165, v129, 4, v165
	v_add_u32_e32 v164, v164, v165
	v_lshlrev_b32_e32 v174, 6, v131
	v_add_u32_e32 v174, s4, v174
	v_add_u32_e32 v174, 63, v174
	v_lshl_add_u32 v165, v174, 12, v165
	global_load_dwordx4 v[180:183], v164, s[20:21]
	global_load_dwordx4 v[184:187], v164, s[20:21] offset:64
	global_load_dwordx4 v[188:191], v164, s[20:21] offset:512
	global_load_dwordx4 v[192:195], v164, s[20:21] offset:576
	v_add_u32_e32 v164, 0x10000, v164
	global_load_dwordx4 v[206:209], v164, s[20:21]
	global_load_dwordx4 v[210:213], v164, s[20:21] offset:64
	global_load_dwordx4 v[214:217], v164, s[20:21] offset:512
	global_load_dwordx4 v[224:227], v164, s[20:21] offset:576
	v_add_u32_e32 v164, 0x10000, v164
	global_load_dwordx4 v[228:231], v164, s[20:21]
	global_load_dwordx4 v[232:235], v164, s[20:21] offset:64
	global_load_dwordx4 v[236:239], v164, s[20:21] offset:512
	global_load_dwordx4 v[240:243], v164, s[20:21] offset:576
	v_add_u32_e32 v164, 0x10000, v164
	global_load_dwordx4 v[244:247], v164, s[20:21]
	global_load_dwordx4 v[248:251], v164, s[20:21] offset:64
	global_load_dwordx4 v[166:169], v164, s[20:21] offset:512
	global_load_dwordx4 v[170:173], v164, s[20:21] offset:576
	v_add_u32_e32 v164, 0x10000, v164
	s_cmp_eq_u32 s37, 4
	s_cbranch_scc1 .Lepi_lean_k4
	s_mov_b32 s13, s12
	s_waitcnt vmcnt(0)
	v_mul_f32_e32 v180, 0x3fb8aa3b, v180
	v_mul_f32_e32 v181, 0x3fb8aa3b, v181
	v_mul_f32_e32 v182, 0x3fb8aa3b, v182
	v_mul_f32_e32 v183, 0x3fb8aa3b, v183
	v_exp_f32_e32 v180, v180
	v_exp_f32_e32 v181, v181
	v_exp_f32_e32 v182, v182
	v_exp_f32_e32 v183, v183
	v_pk_mul_f32 v[124:125], v[124:125], s[12:13]
	v_pk_mul_f32 v[126:127], v[126:127], s[12:13]
	v_pk_mul_f32 v[124:125], v[180:181], v[124:125]
	v_pk_mul_f32 v[126:127], v[182:183], v[126:127]
	v_cvt_pk_bf16_f32 v124, v124, v125
	v_cvt_pk_bf16_f32 v125, v126, v127
	ds_write_b64 v160, v[124:125]
	v_mul_f32_e32 v184, 0x3fb8aa3b, v184
	v_mul_f32_e32 v185, 0x3fb8aa3b, v185
	v_mul_f32_e32 v186, 0x3fb8aa3b, v186
	v_mul_f32_e32 v187, 0x3fb8aa3b, v187
	v_exp_f32_e32 v184, v184
	v_exp_f32_e32 v185, v185
	v_exp_f32_e32 v186, v186
	v_exp_f32_e32 v187, v187
	v_pk_mul_f32 v[120:121], v[120:121], s[12:13]
	v_pk_mul_f32 v[122:123], v[122:123], s[12:13]
	v_pk_mul_f32 v[120:121], v[184:185], v[120:121]
	v_pk_mul_f32 v[122:123], v[186:187], v[122:123]
	v_cvt_pk_bf16_f32 v120, v120, v121
	v_cvt_pk_bf16_f32 v121, v122, v123
	ds_write_b64 v161, v[120:121]
	v_mul_f32_e32 v188, 0x3fb8aa3b, v188
	v_mul_f32_e32 v189, 0x3fb8aa3b, v189
	v_mul_f32_e32 v190, 0x3fb8aa3b, v190
	v_mul_f32_e32 v191, 0x3fb8aa3b, v191
	v_exp_f32_e32 v188, v188
	v_exp_f32_e32 v189, v189
	v_exp_f32_e32 v190, v190
	v_exp_f32_e32 v191, v191
	v_pk_mul_f32 v[116:117], v[116:117], s[12:13]
	v_pk_mul_f32 v[118:119], v[118:119], s[12:13]
	v_pk_mul_f32 v[116:117], v[188:189], v[116:117]
	v_pk_mul_f32 v[118:119], v[190:191], v[118:119]
	v_cvt_pk_bf16_f32 v116, v116, v117
	v_cvt_pk_bf16_f32 v117, v118, v119
	ds_write_b64 v160, v[116:117] offset:256
	v_mul_f32_e32 v192, 0x3fb8aa3b, v192
	v_mul_f32_e32 v193, 0x3fb8aa3b, v193
	v_mul_f32_e32 v194, 0x3fb8aa3b, v194
	v_mul_f32_e32 v195, 0x3fb8aa3b, v195
	v_exp_f32_e32 v192, v192
	v_exp_f32_e32 v193, v193
	v_exp_f32_e32 v194, v194
	v_exp_f32_e32 v195, v195
	v_pk_mul_f32 v[112:113], v[112:113], s[12:13]
	v_pk_mul_f32 v[114:115], v[114:115], s[12:13]
	v_pk_mul_f32 v[112:113], v[192:193], v[112:113]
	v_pk_mul_f32 v[114:115], v[194:195], v[114:115]
	v_cvt_pk_bf16_f32 v112, v112, v113
	v_cvt_pk_bf16_f32 v113, v114, v115
	ds_write_b64 v161, v[112:113] offset:256
	v_mul_f32_e32 v206, 0x3fb8aa3b, v206
	v_mul_f32_e32 v207, 0x3fb8aa3b, v207
	v_mul_f32_e32 v208, 0x3fb8aa3b, v208
	v_mul_f32_e32 v209, 0x3fb8aa3b, v209
	v_exp_f32_e32 v206, v206
	v_exp_f32_e32 v207, v207
	v_exp_f32_e32 v208, v208
	v_exp_f32_e32 v209, v209
	v_pk_mul_f32 v[108:109], v[108:109], s[12:13]
	v_pk_mul_f32 v[110:111], v[110:111], s[12:13]
	v_pk_mul_f32 v[108:109], v[206:207], v[108:109]
	v_pk_mul_f32 v[110:111], v[208:209], v[110:111]
	v_cvt_pk_bf16_f32 v108, v108, v109
	v_cvt_pk_bf16_f32 v109, v110, v111
	ds_write_b64 v160, v[108:109] offset:8448
	v_mul_f32_e32 v210, 0x3fb8aa3b, v210
	v_mul_f32_e32 v211, 0x3fb8aa3b, v211
	v_mul_f32_e32 v212, 0x3fb8aa3b, v212
	v_mul_f32_e32 v213, 0x3fb8aa3b, v213
	v_exp_f32_e32 v210, v210
	v_exp_f32_e32 v211, v211
	v_exp_f32_e32 v212, v212
	v_exp_f32_e32 v213, v213
	v_pk_mul_f32 v[104:105], v[104:105], s[12:13]
	v_pk_mul_f32 v[106:107], v[106:107], s[12:13]
	v_pk_mul_f32 v[104:105], v[210:211], v[104:105]
	v_pk_mul_f32 v[106:107], v[212:213], v[106:107]
	v_cvt_pk_bf16_f32 v104, v104, v105
	v_cvt_pk_bf16_f32 v105, v106, v107
	ds_write_b64 v161, v[104:105] offset:8448
	v_mul_f32_e32 v214, 0x3fb8aa3b, v214
	v_mul_f32_e32 v215, 0x3fb8aa3b, v215
	v_mul_f32_e32 v216, 0x3fb8aa3b, v216
	v_mul_f32_e32 v217, 0x3fb8aa3b, v217
	v_exp_f32_e32 v214, v214
	v_exp_f32_e32 v215, v215
	v_exp_f32_e32 v216, v216
	v_exp_f32_e32 v217, v217
; DEV u32x2 pk4(f32x4 v) { u32x2 r = {pk_bf16(v[0], v[1]), pk_bf16(v[2], v[3])}; return r; }
; DEV int sig4(int x) { return ((x & 1) << 1) | (x >> 1); }
;   DEV void operator()(f32x4 (&acc)[2][2][4][2], int brow, int bcol, int wr, int wc, int fr, int fq) const {
;     ...
;               const f32x4 b4 = *(const f32x4*)(bmat + (size_t)tok * 1024 + lc);
;               const int pcl = (cl & ~15) + 4 * sig4((cl >> 2) & 3);
;               if (mode == 3) {
;                 for (int j = 0; j < 4; ++j) v[j] = v[j] * scale * __expf(b4[j]);
;                 tile_put4(rl, pcl, pk4(v));
	v_pk_mul_f32 v[100:101], v[100:101], s[12:13]
	v_pk_mul_f32 v[102:103], v[102:103], s[12:13]
	v_pk_mul_f32 v[100:101], v[214:215], v[100:101]
	v_pk_mul_f32 v[102:103], v[216:217], v[102:103]
	v_cvt_pk_bf16_f32 v100, v100, v101
	v_cvt_pk_bf16_f32 v101, v102, v103
	ds_write_b64 v160, v[100:101] offset:8192
	v_mul_f32_e32 v224, 0x3fb8aa3b, v224
	v_mul_f32_e32 v225, 0x3fb8aa3b, v225
	v_mul_f32_e32 v226, 0x3fb8aa3b, v226
	v_mul_f32_e32 v227, 0x3fb8aa3b, v227
	v_exp_f32_e32 v224, v224
	v_exp_f32_e32 v225, v225
	v_exp_f32_e32 v226, v226
	v_exp_f32_e32 v227, v227
	v_pk_mul_f32 v[96:97], v[96:97], s[12:13]
	v_pk_mul_f32 v[98:99], v[98:99], s[12:13]
	v_pk_mul_f32 v[96:97], v[224:225], v[96:97]
	v_pk_mul_f32 v[98:99], v[226:227], v[98:99]
	v_cvt_pk_bf16_f32 v96, v96, v97
	v_cvt_pk_bf16_f32 v97, v98, v99
	ds_write_b64 v161, v[96:97] offset:8192
	v_mul_f32_e32 v228, 0x3fb8aa3b, v228
	v_mul_f32_e32 v229, 0x3fb8aa3b, v229
	v_mul_f32_e32 v230, 0x3fb8aa3b, v230
	v_mul_f32_e32 v231, 0x3fb8aa3b, v231
	v_exp_f32_e32 v228, v228
	v_exp_f32_e32 v229, v229
	v_exp_f32_e32 v230, v230
	v_exp_f32_e32 v231, v231
	v_pk_mul_f32 v[92:93], v[92:93], s[12:13]
	v_pk_mul_f32 v[94:95], v[94:95], s[12:13]
	v_pk_mul_f32 v[92:93], v[228:229], v[92:93]
	v_pk_mul_f32 v[94:95], v[230:231], v[94:95]
	v_cvt_pk_bf16_f32 v92, v92, v93
	v_cvt_pk_bf16_f32 v93, v94, v95
	ds_write_b64 v160, v[92:93] offset:16384
	v_mul_f32_e32 v232, 0x3fb8aa3b, v232
	v_mul_f32_e32 v233, 0x3fb8aa3b, v233
	v_mul_f32_e32 v234, 0x3fb8aa3b, v234
	v_mul_f32_e32 v235, 0x3fb8aa3b, v235
	v_exp_f32_e32 v232, v232
	v_exp_f32_e32 v233, v233
	v_exp_f32_e32 v234, v234
	v_exp_f32_e32 v235, v235
	v_pk_mul_f32 v[88:89], v[88:89], s[12:13]
	v_pk_mul_f32 v[90:91], v[90:91], s[12:13]
	v_pk_mul_f32 v[88:89], v[232:233], v[88:89]
	v_pk_mul_f32 v[90:91], v[234:235], v[90:91]
	v_cvt_pk_bf16_f32 v88, v88, v89
	v_cvt_pk_bf16_f32 v89, v90, v91
	ds_write_b64 v161, v[88:89] offset:16384
	v_mul_f32_e32 v236, 0x3fb8aa3b, v236
	v_mul_f32_e32 v237, 0x3fb8aa3b, v237
	v_mul_f32_e32 v238, 0x3fb8aa3b, v238
	v_mul_f32_e32 v239, 0x3fb8aa3b, v239
	v_exp_f32_e32 v236, v236
	v_exp_f32_e32 v237, v237
	v_exp_f32_e32 v238, v238
	v_exp_f32_e32 v239, v239
	v_pk_mul_f32 v[84:85], v[84:85], s[12:13]
	v_pk_mul_f32 v[86:87], v[86:87], s[12:13]
	v_pk_mul_f32 v[84:85], v[236:237], v[84:85]
	v_pk_mul_f32 v[86:87], v[238:239], v[86:87]
	v_cvt_pk_bf16_f32 v84, v84, v85
	v_cvt_pk_bf16_f32 v85, v86, v87
	ds_write_b64 v160, v[84:85] offset:16640
	v_mul_f32_e32 v240, 0x3fb8aa3b, v240
	v_mul_f32_e32 v241, 0x3fb8aa3b, v241
	v_mul_f32_e32 v242, 0x3fb8aa3b, v242
	v_mul_f32_e32 v243, 0x3fb8aa3b, v243
	v_exp_f32_e32 v240, v240
	v_exp_f32_e32 v241, v241
	v_exp_f32_e32 v242, v242
	v_exp_f32_e32 v243, v243
	v_pk_mul_f32 v[80:81], v[80:81], s[12:13]
	v_pk_mul_f32 v[82:83], v[82:83], s[12:13]
	v_pk_mul_f32 v[80:81], v[240:241], v[80:81]
	v_pk_mul_f32 v[82:83], v[242:243], v[82:83]
	v_cvt_pk_bf16_f32 v80, v80, v81
	v_cvt_pk_bf16_f32 v81, v82, v83
	ds_write_b64 v161, v[80:81] offset:16640
	v_mul_f32_e32 v244, 0x3fb8aa3b, v244
	v_mul_f32_e32 v245, 0x3fb8aa3b, v245
	v_mul_f32_e32 v246, 0x3fb8aa3b, v246
	v_mul_f32_e32 v247, 0x3fb8aa3b, v247
	v_exp_f32_e32 v244, v244
	v_exp_f32_e32 v245, v245
	v_exp_f32_e32 v246, v246
	v_exp_f32_e32 v247, v247
	v_pk_mul_f32 v[76:77], v[76:77], s[12:13]
	v_pk_mul_f32 v[78:79], v[78:79], s[12:13]
	v_pk_mul_f32 v[76:77], v[244:245], v[76:77]
	v_pk_mul_f32 v[78:79], v[246:247], v[78:79]
	v_cvt_pk_bf16_f32 v76, v76, v77
	v_cvt_pk_bf16_f32 v77, v78, v79
	ds_write_b64 v160, v[76:77] offset:24832
	v_mul_f32_e32 v248, 0x3fb8aa3b, v248
	v_mul_f32_e32 v249, 0x3fb8aa3b, v249
	v_mul_f32_e32 v250, 0x3fb8aa3b, v250
	v_mul_f32_e32 v251, 0x3fb8aa3b, v251
	v_exp_f32_e32 v248, v248
	v_exp_f32_e32 v249, v249
	v_exp_f32_e32 v250, v250
	v_exp_f32_e32 v251, v251
	v_pk_mul_f32 v[72:73], v[72:73], s[12:13]
	v_pk_mul_f32 v[74:75], v[74:75], s[12:13]
	v_pk_mul_f32 v[72:73], v[248:249], v[72:73]
	v_pk_mul_f32 v[74:75], v[250:251], v[74:75]
	v_cvt_pk_bf16_f32 v72, v72, v73
	v_cvt_pk_bf16_f32 v73, v74, v75
	ds_write_b64 v161, v[72:73] offset:24832
	v_mul_f32_e32 v166, 0x3fb8aa3b, v166
	v_mul_f32_e32 v167, 0x3fb8aa3b, v167
	v_mul_f32_e32 v168, 0x3fb8aa3b, v168
	v_mul_f32_e32 v169, 0x3fb8aa3b, v169
	v_exp_f32_e32 v166, v166
	v_exp_f32_e32 v167, v167
	v_exp_f32_e32 v168, v168
	v_exp_f32_e32 v169, v169
	v_pk_mul_f32 v[68:69], v[68:69], s[12:13]
	v_pk_mul_f32 v[70:71], v[70:71], s[12:13]
	v_pk_mul_f32 v[68:69], v[166:167], v[68:69]
	v_pk_mul_f32 v[70:71], v[168:169], v[70:71]
	v_cvt_pk_bf16_f32 v68, v68, v69
	v_cvt_pk_bf16_f32 v69, v70, v71
	ds_write_b64 v160, v[68:69] offset:24576
	v_mul_f32_e32 v170, 0x3fb8aa3b, v170
	v_mul_f32_e32 v171, 0x3fb8aa3b, v171
	v_mul_f32_e32 v172, 0x3fb8aa3b, v172
	v_mul_f32_e32 v173, 0x3fb8aa3b, v173
	v_exp_f32_e32 v170, v170
	v_exp_f32_e32 v171, v171
	v_exp_f32_e32 v172, v172
	v_exp_f32_e32 v173, v173
	v_pk_mul_f32 v[64:65], v[64:65], s[12:13]
	v_pk_mul_f32 v[66:67], v[66:67], s[12:13]
	v_pk_mul_f32 v[64:65], v[170:171], v[64:65]
	v_pk_mul_f32 v[66:67], v[172:173], v[66:67]
	v_cvt_pk_bf16_f32 v64, v64, v65
	v_cvt_pk_bf16_f32 v65, v66, v67
	ds_write_b64 v161, v[64:65] offset:24576
	v_add_u32_e32 v164, 0x40000, v164
	global_load_dwordx4 v[180:183], v164, s[20:21]
	global_load_dwordx4 v[184:187], v164, s[20:21] offset:64
	global_load_dwordx4 v[188:191], v164, s[20:21] offset:512
	global_load_dwordx4 v[192:195], v164, s[20:21] offset:576
	v_add_u32_e32 v164, 0x10000, v164
	global_load_dwordx4 v[206:209], v164, s[20:21]
	global_load_dwordx4 v[210:213], v164, s[20:21] offset:64
	global_load_dwordx4 v[214:217], v164, s[20:21] offset:512
	global_load_dwordx4 v[224:227], v164, s[20:21] offset:576
	v_add_u32_e32 v164, 0x10000, v164
	global_load_dwordx4 v[228:231], v164, s[20:21]
	global_load_dwordx4 v[232:235], v164, s[20:21] offset:64
	global_load_dwordx4 v[236:239], v164, s[20:21] offset:512
	global_load_dwordx4 v[240:243], v164, s[20:21] offset:576
	v_add_u32_e32 v164, 0x10000, v164
	global_load_dwordx4 v[244:247], v164, s[20:21]
	global_load_dwordx4 v[248:251], v164, s[20:21] offset:64
	global_load_dwordx4 v[166:169], v164, s[20:21] offset:512
	global_load_dwordx4 v[170:173], v164, s[20:21] offset:576
	v_add_u32_e32 v164, 0x10000, v164
	s_waitcnt vmcnt(0)
; DEV u32x2 pk4(f32x4 v) { u32x2 r = {pk_bf16(v[0], v[1]), pk_bf16(v[2], v[3])}; return r; }
; DEV int sig4(int x) { return ((x & 1) << 1) | (x >> 1); }
;   DEV void operator()(f32x4 (&acc)[2][2][4][2], int brow, int bcol, int wr, int wc, int fr, int fq) const {
;     ...
;               const f32x4 b4 = *(const f32x4*)(bmat + (size_t)tok * 1024 + lc);
;               const int pcl = (cl & ~15) + 4 * sig4((cl >> 2) & 3);
;               if (mode == 3) {
;                 for (int j = 0; j < 4; ++j) v[j] = v[j] * scale * __expf(b4[j]);
;                 tile_put4(rl, pcl, pk4(v));
	v_mul_f32_e32 v180, 0x3fb8aa3b, v180
	v_mul_f32_e32 v181, 0x3fb8aa3b, v181
	v_mul_f32_e32 v182, 0x3fb8aa3b, v182
	v_mul_f32_e32 v183, 0x3fb8aa3b, v183
	v_exp_f32_e32 v180, v180
	v_exp_f32_e32 v181, v181
	v_exp_f32_e32 v182, v182
	v_exp_f32_e32 v183, v183
	v_pk_mul_f32 v[60:61], v[60:61], s[12:13]
	v_pk_mul_f32 v[62:63], v[62:63], s[12:13]
	v_pk_mul_f32 v[60:61], v[180:181], v[60:61]
	v_pk_mul_f32 v[62:63], v[182:183], v[62:63]
	v_cvt_pk_bf16_f32 v60, v60, v61
	v_cvt_pk_bf16_f32 v61, v62, v63
	ds_write_b64 v162, v[60:61]
	v_mul_f32_e32 v184, 0x3fb8aa3b, v184
	v_mul_f32_e32 v185, 0x3fb8aa3b, v185
	v_mul_f32_e32 v186, 0x3fb8aa3b, v186
	v_mul_f32_e32 v187, 0x3fb8aa3b, v187
	v_exp_f32_e32 v184, v184
	v_exp_f32_e32 v185, v185
	v_exp_f32_e32 v186, v186
	v_exp_f32_e32 v187, v187
	v_pk_mul_f32 v[56:57], v[56:57], s[12:13]
	v_pk_mul_f32 v[58:59], v[58:59], s[12:13]
	v_pk_mul_f32 v[56:57], v[184:185], v[56:57]
	v_pk_mul_f32 v[58:59], v[186:187], v[58:59]
	v_cvt_pk_bf16_f32 v56, v56, v57
	v_cvt_pk_bf16_f32 v57, v58, v59
	ds_write_b64 v163, v[56:57]
	v_mul_f32_e32 v188, 0x3fb8aa3b, v188
	v_mul_f32_e32 v189, 0x3fb8aa3b, v189
	v_mul_f32_e32 v190, 0x3fb8aa3b, v190
	v_mul_f32_e32 v191, 0x3fb8aa3b, v191
	v_exp_f32_e32 v188, v188
	v_exp_f32_e32 v189, v189
	v_exp_f32_e32 v190, v190
	v_exp_f32_e32 v191, v191
	v_pk_mul_f32 v[52:53], v[52:53], s[12:13]
	v_pk_mul_f32 v[54:55], v[54:55], s[12:13]
	v_pk_mul_f32 v[52:53], v[188:189], v[52:53]
	v_pk_mul_f32 v[54:55], v[190:191], v[54:55]
	v_cvt_pk_bf16_f32 v52, v52, v53
	v_cvt_pk_bf16_f32 v53, v54, v55
	ds_write_b64 v162, v[52:53] offset:256
	v_mul_f32_e32 v192, 0x3fb8aa3b, v192
	v_mul_f32_e32 v193, 0x3fb8aa3b, v193
	v_mul_f32_e32 v194, 0x3fb8aa3b, v194
	v_mul_f32_e32 v195, 0x3fb8aa3b, v195
	v_exp_f32_e32 v192, v192
	v_exp_f32_e32 v193, v193
	v_exp_f32_e32 v194, v194
	v_exp_f32_e32 v195, v195
	v_pk_mul_f32 v[48:49], v[48:49], s[12:13]
	v_pk_mul_f32 v[50:51], v[50:51], s[12:13]
	v_pk_mul_f32 v[48:49], v[192:193], v[48:49]
	v_pk_mul_f32 v[50:51], v[194:195], v[50:51]
	v_cvt_pk_bf16_f32 v48, v48, v49
	v_cvt_pk_bf16_f32 v49, v50, v51
	ds_write_b64 v163, v[48:49] offset:256
	v_mul_f32_e32 v206, 0x3fb8aa3b, v206
	v_mul_f32_e32 v207, 0x3fb8aa3b, v207
	v_mul_f32_e32 v208, 0x3fb8aa3b, v208
	v_mul_f32_e32 v209, 0x3fb8aa3b, v209
	v_exp_f32_e32 v206, v206
	v_exp_f32_e32 v207, v207
	v_exp_f32_e32 v208, v208
	v_exp_f32_e32 v209, v209
	v_pk_mul_f32 v[44:45], v[44:45], s[12:13]
	v_pk_mul_f32 v[46:47], v[46:47], s[12:13]
	v_pk_mul_f32 v[44:45], v[206:207], v[44:45]
	v_pk_mul_f32 v[46:47], v[208:209], v[46:47]
	v_cvt_pk_bf16_f32 v44, v44, v45
	v_cvt_pk_bf16_f32 v45, v46, v47
	ds_write_b64 v162, v[44:45] offset:8448
	v_mul_f32_e32 v210, 0x3fb8aa3b, v210
	v_mul_f32_e32 v211, 0x3fb8aa3b, v211
	v_mul_f32_e32 v212, 0x3fb8aa3b, v212
	v_mul_f32_e32 v213, 0x3fb8aa3b, v213
	v_exp_f32_e32 v210, v210
	v_exp_f32_e32 v211, v211
	v_exp_f32_e32 v212, v212
	v_exp_f32_e32 v213, v213
	v_pk_mul_f32 v[40:41], v[40:41], s[12:13]
	v_pk_mul_f32 v[42:43], v[42:43], s[12:13]
	v_pk_mul_f32 v[40:41], v[210:211], v[40:41]
	v_pk_mul_f32 v[42:43], v[212:213], v[42:43]
	v_cvt_pk_bf16_f32 v40, v40, v41
	v_cvt_pk_bf16_f32 v41, v42, v43
	ds_write_b64 v163, v[40:41] offset:8448
	v_mul_f32_e32 v214, 0x3fb8aa3b, v214
	v_mul_f32_e32 v215, 0x3fb8aa3b, v215
	v_mul_f32_e32 v216, 0x3fb8aa3b, v216
	v_mul_f32_e32 v217, 0x3fb8aa3b, v217
	v_exp_f32_e32 v214, v214
	v_exp_f32_e32 v215, v215
	v_exp_f32_e32 v216, v216
	v_exp_f32_e32 v217, v217
	v_pk_mul_f32 v[36:37], v[36:37], s[12:13]
	v_pk_mul_f32 v[38:39], v[38:39], s[12:13]
	v_pk_mul_f32 v[36:37], v[214:215], v[36:37]
	v_pk_mul_f32 v[38:39], v[216:217], v[38:39]
	v_cvt_pk_bf16_f32 v36, v36, v37
	v_cvt_pk_bf16_f32 v37, v38, v39
	ds_write_b64 v162, v[36:37] offset:8192
	v_mul_f32_e32 v224, 0x3fb8aa3b, v224
	v_mul_f32_e32 v225, 0x3fb8aa3b, v225
	v_mul_f32_e32 v226, 0x3fb8aa3b, v226
	v_mul_f32_e32 v227, 0x3fb8aa3b, v227
	v_exp_f32_e32 v224, v224
	v_exp_f32_e32 v225, v225
	v_exp_f32_e32 v226, v226
	v_exp_f32_e32 v227, v227
	v_pk_mul_f32 v[32:33], v[32:33], s[12:13]
	v_pk_mul_f32 v[34:35], v[34:35], s[12:13]
	v_pk_mul_f32 v[32:33], v[224:225], v[32:33]
	v_pk_mul_f32 v[34:35], v[226:227], v[34:35]
	v_cvt_pk_bf16_f32 v32, v32, v33
	v_cvt_pk_bf16_f32 v33, v34, v35
	ds_write_b64 v163, v[32:33] offset:8192
	v_mul_f32_e32 v228, 0x3fb8aa3b, v228
	v_mul_f32_e32 v229, 0x3fb8aa3b, v229
	v_mul_f32_e32 v230, 0x3fb8aa3b, v230
	v_mul_f32_e32 v231, 0x3fb8aa3b, v231
	v_exp_f32_e32 v228, v228
	v_exp_f32_e32 v229, v229
	v_exp_f32_e32 v230, v230
	v_exp_f32_e32 v231, v231
	v_pk_mul_f32 v[28:29], v[28:29], s[12:13]
	v_pk_mul_f32 v[30:31], v[30:31], s[12:13]
	v_pk_mul_f32 v[28:29], v[228:229], v[28:29]
	v_pk_mul_f32 v[30:31], v[230:231], v[30:31]
	v_cvt_pk_bf16_f32 v28, v28, v29
	v_cvt_pk_bf16_f32 v29, v30, v31
	ds_write_b64 v162, v[28:29] offset:16384
	v_mul_f32_e32 v232, 0x3fb8aa3b, v232
	v_mul_f32_e32 v233, 0x3fb8aa3b, v233
	v_mul_f32_e32 v234, 0x3fb8aa3b, v234
	v_mul_f32_e32 v235, 0x3fb8aa3b, v235
	v_exp_f32_e32 v232, v232
	v_exp_f32_e32 v233, v233
	v_exp_f32_e32 v234, v234
	v_exp_f32_e32 v235, v235
	v_pk_mul_f32 v[24:25], v[24:25], s[12:13]
	v_pk_mul_f32 v[26:27], v[26:27], s[12:13]
	v_pk_mul_f32 v[24:25], v[232:233], v[24:25]
	v_pk_mul_f32 v[26:27], v[234:235], v[26:27]
	v_cvt_pk_bf16_f32 v24, v24, v25
	v_cvt_pk_bf16_f32 v25, v26, v27
	ds_write_b64 v163, v[24:25] offset:16384
	v_mul_f32_e32 v236, 0x3fb8aa3b, v236
	v_mul_f32_e32 v237, 0x3fb8aa3b, v237
	v_mul_f32_e32 v238, 0x3fb8aa3b, v238
	v_mul_f32_e32 v239, 0x3fb8aa3b, v239
	v_exp_f32_e32 v236, v236
	v_exp_f32_e32 v237, v237
	v_exp_f32_e32 v238, v238
	v_exp_f32_e32 v239, v239
; DEV u32x2 pk4(f32x4 v) { u32x2 r = {pk_bf16(v[0], v[1]), pk_bf16(v[2], v[3])}; return r; }
; DEV int sig4(int x) { return ((x & 1) << 1) | (x >> 1); }
;   DEV void operator()(f32x4 (&acc)[2][2][4][2], int brow, int bcol, int wr, int wc, int fr, int fq) const {
;     ...
;               const f32x4 b4 = *(const f32x4*)(bmat + (size_t)tok * 1024 + lc);
;               const int pcl = (cl & ~15) + 4 * sig4((cl >> 2) & 3);
;               if (mode == 3) {
;                 for (int j = 0; j < 4; ++j) v[j] = v[j] * scale * __expf(b4[j]);
;                 tile_put4(rl, pcl, pk4(v));
;               } else {
;                 const f32x4 bl = *(const f32x4*)(bmat + (size_t)(tok | 63) * 1024 + lc);
;                 f32x4 kd, ke;
;                 for (int j = 0; j < 4; ++j) { kd[j] = v[j] * __expf(-b4[j]); ke[j] = v[j] * __expf(bl[j] - b4[j]); }
;                 tile_put4(rl, pcl, pk4(kd));
;                 (void)ke;
	v_pk_mul_f32 v[20:21], v[20:21], s[12:13]
	v_pk_mul_f32 v[22:23], v[22:23], s[12:13]
	v_pk_mul_f32 v[20:21], v[236:237], v[20:21]
	v_pk_mul_f32 v[22:23], v[238:239], v[22:23]
	v_cvt_pk_bf16_f32 v20, v20, v21
	v_cvt_pk_bf16_f32 v21, v22, v23
	ds_write_b64 v162, v[20:21] offset:16640
	v_mul_f32_e32 v240, 0x3fb8aa3b, v240
	v_mul_f32_e32 v241, 0x3fb8aa3b, v241
	v_mul_f32_e32 v242, 0x3fb8aa3b, v242
	v_mul_f32_e32 v243, 0x3fb8aa3b, v243
	v_exp_f32_e32 v240, v240
	v_exp_f32_e32 v241, v241
	v_exp_f32_e32 v242, v242
	v_exp_f32_e32 v243, v243
	v_pk_mul_f32 v[16:17], v[16:17], s[12:13]
	v_pk_mul_f32 v[18:19], v[18:19], s[12:13]
	v_pk_mul_f32 v[16:17], v[240:241], v[16:17]
	v_pk_mul_f32 v[18:19], v[242:243], v[18:19]
	v_cvt_pk_bf16_f32 v16, v16, v17
	v_cvt_pk_bf16_f32 v17, v18, v19
	ds_write_b64 v163, v[16:17] offset:16640
	v_mul_f32_e32 v244, 0x3fb8aa3b, v244
	v_mul_f32_e32 v245, 0x3fb8aa3b, v245
	v_mul_f32_e32 v246, 0x3fb8aa3b, v246
	v_mul_f32_e32 v247, 0x3fb8aa3b, v247
	v_exp_f32_e32 v244, v244
	v_exp_f32_e32 v245, v245
	v_exp_f32_e32 v246, v246
	v_exp_f32_e32 v247, v247
	v_pk_mul_f32 v[12:13], v[12:13], s[12:13]
	v_pk_mul_f32 v[14:15], v[14:15], s[12:13]
	v_pk_mul_f32 v[12:13], v[244:245], v[12:13]
	v_pk_mul_f32 v[14:15], v[246:247], v[14:15]
	v_cvt_pk_bf16_f32 v12, v12, v13
	v_cvt_pk_bf16_f32 v13, v14, v15
	ds_write_b64 v162, v[12:13] offset:24832
	v_mul_f32_e32 v248, 0x3fb8aa3b, v248
	v_mul_f32_e32 v249, 0x3fb8aa3b, v249
	v_mul_f32_e32 v250, 0x3fb8aa3b, v250
	v_mul_f32_e32 v251, 0x3fb8aa3b, v251
	v_exp_f32_e32 v248, v248
	v_exp_f32_e32 v249, v249
	v_exp_f32_e32 v250, v250
	v_exp_f32_e32 v251, v251
	v_pk_mul_f32 v[8:9], v[8:9], s[12:13]
	v_pk_mul_f32 v[10:11], v[10:11], s[12:13]
	v_pk_mul_f32 v[8:9], v[248:249], v[8:9]
	v_pk_mul_f32 v[10:11], v[250:251], v[10:11]
	v_cvt_pk_bf16_f32 v8, v8, v9
	v_cvt_pk_bf16_f32 v9, v10, v11
	ds_write_b64 v163, v[8:9] offset:24832
	v_mul_f32_e32 v166, 0x3fb8aa3b, v166
	v_mul_f32_e32 v167, 0x3fb8aa3b, v167
	v_mul_f32_e32 v168, 0x3fb8aa3b, v168
	v_mul_f32_e32 v169, 0x3fb8aa3b, v169
	v_exp_f32_e32 v166, v166
	v_exp_f32_e32 v167, v167
	v_exp_f32_e32 v168, v168
	v_exp_f32_e32 v169, v169
	v_pk_mul_f32 v[4:5], v[4:5], s[12:13]
	v_pk_mul_f32 v[6:7], v[6:7], s[12:13]
	v_pk_mul_f32 v[4:5], v[166:167], v[4:5]
	v_pk_mul_f32 v[6:7], v[168:169], v[6:7]
	v_cvt_pk_bf16_f32 v4, v4, v5
	v_cvt_pk_bf16_f32 v5, v6, v7
	ds_write_b64 v162, v[4:5] offset:24576
	v_mul_f32_e32 v170, 0x3fb8aa3b, v170
	v_mul_f32_e32 v171, 0x3fb8aa3b, v171
	v_mul_f32_e32 v172, 0x3fb8aa3b, v172
	v_mul_f32_e32 v173, 0x3fb8aa3b, v173
	v_exp_f32_e32 v170, v170
	v_exp_f32_e32 v171, v171
	v_exp_f32_e32 v172, v172
	v_exp_f32_e32 v173, v173
	v_pk_mul_f32 v[0:1], v[0:1], s[12:13]
	v_pk_mul_f32 v[2:3], v[2:3], s[12:13]
	v_pk_mul_f32 v[0:1], v[170:171], v[0:1]
	v_pk_mul_f32 v[2:3], v[172:173], v[2:3]
	v_cvt_pk_bf16_f32 v0, v0, v1
	v_cvt_pk_bf16_f32 v1, v2, v3
	ds_write_b64 v163, v[0:1] offset:24576
	s_branch .Lepi_lean_rows
.Lepi_lean_k4:
	global_load_dwordx4 v[128:131], v165, s[20:21]
	global_load_dwordx4 v[132:135], v165, s[20:21] offset:64
	global_load_dwordx4 v[136:139], v165, s[20:21] offset:512
	global_load_dwordx4 v[140:143], v165, s[20:21] offset:576
	s_waitcnt vmcnt(0)
	v_sub_f32_e32 v174, v128, v180
	v_sub_f32_e32 v175, v129, v181
	v_sub_f32_e32 v204, v130, v182
	v_sub_f32_e32 v205, v131, v183
	v_mul_f32_e32 v180, 0xbfb8aa3b, v180
	v_mul_f32_e32 v181, 0xbfb8aa3b, v181
	v_mul_f32_e32 v182, 0xbfb8aa3b, v182
	v_mul_f32_e32 v183, 0xbfb8aa3b, v183
	v_mul_f32_e32 v174, 0x3fb8aa3b, v174
	v_mul_f32_e32 v175, 0x3fb8aa3b, v175
	v_mul_f32_e32 v204, 0x3fb8aa3b, v204
	v_mul_f32_e32 v205, 0x3fb8aa3b, v205
	v_exp_f32_e32 v180, v180
	v_exp_f32_e32 v181, v181
	v_exp_f32_e32 v182, v182
	v_exp_f32_e32 v183, v183
	v_exp_f32_e32 v174, v174
	v_exp_f32_e32 v175, v175
	v_exp_f32_e32 v204, v204
	v_exp_f32_e32 v205, v205
	v_pk_mul_f32 v[180:181], v[124:125], v[180:181]
	v_pk_mul_f32 v[182:183], v[126:127], v[182:183]
	v_pk_mul_f32 v[124:125], v[124:125], v[174:175]
	v_pk_mul_f32 v[126:127], v[126:127], v[204:205]
	v_cvt_pk_bf16_f32 v180, v180, v181
	v_cvt_pk_bf16_f32 v181, v182, v183
	ds_write_b64 v160, v[180:181]
	v_sub_f32_e32 v174, v132, v184
	v_sub_f32_e32 v175, v133, v185
	v_sub_f32_e32 v204, v134, v186
	v_sub_f32_e32 v205, v135, v187
	v_mul_f32_e32 v184, 0xbfb8aa3b, v184
	v_mul_f32_e32 v185, 0xbfb8aa3b, v185
	v_mul_f32_e32 v186, 0xbfb8aa3b, v186
	v_mul_f32_e32 v187, 0xbfb8aa3b, v187
	v_mul_f32_e32 v174, 0x3fb8aa3b, v174
	v_mul_f32_e32 v175, 0x3fb8aa3b, v175
	v_mul_f32_e32 v204, 0x3fb8aa3b, v204
	v_mul_f32_e32 v205, 0x3fb8aa3b, v205
	v_exp_f32_e32 v184, v184
	v_exp_f32_e32 v185, v185
	v_exp_f32_e32 v186, v186
	v_exp_f32_e32 v187, v187
	v_exp_f32_e32 v174, v174
	v_exp_f32_e32 v175, v175
	v_exp_f32_e32 v204, v204
	v_exp_f32_e32 v205, v205
	v_pk_mul_f32 v[184:185], v[120:121], v[184:185]
	v_pk_mul_f32 v[186:187], v[122:123], v[186:187]
	v_pk_mul_f32 v[120:121], v[120:121], v[174:175]
	v_pk_mul_f32 v[122:123], v[122:123], v[204:205]
	v_cvt_pk_bf16_f32 v184, v184, v185
	v_cvt_pk_bf16_f32 v185, v186, v187
	ds_write_b64 v161, v[184:185]
	v_sub_f32_e32 v174, v136, v188
	v_sub_f32_e32 v175, v137, v189
	v_sub_f32_e32 v204, v138, v190
	v_sub_f32_e32 v205, v139, v191
	v_mul_f32_e32 v188, 0xbfb8aa3b, v188
	v_mul_f32_e32 v189, 0xbfb8aa3b, v189
	v_mul_f32_e32 v190, 0xbfb8aa3b, v190
	v_mul_f32_e32 v191, 0xbfb8aa3b, v191
	v_mul_f32_e32 v174, 0x3fb8aa3b, v174
	v_mul_f32_e32 v175, 0x3fb8aa3b, v175
	v_mul_f32_e32 v204, 0x3fb8aa3b, v204
	v_mul_f32_e32 v205, 0x3fb8aa3b, v205
	v_exp_f32_e32 v188, v188
	v_exp_f32_e32 v189, v189
	v_exp_f32_e32 v190, v190
	v_exp_f32_e32 v191, v191
	v_exp_f32_e32 v174, v174
; DEV u32x2 pk4(f32x4 v) { u32x2 r = {pk_bf16(v[0], v[1]), pk_bf16(v[2], v[3])}; return r; }
;   DEV void operator()(f32x4 (&acc)[2][2][4][2], int brow, int bcol, int wr, int wc, int fr, int fq) const {
;     ...
;               } else {
;                 const f32x4 bl = *(const f32x4*)(bmat + (size_t)(tok | 63) * 1024 + lc);
;                 f32x4 kd, ke;
;                 for (int j = 0; j < 4; ++j) { kd[j] = v[j] * __expf(-b4[j]); ke[j] = v[j] * __expf(bl[j] - b4[j]); }
;                 tile_put4(rl, pcl, pk4(kd));
;                 (void)ke;
	v_exp_f32_e32 v175, v175
	v_exp_f32_e32 v204, v204
	v_exp_f32_e32 v205, v205
	v_pk_mul_f32 v[188:189], v[116:117], v[188:189]
	v_pk_mul_f32 v[190:191], v[118:119], v[190:191]
	v_pk_mul_f32 v[116:117], v[116:117], v[174:175]
	v_pk_mul_f32 v[118:119], v[118:119], v[204:205]
	v_cvt_pk_bf16_f32 v188, v188, v189
	v_cvt_pk_bf16_f32 v189, v190, v191
	ds_write_b64 v160, v[188:189] offset:256
	v_sub_f32_e32 v174, v140, v192
	v_sub_f32_e32 v175, v141, v193
	v_sub_f32_e32 v204, v142, v194
	v_sub_f32_e32 v205, v143, v195
	v_mul_f32_e32 v192, 0xbfb8aa3b, v192
	v_mul_f32_e32 v193, 0xbfb8aa3b, v193
	v_mul_f32_e32 v194, 0xbfb8aa3b, v194
	v_mul_f32_e32 v195, 0xbfb8aa3b, v195
	v_mul_f32_e32 v174, 0x3fb8aa3b, v174
	v_mul_f32_e32 v175, 0x3fb8aa3b, v175
	v_mul_f32_e32 v204, 0x3fb8aa3b, v204
	v_mul_f32_e32 v205, 0x3fb8aa3b, v205
	v_exp_f32_e32 v192, v192
	v_exp_f32_e32 v193, v193
	v_exp_f32_e32 v194, v194
	v_exp_f32_e32 v195, v195
	v_exp_f32_e32 v174, v174
	v_exp_f32_e32 v175, v175
	v_exp_f32_e32 v204, v204
	v_exp_f32_e32 v205, v205
	v_pk_mul_f32 v[192:193], v[112:113], v[192:193]
	v_pk_mul_f32 v[194:195], v[114:115], v[194:195]
	v_pk_mul_f32 v[112:113], v[112:113], v[174:175]
	v_pk_mul_f32 v[114:115], v[114:115], v[204:205]
	v_cvt_pk_bf16_f32 v192, v192, v193
	v_cvt_pk_bf16_f32 v193, v194, v195
	ds_write_b64 v161, v[192:193] offset:256
	v_sub_f32_e32 v174, v128, v206
	v_sub_f32_e32 v175, v129, v207
	v_sub_f32_e32 v204, v130, v208
	v_sub_f32_e32 v205, v131, v209
	v_mul_f32_e32 v206, 0xbfb8aa3b, v206
	v_mul_f32_e32 v207, 0xbfb8aa3b, v207
	v_mul_f32_e32 v208, 0xbfb8aa3b, v208
	v_mul_f32_e32 v209, 0xbfb8aa3b, v209
	v_mul_f32_e32 v174, 0x3fb8aa3b, v174
	v_mul_f32_e32 v175, 0x3fb8aa3b, v175
	v_mul_f32_e32 v204, 0x3fb8aa3b, v204
	v_mul_f32_e32 v205, 0x3fb8aa3b, v205
	v_exp_f32_e32 v206, v206
	v_exp_f32_e32 v207, v207
	v_exp_f32_e32 v208, v208
	v_exp_f32_e32 v209, v209
	v_exp_f32_e32 v174, v174
	v_exp_f32_e32 v175, v175
	v_exp_f32_e32 v204, v204
	v_exp_f32_e32 v205, v205
	v_pk_mul_f32 v[206:207], v[108:109], v[206:207]
	v_pk_mul_f32 v[208:209], v[110:111], v[208:209]
	v_pk_mul_f32 v[108:109], v[108:109], v[174:175]
	v_pk_mul_f32 v[110:111], v[110:111], v[204:205]
	v_cvt_pk_bf16_f32 v206, v206, v207
	v_cvt_pk_bf16_f32 v207, v208, v209
	ds_write_b64 v160, v[206:207] offset:8448
	v_sub_f32_e32 v174, v132, v210
	v_sub_f32_e32 v175, v133, v211
	v_sub_f32_e32 v204, v134, v212
	v_sub_f32_e32 v205, v135, v213
	v_mul_f32_e32 v210, 0xbfb8aa3b, v210
	v_mul_f32_e32 v211, 0xbfb8aa3b, v211
	v_mul_f32_e32 v212, 0xbfb8aa3b, v212
	v_mul_f32_e32 v213, 0xbfb8aa3b, v213
	v_mul_f32_e32 v174, 0x3fb8aa3b, v174
	v_mul_f32_e32 v175, 0x3fb8aa3b, v175
	v_mul_f32_e32 v204, 0x3fb8aa3b, v204
	v_mul_f32_e32 v205, 0x3fb8aa3b, v205
	v_exp_f32_e32 v210, v210
	v_exp_f32_e32 v211, v211
	v_exp_f32_e32 v212, v212
	v_exp_f32_e32 v213, v213
	v_exp_f32_e32 v174, v174
	v_exp_f32_e32 v175, v175
	v_exp_f32_e32 v204, v204
	v_exp_f32_e32 v205, v205
	v_pk_mul_f32 v[210:211], v[104:105], v[210:211]
	v_pk_mul_f32 v[212:213], v[106:107], v[212:213]
	v_pk_mul_f32 v[104:105], v[104:105], v[174:175]
	v_pk_mul_f32 v[106:107], v[106:107], v[204:205]
	v_cvt_pk_bf16_f32 v210, v210, v211
	v_cvt_pk_bf16_f32 v211, v212, v213
	ds_write_b64 v161, v[210:211] offset:8448
	v_sub_f32_e32 v174, v136, v214
	v_sub_f32_e32 v175, v137, v215
	v_sub_f32_e32 v204, v138, v216
	v_sub_f32_e32 v205, v139, v217
	v_mul_f32_e32 v214, 0xbfb8aa3b, v214
	v_mul_f32_e32 v215, 0xbfb8aa3b, v215
	v_mul_f32_e32 v216, 0xbfb8aa3b, v216
	v_mul_f32_e32 v217, 0xbfb8aa3b, v217
	v_mul_f32_e32 v174, 0x3fb8aa3b, v174
	v_mul_f32_e32 v175, 0x3fb8aa3b, v175
	v_mul_f32_e32 v204, 0x3fb8aa3b, v204
	v_mul_f32_e32 v205, 0x3fb8aa3b, v205
	v_exp_f32_e32 v214, v214
	v_exp_f32_e32 v215, v215
	v_exp_f32_e32 v216, v216
	v_exp_f32_e32 v217, v217
	v_exp_f32_e32 v174, v174
	v_exp_f32_e32 v175, v175
	v_exp_f32_e32 v204, v204
	v_exp_f32_e32 v205, v205
	v_pk_mul_f32 v[214:215], v[100:101], v[214:215]
	v_pk_mul_f32 v[216:217], v[102:103], v[216:217]
	v_pk_mul_f32 v[100:101], v[100:101], v[174:175]
	v_pk_mul_f32 v[102:103], v[102:103], v[204:205]
	v_cvt_pk_bf16_f32 v214, v214, v215
	v_cvt_pk_bf16_f32 v215, v216, v217
	ds_write_b64 v160, v[214:215] offset:8192
	v_sub_f32_e32 v174, v140, v224
	v_sub_f32_e32 v175, v141, v225
	v_sub_f32_e32 v204, v142, v226
	v_sub_f32_e32 v205, v143, v227
	v_mul_f32_e32 v224, 0xbfb8aa3b, v224
	v_mul_f32_e32 v225, 0xbfb8aa3b, v225
	v_mul_f32_e32 v226, 0xbfb8aa3b, v226
	v_mul_f32_e32 v227, 0xbfb8aa3b, v227
	v_mul_f32_e32 v174, 0x3fb8aa3b, v174
	v_mul_f32_e32 v175, 0x3fb8aa3b, v175
	v_mul_f32_e32 v204, 0x3fb8aa3b, v204
	v_mul_f32_e32 v205, 0x3fb8aa3b, v205
	v_exp_f32_e32 v224, v224
	v_exp_f32_e32 v225, v225
	v_exp_f32_e32 v226, v226
	v_exp_f32_e32 v227, v227
	v_exp_f32_e32 v174, v174
	v_exp_f32_e32 v175, v175
	v_exp_f32_e32 v204, v204
	v_exp_f32_e32 v205, v205
	v_pk_mul_f32 v[224:225], v[96:97], v[224:225]
	v_pk_mul_f32 v[226:227], v[98:99], v[226:227]
	v_pk_mul_f32 v[96:97], v[96:97], v[174:175]
	v_pk_mul_f32 v[98:99], v[98:99], v[204:205]
	v_cvt_pk_bf16_f32 v224, v224, v225
	v_cvt_pk_bf16_f32 v225, v226, v227
	ds_write_b64 v161, v[224:225] offset:8192
	v_sub_f32_e32 v174, v128, v228
	v_sub_f32_e32 v175, v129, v229
	v_sub_f32_e32 v204, v130, v230
	v_sub_f32_e32 v205, v131, v231
	v_mul_f32_e32 v228, 0xbfb8aa3b, v228
	v_mul_f32_e32 v229, 0xbfb8aa3b, v229
	v_mul_f32_e32 v230, 0xbfb8aa3b, v230
	v_mul_f32_e32 v231, 0xbfb8aa3b, v231
	v_mul_f32_e32 v174, 0x3fb8aa3b, v174
	v_mul_f32_e32 v175, 0x3fb8aa3b, v175
	v_mul_f32_e32 v204, 0x3fb8aa3b, v204
	v_mul_f32_e32 v205, 0x3fb8aa3b, v205
	v_exp_f32_e32 v228, v228
	v_exp_f32_e32 v229, v229
	v_exp_f32_e32 v230, v230
; DEV u32x2 pk4(f32x4 v) { u32x2 r = {pk_bf16(v[0], v[1]), pk_bf16(v[2], v[3])}; return r; }
;   DEV void operator()(f32x4 (&acc)[2][2][4][2], int brow, int bcol, int wr, int wc, int fr, int fq) const {
;     ...
;               } else {
;                 const f32x4 bl = *(const f32x4*)(bmat + (size_t)(tok | 63) * 1024 + lc);
;                 f32x4 kd, ke;
;                 for (int j = 0; j < 4; ++j) { kd[j] = v[j] * __expf(-b4[j]); ke[j] = v[j] * __expf(bl[j] - b4[j]); }
;                 tile_put4(rl, pcl, pk4(kd));
;                 (void)ke;
	v_exp_f32_e32 v231, v231
	v_exp_f32_e32 v174, v174
	v_exp_f32_e32 v175, v175
	v_exp_f32_e32 v204, v204
	v_exp_f32_e32 v205, v205
	v_pk_mul_f32 v[228:229], v[92:93], v[228:229]
	v_pk_mul_f32 v[230:231], v[94:95], v[230:231]
	v_pk_mul_f32 v[92:93], v[92:93], v[174:175]
	v_pk_mul_f32 v[94:95], v[94:95], v[204:205]
	v_cvt_pk_bf16_f32 v228, v228, v229
	v_cvt_pk_bf16_f32 v229, v230, v231
	ds_write_b64 v160, v[228:229] offset:16384
	v_sub_f32_e32 v174, v132, v232
	v_sub_f32_e32 v175, v133, v233
	v_sub_f32_e32 v204, v134, v234
	v_sub_f32_e32 v205, v135, v235
	v_mul_f32_e32 v232, 0xbfb8aa3b, v232
	v_mul_f32_e32 v233, 0xbfb8aa3b, v233
	v_mul_f32_e32 v234, 0xbfb8aa3b, v234
	v_mul_f32_e32 v235, 0xbfb8aa3b, v235
	v_mul_f32_e32 v174, 0x3fb8aa3b, v174
	v_mul_f32_e32 v175, 0x3fb8aa3b, v175
	v_mul_f32_e32 v204, 0x3fb8aa3b, v204
	v_mul_f32_e32 v205, 0x3fb8aa3b, v205
	v_exp_f32_e32 v232, v232
	v_exp_f32_e32 v233, v233
	v_exp_f32_e32 v234, v234
	v_exp_f32_e32 v235, v235
	v_exp_f32_e32 v174, v174
	v_exp_f32_e32 v175, v175
	v_exp_f32_e32 v204, v204
	v_exp_f32_e32 v205, v205
	v_pk_mul_f32 v[232:233], v[88:89], v[232:233]
	v_pk_mul_f32 v[234:235], v[90:91], v[234:235]
	v_pk_mul_f32 v[88:89], v[88:89], v[174:175]
	v_pk_mul_f32 v[90:91], v[90:91], v[204:205]
	v_cvt_pk_bf16_f32 v232, v232, v233
	v_cvt_pk_bf16_f32 v233, v234, v235
	ds_write_b64 v161, v[232:233] offset:16384
	v_sub_f32_e32 v174, v136, v236
	v_sub_f32_e32 v175, v137, v237
	v_sub_f32_e32 v204, v138, v238
	v_sub_f32_e32 v205, v139, v239
	v_mul_f32_e32 v236, 0xbfb8aa3b, v236
	v_mul_f32_e32 v237, 0xbfb8aa3b, v237
	v_mul_f32_e32 v238, 0xbfb8aa3b, v238
	v_mul_f32_e32 v239, 0xbfb8aa3b, v239
	v_mul_f32_e32 v174, 0x3fb8aa3b, v174
	v_mul_f32_e32 v175, 0x3fb8aa3b, v175
	v_mul_f32_e32 v204, 0x3fb8aa3b, v204
	v_mul_f32_e32 v205, 0x3fb8aa3b, v205
	v_exp_f32_e32 v236, v236
	v_exp_f32_e32 v237, v237
	v_exp_f32_e32 v238, v238
	v_exp_f32_e32 v239, v239
	v_exp_f32_e32 v174, v174
	v_exp_f32_e32 v175, v175
	v_exp_f32_e32 v204, v204
	v_exp_f32_e32 v205, v205
	v_pk_mul_f32 v[236:237], v[84:85], v[236:237]
	v_pk_mul_f32 v[238:239], v[86:87], v[238:239]
	v_pk_mul_f32 v[84:85], v[84:85], v[174:175]
	v_pk_mul_f32 v[86:87], v[86:87], v[204:205]
	v_cvt_pk_bf16_f32 v236, v236, v237
	v_cvt_pk_bf16_f32 v237, v238, v239
	ds_write_b64 v160, v[236:237] offset:16640
	v_sub_f32_e32 v174, v140, v240
	v_sub_f32_e32 v175, v141, v241
	v_sub_f32_e32 v204, v142, v242
	v_sub_f32_e32 v205, v143, v243
	v_mul_f32_e32 v240, 0xbfb8aa3b, v240
	v_mul_f32_e32 v241, 0xbfb8aa3b, v241
	v_mul_f32_e32 v242, 0xbfb8aa3b, v242
	v_mul_f32_e32 v243, 0xbfb8aa3b, v243
	v_mul_f32_e32 v174, 0x3fb8aa3b, v174
	v_mul_f32_e32 v175, 0x3fb8aa3b, v175
	v_mul_f32_e32 v204, 0x3fb8aa3b, v204
	v_mul_f32_e32 v205, 0x3fb8aa3b, v205
	v_exp_f32_e32 v240, v240
	v_exp_f32_e32 v241, v241
	v_exp_f32_e32 v242, v242
	v_exp_f32_e32 v243, v243
	v_exp_f32_e32 v174, v174
	v_exp_f32_e32 v175, v175
	v_exp_f32_e32 v204, v204
	v_exp_f32_e32 v205, v205
	v_pk_mul_f32 v[240:241], v[80:81], v[240:241]
	v_pk_mul_f32 v[242:243], v[82:83], v[242:243]
	v_pk_mul_f32 v[80:81], v[80:81], v[174:175]
	v_pk_mul_f32 v[82:83], v[82:83], v[204:205]
	v_cvt_pk_bf16_f32 v240, v240, v241
	v_cvt_pk_bf16_f32 v241, v242, v243
	ds_write_b64 v161, v[240:241] offset:16640
	v_sub_f32_e32 v174, v128, v244
	v_sub_f32_e32 v175, v129, v245
	v_sub_f32_e32 v204, v130, v246
	v_sub_f32_e32 v205, v131, v247
	v_mul_f32_e32 v244, 0xbfb8aa3b, v244
	v_mul_f32_e32 v245, 0xbfb8aa3b, v245
	v_mul_f32_e32 v246, 0xbfb8aa3b, v246
	v_mul_f32_e32 v247, 0xbfb8aa3b, v247
	v_mul_f32_e32 v174, 0x3fb8aa3b, v174
	v_mul_f32_e32 v175, 0x3fb8aa3b, v175
	v_mul_f32_e32 v204, 0x3fb8aa3b, v204
	v_mul_f32_e32 v205, 0x3fb8aa3b, v205
	v_exp_f32_e32 v244, v244
	v_exp_f32_e32 v245, v245
	v_exp_f32_e32 v246, v246
	v_exp_f32_e32 v247, v247
	v_exp_f32_e32 v174, v174
	v_exp_f32_e32 v175, v175
	v_exp_f32_e32 v204, v204
	v_exp_f32_e32 v205, v205
	v_pk_mul_f32 v[244:245], v[76:77], v[244:245]
	v_pk_mul_f32 v[246:247], v[78:79], v[246:247]
	v_pk_mul_f32 v[76:77], v[76:77], v[174:175]
	v_pk_mul_f32 v[78:79], v[78:79], v[204:205]
	v_cvt_pk_bf16_f32 v244, v244, v245
	v_cvt_pk_bf16_f32 v245, v246, v247
	ds_write_b64 v160, v[244:245] offset:24832
	v_sub_f32_e32 v174, v132, v248
	v_sub_f32_e32 v175, v133, v249
	v_sub_f32_e32 v204, v134, v250
	v_sub_f32_e32 v205, v135, v251
	v_mul_f32_e32 v248, 0xbfb8aa3b, v248
	v_mul_f32_e32 v249, 0xbfb8aa3b, v249
	v_mul_f32_e32 v250, 0xbfb8aa3b, v250
	v_mul_f32_e32 v251, 0xbfb8aa3b, v251
	v_mul_f32_e32 v174, 0x3fb8aa3b, v174
	v_mul_f32_e32 v175, 0x3fb8aa3b, v175
	v_mul_f32_e32 v204, 0x3fb8aa3b, v204
	v_mul_f32_e32 v205, 0x3fb8aa3b, v205
	v_exp_f32_e32 v248, v248
	v_exp_f32_e32 v249, v249
	v_exp_f32_e32 v250, v250
	v_exp_f32_e32 v251, v251
	v_exp_f32_e32 v174, v174
	v_exp_f32_e32 v175, v175
	v_exp_f32_e32 v204, v204
	v_exp_f32_e32 v205, v205
	v_pk_mul_f32 v[248:249], v[72:73], v[248:249]
	v_pk_mul_f32 v[250:251], v[74:75], v[250:251]
	v_pk_mul_f32 v[72:73], v[72:73], v[174:175]
	v_pk_mul_f32 v[74:75], v[74:75], v[204:205]
	v_cvt_pk_bf16_f32 v248, v248, v249
	v_cvt_pk_bf16_f32 v249, v250, v251
	ds_write_b64 v161, v[248:249] offset:24832
	v_sub_f32_e32 v174, v136, v166
	v_sub_f32_e32 v175, v137, v167
	v_sub_f32_e32 v204, v138, v168
	v_sub_f32_e32 v205, v139, v169
	v_mul_f32_e32 v166, 0xbfb8aa3b, v166
	v_mul_f32_e32 v167, 0xbfb8aa3b, v167
	v_mul_f32_e32 v168, 0xbfb8aa3b, v168
	v_mul_f32_e32 v169, 0xbfb8aa3b, v169
	v_mul_f32_e32 v174, 0x3fb8aa3b, v174
	v_mul_f32_e32 v175, 0x3fb8aa3b, v175
	v_mul_f32_e32 v204, 0x3fb8aa3b, v204
	v_mul_f32_e32 v205, 0x3fb8aa3b, v205
	v_exp_f32_e32 v166, v166
	v_exp_f32_e32 v167, v167
	v_exp_f32_e32 v168, v168
; DEV u32x2 pk4(f32x4 v) { u32x2 r = {pk_bf16(v[0], v[1]), pk_bf16(v[2], v[3])}; return r; }
;   DEV void operator()(f32x4 (&acc)[2][2][4][2], int brow, int bcol, int wr, int wc, int fr, int fq) const {
;     ...
;               } else {
;                 const f32x4 bl = *(const f32x4*)(bmat + (size_t)(tok | 63) * 1024 + lc);
;                 f32x4 kd, ke;
;                 for (int j = 0; j < 4; ++j) { kd[j] = v[j] * __expf(-b4[j]); ke[j] = v[j] * __expf(bl[j] - b4[j]); }
;                 tile_put4(rl, pcl, pk4(kd));
;                 (void)ke;
	v_exp_f32_e32 v169, v169
	v_exp_f32_e32 v174, v174
	v_exp_f32_e32 v175, v175
	v_exp_f32_e32 v204, v204
	v_exp_f32_e32 v205, v205
	v_pk_mul_f32 v[166:167], v[68:69], v[166:167]
	v_pk_mul_f32 v[168:169], v[70:71], v[168:169]
	v_pk_mul_f32 v[68:69], v[68:69], v[174:175]
	v_pk_mul_f32 v[70:71], v[70:71], v[204:205]
	v_cvt_pk_bf16_f32 v166, v166, v167
	v_cvt_pk_bf16_f32 v167, v168, v169
	ds_write_b64 v160, v[166:167] offset:24576
	v_sub_f32_e32 v174, v140, v170
	v_sub_f32_e32 v175, v141, v171
	v_sub_f32_e32 v204, v142, v172
	v_sub_f32_e32 v205, v143, v173
	v_mul_f32_e32 v170, 0xbfb8aa3b, v170
	v_mul_f32_e32 v171, 0xbfb8aa3b, v171
	v_mul_f32_e32 v172, 0xbfb8aa3b, v172
	v_mul_f32_e32 v173, 0xbfb8aa3b, v173
	v_mul_f32_e32 v174, 0x3fb8aa3b, v174
	v_mul_f32_e32 v175, 0x3fb8aa3b, v175
	v_mul_f32_e32 v204, 0x3fb8aa3b, v204
	v_mul_f32_e32 v205, 0x3fb8aa3b, v205
	v_exp_f32_e32 v170, v170
	v_exp_f32_e32 v171, v171
	v_exp_f32_e32 v172, v172
	v_exp_f32_e32 v173, v173
	v_exp_f32_e32 v174, v174
	v_exp_f32_e32 v175, v175
	v_exp_f32_e32 v204, v204
	v_exp_f32_e32 v205, v205
	v_pk_mul_f32 v[170:171], v[64:65], v[170:171]
	v_pk_mul_f32 v[172:173], v[66:67], v[172:173]
	v_pk_mul_f32 v[64:65], v[64:65], v[174:175]
	v_pk_mul_f32 v[66:67], v[66:67], v[204:205]
	v_cvt_pk_bf16_f32 v170, v170, v171
	v_cvt_pk_bf16_f32 v171, v172, v173
	ds_write_b64 v161, v[170:171] offset:24576
	v_add_u32_e32 v164, 0x40000, v164
	global_load_dwordx4 v[180:183], v164, s[20:21]
	global_load_dwordx4 v[184:187], v164, s[20:21] offset:64
	global_load_dwordx4 v[188:191], v164, s[20:21] offset:512
	global_load_dwordx4 v[192:195], v164, s[20:21] offset:576
	v_add_u32_e32 v164, 0x10000, v164
	global_load_dwordx4 v[206:209], v164, s[20:21]
	global_load_dwordx4 v[210:213], v164, s[20:21] offset:64
	global_load_dwordx4 v[214:217], v164, s[20:21] offset:512
	global_load_dwordx4 v[224:227], v164, s[20:21] offset:576
	v_add_u32_e32 v164, 0x10000, v164
	global_load_dwordx4 v[228:231], v164, s[20:21]
	global_load_dwordx4 v[232:235], v164, s[20:21] offset:64
	global_load_dwordx4 v[236:239], v164, s[20:21] offset:512
	global_load_dwordx4 v[240:243], v164, s[20:21] offset:576
	v_add_u32_e32 v164, 0x10000, v164
	global_load_dwordx4 v[244:247], v164, s[20:21]
	global_load_dwordx4 v[248:251], v164, s[20:21] offset:64
	global_load_dwordx4 v[166:169], v164, s[20:21] offset:512
	global_load_dwordx4 v[170:173], v164, s[20:21] offset:576
	v_add_u32_e32 v164, 0x10000, v164
	v_add_u32_e32 v165, 0x80000, v165
	global_load_dwordx4 v[144:147], v165, s[20:21]
	global_load_dwordx4 v[148:151], v165, s[20:21] offset:64
	global_load_dwordx4 v[152:155], v165, s[20:21] offset:512
	global_load_dwordx4 v[156:159], v165, s[20:21] offset:576
	s_waitcnt vmcnt(0)
	v_sub_f32_e32 v174, v144, v180
	v_sub_f32_e32 v175, v145, v181
	v_sub_f32_e32 v204, v146, v182
	v_sub_f32_e32 v205, v147, v183
	v_mul_f32_e32 v180, 0xbfb8aa3b, v180
	v_mul_f32_e32 v181, 0xbfb8aa3b, v181
	v_mul_f32_e32 v182, 0xbfb8aa3b, v182
	v_mul_f32_e32 v183, 0xbfb8aa3b, v183
	v_mul_f32_e32 v174, 0x3fb8aa3b, v174
	v_mul_f32_e32 v175, 0x3fb8aa3b, v175
	v_mul_f32_e32 v204, 0x3fb8aa3b, v204
	v_mul_f32_e32 v205, 0x3fb8aa3b, v205
	v_exp_f32_e32 v180, v180
	v_exp_f32_e32 v181, v181
	v_exp_f32_e32 v182, v182
	v_exp_f32_e32 v183, v183
	v_exp_f32_e32 v174, v174
	v_exp_f32_e32 v175, v175
	v_exp_f32_e32 v204, v204
	v_exp_f32_e32 v205, v205
	v_pk_mul_f32 v[180:181], v[60:61], v[180:181]
	v_pk_mul_f32 v[182:183], v[62:63], v[182:183]
	v_pk_mul_f32 v[60:61], v[60:61], v[174:175]
	v_pk_mul_f32 v[62:63], v[62:63], v[204:205]
	v_cvt_pk_bf16_f32 v180, v180, v181
	v_cvt_pk_bf16_f32 v181, v182, v183
	ds_write_b64 v162, v[180:181]
	v_sub_f32_e32 v174, v148, v184
	v_sub_f32_e32 v175, v149, v185
	v_sub_f32_e32 v204, v150, v186
	v_sub_f32_e32 v205, v151, v187
	v_mul_f32_e32 v184, 0xbfb8aa3b, v184
	v_mul_f32_e32 v185, 0xbfb8aa3b, v185
	v_mul_f32_e32 v186, 0xbfb8aa3b, v186
	v_mul_f32_e32 v187, 0xbfb8aa3b, v187
	v_mul_f32_e32 v174, 0x3fb8aa3b, v174
	v_mul_f32_e32 v175, 0x3fb8aa3b, v175
	v_mul_f32_e32 v204, 0x3fb8aa3b, v204
	v_mul_f32_e32 v205, 0x3fb8aa3b, v205
	v_exp_f32_e32 v184, v184
	v_exp_f32_e32 v185, v185
	v_exp_f32_e32 v186, v186
	v_exp_f32_e32 v187, v187
	v_exp_f32_e32 v174, v174
	v_exp_f32_e32 v175, v175
	v_exp_f32_e32 v204, v204
	v_exp_f32_e32 v205, v205
	v_pk_mul_f32 v[184:185], v[56:57], v[184:185]
	v_pk_mul_f32 v[186:187], v[58:59], v[186:187]
	v_pk_mul_f32 v[56:57], v[56:57], v[174:175]
	v_pk_mul_f32 v[58:59], v[58:59], v[204:205]
	v_cvt_pk_bf16_f32 v184, v184, v185
	v_cvt_pk_bf16_f32 v185, v186, v187
	ds_write_b64 v163, v[184:185]
	v_sub_f32_e32 v174, v152, v188
	v_sub_f32_e32 v175, v153, v189
	v_sub_f32_e32 v204, v154, v190
	v_sub_f32_e32 v205, v155, v191
	v_mul_f32_e32 v188, 0xbfb8aa3b, v188
	v_mul_f32_e32 v189, 0xbfb8aa3b, v189
	v_mul_f32_e32 v190, 0xbfb8aa3b, v190
	v_mul_f32_e32 v191, 0xbfb8aa3b, v191
	v_mul_f32_e32 v174, 0x3fb8aa3b, v174
	v_mul_f32_e32 v175, 0x3fb8aa3b, v175
	v_mul_f32_e32 v204, 0x3fb8aa3b, v204
	v_mul_f32_e32 v205, 0x3fb8aa3b, v205
	v_exp_f32_e32 v188, v188
	v_exp_f32_e32 v189, v189
	v_exp_f32_e32 v190, v190
	v_exp_f32_e32 v191, v191
	v_exp_f32_e32 v174, v174
	v_exp_f32_e32 v175, v175
	v_exp_f32_e32 v204, v204
	v_exp_f32_e32 v205, v205
	v_pk_mul_f32 v[188:189], v[52:53], v[188:189]
	v_pk_mul_f32 v[190:191], v[54:55], v[190:191]
	v_pk_mul_f32 v[52:53], v[52:53], v[174:175]
	v_pk_mul_f32 v[54:55], v[54:55], v[204:205]
	v_cvt_pk_bf16_f32 v188, v188, v189
	v_cvt_pk_bf16_f32 v189, v190, v191
	ds_write_b64 v162, v[188:189] offset:256
	v_sub_f32_e32 v174, v156, v192
	v_sub_f32_e32 v175, v157, v193
	v_sub_f32_e32 v204, v158, v194
	v_sub_f32_e32 v205, v159, v195
; DEV u32x2 pk4(f32x4 v) { u32x2 r = {pk_bf16(v[0], v[1]), pk_bf16(v[2], v[3])}; return r; }
;   DEV void operator()(f32x4 (&acc)[2][2][4][2], int brow, int bcol, int wr, int wc, int fr, int fq) const {
;     ...
;               } else {
;                 const f32x4 bl = *(const f32x4*)(bmat + (size_t)(tok | 63) * 1024 + lc);
;                 f32x4 kd, ke;
;                 for (int j = 0; j < 4; ++j) { kd[j] = v[j] * __expf(-b4[j]); ke[j] = v[j] * __expf(bl[j] - b4[j]); }
;                 tile_put4(rl, pcl, pk4(kd));
;                 (void)ke;
	v_mul_f32_e32 v192, 0xbfb8aa3b, v192
	v_mul_f32_e32 v193, 0xbfb8aa3b, v193
	v_mul_f32_e32 v194, 0xbfb8aa3b, v194
	v_mul_f32_e32 v195, 0xbfb8aa3b, v195
	v_mul_f32_e32 v174, 0x3fb8aa3b, v174
	v_mul_f32_e32 v175, 0x3fb8aa3b, v175
	v_mul_f32_e32 v204, 0x3fb8aa3b, v204
	v_mul_f32_e32 v205, 0x3fb8aa3b, v205
	v_exp_f32_e32 v192, v192
	v_exp_f32_e32 v193, v193
	v_exp_f32_e32 v194, v194
	v_exp_f32_e32 v195, v195
	v_exp_f32_e32 v174, v174
	v_exp_f32_e32 v175, v175
	v_exp_f32_e32 v204, v204
	v_exp_f32_e32 v205, v205
	v_pk_mul_f32 v[192:193], v[48:49], v[192:193]
	v_pk_mul_f32 v[194:195], v[50:51], v[194:195]
	v_pk_mul_f32 v[48:49], v[48:49], v[174:175]
	v_pk_mul_f32 v[50:51], v[50:51], v[204:205]
	v_cvt_pk_bf16_f32 v192, v192, v193
	v_cvt_pk_bf16_f32 v193, v194, v195
	ds_write_b64 v163, v[192:193] offset:256
	v_sub_f32_e32 v174, v144, v206
	v_sub_f32_e32 v175, v145, v207
	v_sub_f32_e32 v204, v146, v208
	v_sub_f32_e32 v205, v147, v209
	v_mul_f32_e32 v206, 0xbfb8aa3b, v206
	v_mul_f32_e32 v207, 0xbfb8aa3b, v207
	v_mul_f32_e32 v208, 0xbfb8aa3b, v208
	v_mul_f32_e32 v209, 0xbfb8aa3b, v209
	v_mul_f32_e32 v174, 0x3fb8aa3b, v174
	v_mul_f32_e32 v175, 0x3fb8aa3b, v175
	v_mul_f32_e32 v204, 0x3fb8aa3b, v204
	v_mul_f32_e32 v205, 0x3fb8aa3b, v205
	v_exp_f32_e32 v206, v206
	v_exp_f32_e32 v207, v207
	v_exp_f32_e32 v208, v208
	v_exp_f32_e32 v209, v209
	v_exp_f32_e32 v174, v174
	v_exp_f32_e32 v175, v175
	v_exp_f32_e32 v204, v204
	v_exp_f32_e32 v205, v205
	v_pk_mul_f32 v[206:207], v[44:45], v[206:207]
	v_pk_mul_f32 v[208:209], v[46:47], v[208:209]
	v_pk_mul_f32 v[44:45], v[44:45], v[174:175]
	v_pk_mul_f32 v[46:47], v[46:47], v[204:205]
	v_cvt_pk_bf16_f32 v206, v206, v207
	v_cvt_pk_bf16_f32 v207, v208, v209
	ds_write_b64 v162, v[206:207] offset:8448
	v_sub_f32_e32 v174, v148, v210
	v_sub_f32_e32 v175, v149, v211
	v_sub_f32_e32 v204, v150, v212
	v_sub_f32_e32 v205, v151, v213
	v_mul_f32_e32 v210, 0xbfb8aa3b, v210
	v_mul_f32_e32 v211, 0xbfb8aa3b, v211
	v_mul_f32_e32 v212, 0xbfb8aa3b, v212
	v_mul_f32_e32 v213, 0xbfb8aa3b, v213
	v_mul_f32_e32 v174, 0x3fb8aa3b, v174
	v_mul_f32_e32 v175, 0x3fb8aa3b, v175
	v_mul_f32_e32 v204, 0x3fb8aa3b, v204
	v_mul_f32_e32 v205, 0x3fb8aa3b, v205
	v_exp_f32_e32 v210, v210
	v_exp_f32_e32 v211, v211
	v_exp_f32_e32 v212, v212
	v_exp_f32_e32 v213, v213
	v_exp_f32_e32 v174, v174
	v_exp_f32_e32 v175, v175
	v_exp_f32_e32 v204, v204
	v_exp_f32_e32 v205, v205
	v_pk_mul_f32 v[210:211], v[40:41], v[210:211]
	v_pk_mul_f32 v[212:213], v[42:43], v[212:213]
	v_pk_mul_f32 v[40:41], v[40:41], v[174:175]
	v_pk_mul_f32 v[42:43], v[42:43], v[204:205]
	v_cvt_pk_bf16_f32 v210, v210, v211
	v_cvt_pk_bf16_f32 v211, v212, v213
	ds_write_b64 v163, v[210:211] offset:8448
	v_sub_f32_e32 v174, v152, v214
	v_sub_f32_e32 v175, v153, v215
	v_sub_f32_e32 v204, v154, v216
	v_sub_f32_e32 v205, v155, v217
	v_mul_f32_e32 v214, 0xbfb8aa3b, v214
	v_mul_f32_e32 v215, 0xbfb8aa3b, v215
	v_mul_f32_e32 v216, 0xbfb8aa3b, v216
	v_mul_f32_e32 v217, 0xbfb8aa3b, v217
	v_mul_f32_e32 v174, 0x3fb8aa3b, v174
	v_mul_f32_e32 v175, 0x3fb8aa3b, v175
	v_mul_f32_e32 v204, 0x3fb8aa3b, v204
	v_mul_f32_e32 v205, 0x3fb8aa3b, v205
	v_exp_f32_e32 v214, v214
	v_exp_f32_e32 v215, v215
	v_exp_f32_e32 v216, v216
	v_exp_f32_e32 v217, v217
	v_exp_f32_e32 v174, v174
	v_exp_f32_e32 v175, v175
	v_exp_f32_e32 v204, v204
	v_exp_f32_e32 v205, v205
	v_pk_mul_f32 v[214:215], v[36:37], v[214:215]
	v_pk_mul_f32 v[216:217], v[38:39], v[216:217]
	v_pk_mul_f32 v[36:37], v[36:37], v[174:175]
	v_pk_mul_f32 v[38:39], v[38:39], v[204:205]
	v_cvt_pk_bf16_f32 v214, v214, v215
	v_cvt_pk_bf16_f32 v215, v216, v217
	ds_write_b64 v162, v[214:215] offset:8192
	v_sub_f32_e32 v174, v156, v224
	v_sub_f32_e32 v175, v157, v225
	v_sub_f32_e32 v204, v158, v226
	v_sub_f32_e32 v205, v159, v227
	v_mul_f32_e32 v224, 0xbfb8aa3b, v224
	v_mul_f32_e32 v225, 0xbfb8aa3b, v225
	v_mul_f32_e32 v226, 0xbfb8aa3b, v226
	v_mul_f32_e32 v227, 0xbfb8aa3b, v227
	v_mul_f32_e32 v174, 0x3fb8aa3b, v174
	v_mul_f32_e32 v175, 0x3fb8aa3b, v175
	v_mul_f32_e32 v204, 0x3fb8aa3b, v204
	v_mul_f32_e32 v205, 0x3fb8aa3b, v205
	v_exp_f32_e32 v224, v224
	v_exp_f32_e32 v225, v225
	v_exp_f32_e32 v226, v226
	v_exp_f32_e32 v227, v227
	v_exp_f32_e32 v174, v174
	v_exp_f32_e32 v175, v175
	v_exp_f32_e32 v204, v204
	v_exp_f32_e32 v205, v205
	v_pk_mul_f32 v[224:225], v[32:33], v[224:225]
	v_pk_mul_f32 v[226:227], v[34:35], v[226:227]
	v_pk_mul_f32 v[32:33], v[32:33], v[174:175]
	v_pk_mul_f32 v[34:35], v[34:35], v[204:205]
	v_cvt_pk_bf16_f32 v224, v224, v225
	v_cvt_pk_bf16_f32 v225, v226, v227
	ds_write_b64 v163, v[224:225] offset:8192
	v_sub_f32_e32 v174, v144, v228
	v_sub_f32_e32 v175, v145, v229
	v_sub_f32_e32 v204, v146, v230
	v_sub_f32_e32 v205, v147, v231
	v_mul_f32_e32 v228, 0xbfb8aa3b, v228
	v_mul_f32_e32 v229, 0xbfb8aa3b, v229
	v_mul_f32_e32 v230, 0xbfb8aa3b, v230
	v_mul_f32_e32 v231, 0xbfb8aa3b, v231
	v_mul_f32_e32 v174, 0x3fb8aa3b, v174
	v_mul_f32_e32 v175, 0x3fb8aa3b, v175
	v_mul_f32_e32 v204, 0x3fb8aa3b, v204
	v_mul_f32_e32 v205, 0x3fb8aa3b, v205
	v_exp_f32_e32 v228, v228
	v_exp_f32_e32 v229, v229
	v_exp_f32_e32 v230, v230
	v_exp_f32_e32 v231, v231
	v_exp_f32_e32 v174, v174
	v_exp_f32_e32 v175, v175
	v_exp_f32_e32 v204, v204
	v_exp_f32_e32 v205, v205
	v_pk_mul_f32 v[228:229], v[28:29], v[228:229]
	v_pk_mul_f32 v[230:231], v[30:31], v[230:231]
	v_pk_mul_f32 v[28:29], v[28:29], v[174:175]
	v_pk_mul_f32 v[30:31], v[30:31], v[204:205]
	v_cvt_pk_bf16_f32 v228, v228, v229
	v_cvt_pk_bf16_f32 v229, v230, v231
	ds_write_b64 v162, v[228:229] offset:16384
	v_sub_f32_e32 v174, v148, v232
	v_sub_f32_e32 v175, v149, v233
	v_sub_f32_e32 v204, v150, v234
	v_sub_f32_e32 v205, v151, v235
; DEV u32x2 pk4(f32x4 v) { u32x2 r = {pk_bf16(v[0], v[1]), pk_bf16(v[2], v[3])}; return r; }
; template <bool NT = false>
; DEV void tile_rows_out(bf16_t* __restrict__ out0, const size_t ld, const int tid) {
; #pragma unroll
;   for (int i = 0; i < 16; ++i) {
;     const int id = i * 512 + tid, r = id >> 5, pos = id & 31, c = pos ^ (r & 31);
;     const u32x4 v = *(const u32x4*)(smem + r * 512 + pos * 16);
;     if (NT) __builtin_nontemporal_store(v, (u32x4*)(out0 + (size_t)r * ld + 8 * c)); else *(u32x4*)(out0 + (size_t)r * ld + 8 * c) = v;
;   }
;   DEV void operator()(f32x4 (&acc)[2][2][4][2], int brow, int bcol, int wr, int wc, int fr, int fq) const {
;     ...
;               } else {
;                 const f32x4 bl = *(const f32x4*)(bmat + (size_t)(tok | 63) * 1024 + lc);
;                 f32x4 kd, ke;
;                 for (int j = 0; j < 4; ++j) { kd[j] = v[j] * __expf(-b4[j]); ke[j] = v[j] * __expf(bl[j] - b4[j]); }
;                 tile_put4(rl, pcl, pk4(kd));
;                 (void)ke;
;               }
;             }
;           }
;       }
;     __syncthreads();
;     tile_rows_out<true>(out + (size_t)brow * ld + (bcol - segstart), (size_t)ld, (wr * 4 + wc) * 64 + fq * 16 + fr);
	v_mul_f32_e32 v232, 0xbfb8aa3b, v232
	v_mul_f32_e32 v233, 0xbfb8aa3b, v233
	v_mul_f32_e32 v234, 0xbfb8aa3b, v234
	v_mul_f32_e32 v235, 0xbfb8aa3b, v235
	v_mul_f32_e32 v174, 0x3fb8aa3b, v174
	v_mul_f32_e32 v175, 0x3fb8aa3b, v175
	v_mul_f32_e32 v204, 0x3fb8aa3b, v204
	v_mul_f32_e32 v205, 0x3fb8aa3b, v205
	v_exp_f32_e32 v232, v232
	v_exp_f32_e32 v233, v233
	v_exp_f32_e32 v234, v234
	v_exp_f32_e32 v235, v235
	v_exp_f32_e32 v174, v174
	v_exp_f32_e32 v175, v175
	v_exp_f32_e32 v204, v204
	v_exp_f32_e32 v205, v205
	v_pk_mul_f32 v[232:233], v[24:25], v[232:233]
	v_pk_mul_f32 v[234:235], v[26:27], v[234:235]
	v_pk_mul_f32 v[24:25], v[24:25], v[174:175]
	v_pk_mul_f32 v[26:27], v[26:27], v[204:205]
	v_cvt_pk_bf16_f32 v232, v232, v233
	v_cvt_pk_bf16_f32 v233, v234, v235
	ds_write_b64 v163, v[232:233] offset:16384
	v_sub_f32_e32 v174, v152, v236
	v_sub_f32_e32 v175, v153, v237
	v_sub_f32_e32 v204, v154, v238
	v_sub_f32_e32 v205, v155, v239
	v_mul_f32_e32 v236, 0xbfb8aa3b, v236
	v_mul_f32_e32 v237, 0xbfb8aa3b, v237
	v_mul_f32_e32 v238, 0xbfb8aa3b, v238
	v_mul_f32_e32 v239, 0xbfb8aa3b, v239
	v_mul_f32_e32 v174, 0x3fb8aa3b, v174
	v_mul_f32_e32 v175, 0x3fb8aa3b, v175
	v_mul_f32_e32 v204, 0x3fb8aa3b, v204
	v_mul_f32_e32 v205, 0x3fb8aa3b, v205
	v_exp_f32_e32 v236, v236
	v_exp_f32_e32 v237, v237
	v_exp_f32_e32 v238, v238
	v_exp_f32_e32 v239, v239
	v_exp_f32_e32 v174, v174
	v_exp_f32_e32 v175, v175
	v_exp_f32_e32 v204, v204
	v_exp_f32_e32 v205, v205
	v_pk_mul_f32 v[236:237], v[20:21], v[236:237]
	v_pk_mul_f32 v[238:239], v[22:23], v[238:239]
	v_pk_mul_f32 v[20:21], v[20:21], v[174:175]
	v_pk_mul_f32 v[22:23], v[22:23], v[204:205]
	v_cvt_pk_bf16_f32 v236, v236, v237
	v_cvt_pk_bf16_f32 v237, v238, v239
	ds_write_b64 v162, v[236:237] offset:16640
	v_sub_f32_e32 v174, v156, v240
	v_sub_f32_e32 v175, v157, v241
	v_sub_f32_e32 v204, v158, v242
	v_sub_f32_e32 v205, v159, v243
	v_mul_f32_e32 v240, 0xbfb8aa3b, v240
	v_mul_f32_e32 v241, 0xbfb8aa3b, v241
	v_mul_f32_e32 v242, 0xbfb8aa3b, v242
	v_mul_f32_e32 v243, 0xbfb8aa3b, v243
	v_mul_f32_e32 v174, 0x3fb8aa3b, v174
	v_mul_f32_e32 v175, 0x3fb8aa3b, v175
	v_mul_f32_e32 v204, 0x3fb8aa3b, v204
	v_mul_f32_e32 v205, 0x3fb8aa3b, v205
	v_exp_f32_e32 v240, v240
	v_exp_f32_e32 v241, v241
	v_exp_f32_e32 v242, v242
	v_exp_f32_e32 v243, v243
	v_exp_f32_e32 v174, v174
	v_exp_f32_e32 v175, v175
	v_exp_f32_e32 v204, v204
	v_exp_f32_e32 v205, v205
	v_pk_mul_f32 v[240:241], v[16:17], v[240:241]
	v_pk_mul_f32 v[242:243], v[18:19], v[242:243]
	v_pk_mul_f32 v[16:17], v[16:17], v[174:175]
	v_pk_mul_f32 v[18:19], v[18:19], v[204:205]
	v_cvt_pk_bf16_f32 v240, v240, v241
	v_cvt_pk_bf16_f32 v241, v242, v243
	ds_write_b64 v163, v[240:241] offset:16640
	v_sub_f32_e32 v174, v144, v244
	v_sub_f32_e32 v175, v145, v245
	v_sub_f32_e32 v204, v146, v246
	v_sub_f32_e32 v205, v147, v247
	v_mul_f32_e32 v244, 0xbfb8aa3b, v244
	v_mul_f32_e32 v245, 0xbfb8aa3b, v245
	v_mul_f32_e32 v246, 0xbfb8aa3b, v246
	v_mul_f32_e32 v247, 0xbfb8aa3b, v247
	v_mul_f32_e32 v174, 0x3fb8aa3b, v174
	v_mul_f32_e32 v175, 0x3fb8aa3b, v175
	v_mul_f32_e32 v204, 0x3fb8aa3b, v204
	v_mul_f32_e32 v205, 0x3fb8aa3b, v205
	v_exp_f32_e32 v244, v244
	v_exp_f32_e32 v245, v245
	v_exp_f32_e32 v246, v246
	v_exp_f32_e32 v247, v247
	v_exp_f32_e32 v174, v174
	v_exp_f32_e32 v175, v175
	v_exp_f32_e32 v204, v204
	v_exp_f32_e32 v205, v205
	v_pk_mul_f32 v[244:245], v[12:13], v[244:245]
	v_pk_mul_f32 v[246:247], v[14:15], v[246:247]
	v_pk_mul_f32 v[12:13], v[12:13], v[174:175]
	v_pk_mul_f32 v[14:15], v[14:15], v[204:205]
	v_cvt_pk_bf16_f32 v244, v244, v245
	v_cvt_pk_bf16_f32 v245, v246, v247
	ds_write_b64 v162, v[244:245] offset:24832
	v_sub_f32_e32 v174, v148, v248
	v_sub_f32_e32 v175, v149, v249
	v_sub_f32_e32 v204, v150, v250
	v_sub_f32_e32 v205, v151, v251
	v_mul_f32_e32 v248, 0xbfb8aa3b, v248
	v_mul_f32_e32 v249, 0xbfb8aa3b, v249
	v_mul_f32_e32 v250, 0xbfb8aa3b, v250
	v_mul_f32_e32 v251, 0xbfb8aa3b, v251
	v_mul_f32_e32 v174, 0x3fb8aa3b, v174
	v_mul_f32_e32 v175, 0x3fb8aa3b, v175
	v_mul_f32_e32 v204, 0x3fb8aa3b, v204
	v_mul_f32_e32 v205, 0x3fb8aa3b, v205
	v_exp_f32_e32 v248, v248
	v_exp_f32_e32 v249, v249
	v_exp_f32_e32 v250, v250
	v_exp_f32_e32 v251, v251
	v_exp_f32_e32 v174, v174
	v_exp_f32_e32 v175, v175
	v_exp_f32_e32 v204, v204
	v_exp_f32_e32 v205, v205
	v_pk_mul_f32 v[248:249], v[8:9], v[248:249]
	v_pk_mul_f32 v[250:251], v[10:11], v[250:251]
	v_pk_mul_f32 v[8:9], v[8:9], v[174:175]
	v_pk_mul_f32 v[10:11], v[10:11], v[204:205]
	v_cvt_pk_bf16_f32 v248, v248, v249
	v_cvt_pk_bf16_f32 v249, v250, v251
	ds_write_b64 v163, v[248:249] offset:24832
	v_sub_f32_e32 v174, v152, v166
	v_sub_f32_e32 v175, v153, v167
	v_sub_f32_e32 v204, v154, v168
	v_sub_f32_e32 v205, v155, v169
	v_mul_f32_e32 v166, 0xbfb8aa3b, v166
	v_mul_f32_e32 v167, 0xbfb8aa3b, v167
	v_mul_f32_e32 v168, 0xbfb8aa3b, v168
	v_mul_f32_e32 v169, 0xbfb8aa3b, v169
	v_mul_f32_e32 v174, 0x3fb8aa3b, v174
	v_mul_f32_e32 v175, 0x3fb8aa3b, v175
	v_mul_f32_e32 v204, 0x3fb8aa3b, v204
	v_mul_f32_e32 v205, 0x3fb8aa3b, v205
	v_exp_f32_e32 v166, v166
	v_exp_f32_e32 v167, v167
	v_exp_f32_e32 v168, v168
	v_exp_f32_e32 v169, v169
	v_exp_f32_e32 v174, v174
	v_exp_f32_e32 v175, v175
	v_exp_f32_e32 v204, v204
	v_exp_f32_e32 v205, v205
	v_pk_mul_f32 v[166:167], v[4:5], v[166:167]
	v_pk_mul_f32 v[168:169], v[6:7], v[168:169]
	v_pk_mul_f32 v[4:5], v[4:5], v[174:175]
	v_pk_mul_f32 v[6:7], v[6:7], v[204:205]
	v_cvt_pk_bf16_f32 v166, v166, v167
	v_cvt_pk_bf16_f32 v167, v168, v169
	ds_write_b64 v162, v[166:167] offset:24576
	v_sub_f32_e32 v174, v156, v170
	v_sub_f32_e32 v175, v157, v171
	v_sub_f32_e32 v204, v158, v172
	v_sub_f32_e32 v205, v159, v173
	v_mul_f32_e32 v170, 0xbfb8aa3b, v170
	v_mul_f32_e32 v171, 0xbfb8aa3b, v171
	v_mul_f32_e32 v172, 0xbfb8aa3b, v172
	v_mul_f32_e32 v173, 0xbfb8aa3b, v173
	v_mul_f32_e32 v174, 0x3fb8aa3b, v174
	v_mul_f32_e32 v175, 0x3fb8aa3b, v175
	v_mul_f32_e32 v204, 0x3fb8aa3b, v204
	v_mul_f32_e32 v205, 0x3fb8aa3b, v205
	v_exp_f32_e32 v170, v170
	v_exp_f32_e32 v171, v171
	v_exp_f32_e32 v172, v172
	v_exp_f32_e32 v173, v173
	v_exp_f32_e32 v174, v174
	v_exp_f32_e32 v175, v175
	v_exp_f32_e32 v204, v204
	v_exp_f32_e32 v205, v205
	v_pk_mul_f32 v[170:171], v[0:1], v[170:171]
	v_pk_mul_f32 v[172:173], v[2:3], v[172:173]
	v_pk_mul_f32 v[0:1], v[0:1], v[174:175]
	v_pk_mul_f32 v[2:3], v[2:3], v[204:205]
	v_cvt_pk_bf16_f32 v170, v170, v171
	v_cvt_pk_bf16_f32 v171, v172, v173
	ds_write_b64 v163, v[170:171] offset:24576
	s_mul_i32 s0, s4, s8
	s_sub_i32 s1, s6, s36
	s_add_i32 s0, s0, s1
	s_ashr_i32 s1, s0, 31
	s_lshl_b64 s[0:1], s[0:1], 1
	s_add_u32 s0, s14, s0
	s_addc_u32 s1, s15, s1
	v_lshrrev_b32_e32 v138, 5, v198
	v_and_b32_e32 v139, 31, v198
	v_xor_b32_e32 v139, v139, v138
	v_mul_lo_u32 v140, v138, s8
	v_lshlrev_b32_e32 v140, 1, v140
	v_lshl_add_u32 v141, v139, 4, v140
	v_xor_b32_e32 v139, 16, v139
	v_lshl_add_u32 v142, v139, 4, v140
	s_lshl_b32 s5, s8, 5
	v_add_u32_e32 v142, s5, v142
	s_lshl_b32 s5, s8, 6
	v_lshlrev_b32_e32 v143, 4, v198
	v_add_u32_e32 v144, 0x10000, v143
	s_waitcnt lgkmcnt(0)
	s_barrier
; DEV u32x2 pk4(f32x4 v) { u32x2 r = {pk_bf16(v[0], v[1]), pk_bf16(v[2], v[3])}; return r; }
; template <bool NT = false>
; DEV void tile_rows_out(bf16_t* __restrict__ out0, const size_t ld, const int tid) {
; #pragma unroll
;   for (int i = 0; i < 16; ++i) {
;     const int id = i * 512 + tid, r = id >> 5, pos = id & 31, c = pos ^ (r & 31);
;     const u32x4 v = *(const u32x4*)(smem + r * 512 + pos * 16);
;     if (NT) __builtin_nontemporal_store(v, (u32x4*)(out0 + (size_t)r * ld + 8 * c)); else *(u32x4*)(out0 + (size_t)r * ld + 8 * c) = v;
;   }
;   DEV void operator()(f32x4 (&acc)[2][2][4][2], int brow, int bcol, int wr, int wc, int fr, int fq) const {
;     ...
;     tile_rows_out<true>(out + (size_t)brow * ld + (bcol - segstart), (size_t)ld, (wr * 4 + wc) * 64 + fq * 16 + fr);
;     if (mode == 4) {
;       __syncthreads();
; #pragma unroll
;       for (int ai = 0; ai < 2; ++ai)
; #pragma unroll
;         for (int m = 0; m < 4; ++m) {
;           const int rl = ai * 128 + wr * 64 + m * 16 + fr, tok = brow + rl;
;           const int tposl = (rl & ~15) + sig16(rl & 15);
; #pragma unroll
;           for (int bj = 0; bj < 2; ++bj)
; #pragma unroll
;             for (int n = 0; n < 2; ++n) {
;               const int cl = bj * 128 + wc * 32 + n * 16 + fq * 4, lc = bcol - segstart + cl;
;               const f32x4 v = acc[ai][bj][m][n];
;               const f32x4 b4 = *(const f32x4*)(bmat + (size_t)tok * 1024 + lc);
;               const f32x4 bl = *(const f32x4*)(bmat + (size_t)(tok | 63) * 1024 + lc);
;               const u32x2 kk = pk4((f32x4){v[0] * __expf(bl[0] - b4[0]), v[1] * __expf(bl[1] - b4[1]), v[2] * __expf(bl[2] - b4[2]), v[3] * __expf(bl[3] - b4[3])});
; #pragma unroll
;               for (int j = 0; j < 4; ++j) {
;                 const int row = cl + j;
;                 const unsigned short val = (unsigned short)((j & 1) ? (kk[j >> 1] >> 16) : (kk[j >> 1] & 0xffff));
;                 *(unsigned short*)(smem + row * 512 + (((tposl >> 3) ^ (row & 31)) * 16) + (tposl & 7) * 2) = val;
;               }
	ds_read_b128 v[180:183], v143
	ds_read_b128 v[184:187], v143 offset:8192
	ds_read_b128 v[188:191], v143 offset:16384
	ds_read_b128 v[192:195], v143 offset:24576
	ds_read_b128 v[206:209], v143 offset:32768
	ds_read_b128 v[210:213], v143 offset:40960
	ds_read_b128 v[214:217], v143 offset:49152
	ds_read_b128 v[224:227], v143 offset:57344
	ds_read_b128 v[228:231], v144
	ds_read_b128 v[232:235], v144 offset:8192
	ds_read_b128 v[236:239], v144 offset:16384
	ds_read_b128 v[240:243], v144 offset:24576
	ds_read_b128 v[244:247], v144 offset:32768
	ds_read_b128 v[248:251], v144 offset:40960
	ds_read_b128 v[166:169], v144 offset:49152
	ds_read_b128 v[170:173], v144 offset:57344
	s_waitcnt lgkmcnt(15)
	global_store_dwordx4 v141, v[180:183], s[0:1] nt
	v_add_u32_e32 v141, s5, v141
	s_waitcnt lgkmcnt(14)
	global_store_dwordx4 v142, v[184:187], s[0:1] nt
	v_add_u32_e32 v142, s5, v142
	s_waitcnt lgkmcnt(13)
	global_store_dwordx4 v141, v[188:191], s[0:1] nt
	v_add_u32_e32 v141, s5, v141
	s_waitcnt lgkmcnt(12)
	global_store_dwordx4 v142, v[192:195], s[0:1] nt
	v_add_u32_e32 v142, s5, v142
	s_waitcnt lgkmcnt(11)
	global_store_dwordx4 v141, v[206:209], s[0:1] nt
	v_add_u32_e32 v141, s5, v141
	s_waitcnt lgkmcnt(10)
	global_store_dwordx4 v142, v[210:213], s[0:1] nt
	v_add_u32_e32 v142, s5, v142
	s_waitcnt lgkmcnt(9)
	global_store_dwordx4 v141, v[214:217], s[0:1] nt
	v_add_u32_e32 v141, s5, v141
	s_waitcnt lgkmcnt(8)
	global_store_dwordx4 v142, v[224:227], s[0:1] nt
	v_add_u32_e32 v142, s5, v142
	s_waitcnt lgkmcnt(7)
	global_store_dwordx4 v141, v[228:231], s[0:1] nt
	v_add_u32_e32 v141, s5, v141
	s_waitcnt lgkmcnt(6)
	global_store_dwordx4 v142, v[232:235], s[0:1] nt
	v_add_u32_e32 v142, s5, v142
	s_waitcnt lgkmcnt(5)
	global_store_dwordx4 v141, v[236:239], s[0:1] nt
	v_add_u32_e32 v141, s5, v141
	s_waitcnt lgkmcnt(4)
	global_store_dwordx4 v142, v[240:243], s[0:1] nt
	v_add_u32_e32 v142, s5, v142
	s_waitcnt lgkmcnt(3)
	global_store_dwordx4 v141, v[244:247], s[0:1] nt
	v_add_u32_e32 v141, s5, v141
	s_waitcnt lgkmcnt(2)
	global_store_dwordx4 v142, v[248:251], s[0:1] nt
	v_add_u32_e32 v142, s5, v142
	s_waitcnt lgkmcnt(1)
	global_store_dwordx4 v141, v[166:169], s[0:1] nt
	s_waitcnt lgkmcnt(0)
	global_store_dwordx4 v142, v[170:173], s[0:1] nt
	v_and_b32_e32 v148, 15, v198
	v_bfe_u32 v149, v198, 4, 2
	v_bfe_u32 v150, v198, 6, 2
	v_lshrrev_b32_e32 v151, 8, v198
	v_bfe_u32 v152, v148, 2, 1
	v_lshl_or_b32 v152, v151, 3, v152
	v_lshlrev_b32_e32 v153, 2, v149
	v_xor_b32_e32 v152, v152, v153
	v_lshlrev_b32_e32 v154, 5, v150
	v_lshl_add_u32 v154, v149, 2, v154
	v_lshlrev_b32_e32 v154, 9, v154
	v_lshrrev_b32_e32 v155, 3, v148
	v_and_b32_e32 v156, 3, v148
	v_lshl_add_u32 v155, v155, 2, v156
	v_lshl_add_u32 v154, v155, 1, v154
	v_xor_b32_e32 v157, 0, v152
	v_lshl_add_u32 v128, v157, 4, v154
	v_add_u32_e32 v136, 0x10000, v128
	v_xor_b32_e32 v157, 1, v152
	v_lshl_add_u32 v129, v157, 4, v154
	v_add_u32_e32 v137, 0x10000, v129
	v_xor_b32_e32 v157, 2, v152
	v_lshl_add_u32 v130, v157, 4, v154
	v_add_u32_e32 v138, 0x10000, v130
	v_xor_b32_e32 v157, 3, v152
	v_lshl_add_u32 v131, v157, 4, v154
	v_add_u32_e32 v139, 0x10000, v131
	v_xor_b32_e32 v157, 4, v152
	v_lshl_add_u32 v132, v157, 4, v154
	v_add_u32_e32 v140, 0x10000, v132
	v_xor_b32_e32 v157, 5, v152
	v_lshl_add_u32 v133, v157, 4, v154
	v_add_u32_e32 v141, 0x10000, v133
	v_xor_b32_e32 v157, 6, v152
	v_lshl_add_u32 v134, v157, 4, v154
	v_add_u32_e32 v142, 0x10000, v134
	v_xor_b32_e32 v157, 7, v152
	v_lshl_add_u32 v135, v157, 4, v154
	v_add_u32_e32 v143, 0x10000, v135
	s_waitcnt lgkmcnt(0)
	s_barrier
	v_cvt_pk_bf16_f32 v124, v124, v125
	v_cvt_pk_bf16_f32 v125, v126, v127
	ds_write_b16 v128, v124
	ds_write_b16_d16_hi v129, v124 offset:512
	ds_write_b16 v130, v125 offset:1024
	ds_write_b16_d16_hi v131, v125 offset:1536
	v_cvt_pk_bf16_f32 v120, v120, v121
	v_cvt_pk_bf16_f32 v121, v122, v123
	ds_write_b16 v128, v120 offset:8448
	ds_write_b16_d16_hi v129, v120 offset:8960
	ds_write_b16 v130, v121 offset:9472
	ds_write_b16_d16_hi v131, v121 offset:9984
	v_cvt_pk_bf16_f32 v116, v116, v117
	v_cvt_pk_bf16_f32 v117, v118, v119
	ds_write_b16 v136, v116
	ds_write_b16_d16_hi v137, v116 offset:512
	ds_write_b16 v138, v117 offset:1024
	ds_write_b16_d16_hi v139, v117 offset:1536
	v_cvt_pk_bf16_f32 v112, v112, v113
	v_cvt_pk_bf16_f32 v113, v114, v115
	ds_write_b16 v136, v112 offset:8448
	ds_write_b16_d16_hi v137, v112 offset:8960
	ds_write_b16 v138, v113 offset:9472
	ds_write_b16_d16_hi v139, v113 offset:9984
	v_cvt_pk_bf16_f32 v108, v108, v109
	v_cvt_pk_bf16_f32 v109, v110, v111
	ds_write_b16 v130, v108
	ds_write_b16_d16_hi v131, v108 offset:512
	ds_write_b16 v128, v109 offset:1024
	ds_write_b16_d16_hi v129, v109 offset:1536
	v_cvt_pk_bf16_f32 v104, v104, v105
	v_cvt_pk_bf16_f32 v105, v106, v107
	ds_write_b16 v130, v104 offset:8448
	ds_write_b16_d16_hi v131, v104 offset:8960
	ds_write_b16 v128, v105 offset:9472
	ds_write_b16_d16_hi v129, v105 offset:9984
	v_cvt_pk_bf16_f32 v100, v100, v101
	v_cvt_pk_bf16_f32 v101, v102, v103
	ds_write_b16 v138, v100
	ds_write_b16_d16_hi v139, v100 offset:512
	ds_write_b16 v136, v101 offset:1024
	ds_write_b16_d16_hi v137, v101 offset:1536
	v_cvt_pk_bf16_f32 v96, v96, v97
	v_cvt_pk_bf16_f32 v97, v98, v99
	ds_write_b16 v138, v96 offset:8448
	ds_write_b16_d16_hi v139, v96 offset:8960
	ds_write_b16 v136, v97 offset:9472
	ds_write_b16_d16_hi v137, v97 offset:9984
	v_cvt_pk_bf16_f32 v92, v92, v93
	v_cvt_pk_bf16_f32 v93, v94, v95
	ds_write_b16 v132, v92
	ds_write_b16_d16_hi v133, v92 offset:512
	ds_write_b16 v134, v93 offset:1024
	ds_write_b16_d16_hi v135, v93 offset:1536
	v_cvt_pk_bf16_f32 v88, v88, v89
; DEV u32x2 pk4(f32x4 v) { u32x2 r = {pk_bf16(v[0], v[1]), pk_bf16(v[2], v[3])}; return r; }
;   DEV void operator()(f32x4 (&acc)[2][2][4][2], int brow, int bcol, int wr, int wc, int fr, int fq) const {
;     ...
;               const u32x2 kk = pk4((f32x4){v[0] * __expf(bl[0] - b4[0]), v[1] * __expf(bl[1] - b4[1]), v[2] * __expf(bl[2] - b4[2]), v[3] * __expf(bl[3] - b4[3])});
; #pragma unroll
;               for (int j = 0; j < 4; ++j) {
;                 const int row = cl + j;
;                 const unsigned short val = (unsigned short)((j & 1) ? (kk[j >> 1] >> 16) : (kk[j >> 1] & 0xffff));
;                 *(unsigned short*)(smem + row * 512 + (((tposl >> 3) ^ (row & 31)) * 16) + (tposl & 7) * 2) = val;
;               }
;             }
;         }
;       __syncthreads();
;       const int bt = brow >> 11, tl0 = brow & 2047, hd = (bcol - segstart) >> 8;
;       tile_rows_out<true>(keT + ((size_t)((bt * 4 + hd) * 256)) * 2048 + tl0, 2048, (wr * 4 + wc) * 64 + fq * 16 + fr);
	v_cvt_pk_bf16_f32 v89, v90, v91
	ds_write_b16 v132, v88 offset:8448
	ds_write_b16_d16_hi v133, v88 offset:8960
	ds_write_b16 v134, v89 offset:9472
	ds_write_b16_d16_hi v135, v89 offset:9984
	v_cvt_pk_bf16_f32 v84, v84, v85
	v_cvt_pk_bf16_f32 v85, v86, v87
	ds_write_b16 v140, v84
	ds_write_b16_d16_hi v141, v84 offset:512
	ds_write_b16 v142, v85 offset:1024
	ds_write_b16_d16_hi v143, v85 offset:1536
	v_cvt_pk_bf16_f32 v80, v80, v81
	v_cvt_pk_bf16_f32 v81, v82, v83
	ds_write_b16 v140, v80 offset:8448
	ds_write_b16_d16_hi v141, v80 offset:8960
	ds_write_b16 v142, v81 offset:9472
	ds_write_b16_d16_hi v143, v81 offset:9984
	v_cvt_pk_bf16_f32 v76, v76, v77
	v_cvt_pk_bf16_f32 v77, v78, v79
	ds_write_b16 v134, v76
	ds_write_b16_d16_hi v135, v76 offset:512
	ds_write_b16 v132, v77 offset:1024
	ds_write_b16_d16_hi v133, v77 offset:1536
	v_cvt_pk_bf16_f32 v72, v72, v73
	v_cvt_pk_bf16_f32 v73, v74, v75
	ds_write_b16 v134, v72 offset:8448
	ds_write_b16_d16_hi v135, v72 offset:8960
	ds_write_b16 v132, v73 offset:9472
	ds_write_b16_d16_hi v133, v73 offset:9984
	v_cvt_pk_bf16_f32 v68, v68, v69
	v_cvt_pk_bf16_f32 v69, v70, v71
	ds_write_b16 v142, v68
	ds_write_b16_d16_hi v143, v68 offset:512
	ds_write_b16 v140, v69 offset:1024
	ds_write_b16_d16_hi v141, v69 offset:1536
	v_cvt_pk_bf16_f32 v64, v64, v65
	v_cvt_pk_bf16_f32 v65, v66, v67
	ds_write_b16 v142, v64 offset:8448
	ds_write_b16_d16_hi v143, v64 offset:8960
	ds_write_b16 v140, v65 offset:9472
	ds_write_b16_d16_hi v141, v65 offset:9984
	v_cvt_pk_bf16_f32 v60, v60, v61
	v_cvt_pk_bf16_f32 v61, v62, v63
	ds_write_b16 v128, v60 offset:256
	ds_write_b16_d16_hi v129, v60 offset:768
	ds_write_b16 v130, v61 offset:1280
	ds_write_b16_d16_hi v131, v61 offset:1792
	v_cvt_pk_bf16_f32 v56, v56, v57
	v_cvt_pk_bf16_f32 v57, v58, v59
	ds_write_b16 v128, v56 offset:8192
	ds_write_b16_d16_hi v129, v56 offset:8704
	ds_write_b16 v130, v57 offset:9216
	ds_write_b16_d16_hi v131, v57 offset:9728
	v_cvt_pk_bf16_f32 v52, v52, v53
	v_cvt_pk_bf16_f32 v53, v54, v55
	ds_write_b16 v136, v52 offset:256
	ds_write_b16_d16_hi v137, v52 offset:768
	ds_write_b16 v138, v53 offset:1280
	ds_write_b16_d16_hi v139, v53 offset:1792
	v_cvt_pk_bf16_f32 v48, v48, v49
	v_cvt_pk_bf16_f32 v49, v50, v51
	ds_write_b16 v136, v48 offset:8192
	ds_write_b16_d16_hi v137, v48 offset:8704
	ds_write_b16 v138, v49 offset:9216
	ds_write_b16_d16_hi v139, v49 offset:9728
	v_cvt_pk_bf16_f32 v44, v44, v45
	v_cvt_pk_bf16_f32 v45, v46, v47
	ds_write_b16 v130, v44 offset:256
	ds_write_b16_d16_hi v131, v44 offset:768
	ds_write_b16 v128, v45 offset:1280
	ds_write_b16_d16_hi v129, v45 offset:1792
	v_cvt_pk_bf16_f32 v40, v40, v41
	v_cvt_pk_bf16_f32 v41, v42, v43
	ds_write_b16 v130, v40 offset:8192
	ds_write_b16_d16_hi v131, v40 offset:8704
	ds_write_b16 v128, v41 offset:9216
	ds_write_b16_d16_hi v129, v41 offset:9728
	v_cvt_pk_bf16_f32 v36, v36, v37
	v_cvt_pk_bf16_f32 v37, v38, v39
	ds_write_b16 v138, v36 offset:256
	ds_write_b16_d16_hi v139, v36 offset:768
	ds_write_b16 v136, v37 offset:1280
	ds_write_b16_d16_hi v137, v37 offset:1792
	v_cvt_pk_bf16_f32 v32, v32, v33
	v_cvt_pk_bf16_f32 v33, v34, v35
	ds_write_b16 v138, v32 offset:8192
	ds_write_b16_d16_hi v139, v32 offset:8704
	ds_write_b16 v136, v33 offset:9216
	ds_write_b16_d16_hi v137, v33 offset:9728
	v_cvt_pk_bf16_f32 v28, v28, v29
	v_cvt_pk_bf16_f32 v29, v30, v31
	ds_write_b16 v132, v28 offset:256
	ds_write_b16_d16_hi v133, v28 offset:768
	ds_write_b16 v134, v29 offset:1280
	ds_write_b16_d16_hi v135, v29 offset:1792
	v_cvt_pk_bf16_f32 v24, v24, v25
	v_cvt_pk_bf16_f32 v25, v26, v27
	ds_write_b16 v132, v24 offset:8192
	ds_write_b16_d16_hi v133, v24 offset:8704
	ds_write_b16 v134, v25 offset:9216
	ds_write_b16_d16_hi v135, v25 offset:9728
	v_cvt_pk_bf16_f32 v20, v20, v21
	v_cvt_pk_bf16_f32 v21, v22, v23
	ds_write_b16 v140, v20 offset:256
	ds_write_b16_d16_hi v141, v20 offset:768
	ds_write_b16 v142, v21 offset:1280
	ds_write_b16_d16_hi v143, v21 offset:1792
	v_cvt_pk_bf16_f32 v16, v16, v17
	v_cvt_pk_bf16_f32 v17, v18, v19
	ds_write_b16 v140, v16 offset:8192
	ds_write_b16_d16_hi v141, v16 offset:8704
	ds_write_b16 v142, v17 offset:9216
	ds_write_b16_d16_hi v143, v17 offset:9728
	v_cvt_pk_bf16_f32 v12, v12, v13
	v_cvt_pk_bf16_f32 v13, v14, v15
	ds_write_b16 v134, v12 offset:256
	ds_write_b16_d16_hi v135, v12 offset:768
	ds_write_b16 v132, v13 offset:1280
	ds_write_b16_d16_hi v133, v13 offset:1792
	v_cvt_pk_bf16_f32 v8, v8, v9
	v_cvt_pk_bf16_f32 v9, v10, v11
	ds_write_b16 v134, v8 offset:8192
	ds_write_b16_d16_hi v135, v8 offset:8704
	ds_write_b16 v132, v9 offset:9216
	ds_write_b16_d16_hi v133, v9 offset:9728
	v_cvt_pk_bf16_f32 v4, v4, v5
	v_cvt_pk_bf16_f32 v5, v6, v7
	ds_write_b16 v142, v4 offset:256
	ds_write_b16_d16_hi v143, v4 offset:768
	ds_write_b16 v140, v5 offset:1280
	ds_write_b16_d16_hi v141, v5 offset:1792
	v_cvt_pk_bf16_f32 v0, v0, v1
	v_cvt_pk_bf16_f32 v1, v2, v3
	ds_write_b16 v142, v0 offset:8192
	ds_write_b16_d16_hi v143, v0 offset:8704
	ds_write_b16 v140, v1 offset:9216
	ds_write_b16_d16_hi v141, v1 offset:9728
	v_readlane_b32 s0, v253, 25
	v_readlane_b32 s1, v253, 26
	s_lshr_b32 s20, s4, 11
	s_lshl_b32 s20, s20, 2
	s_sub_i32 s21, s6, s36
	s_lshr_b32 s21, s21, 8
	s_add_i32 s20, s20, s21
	s_lshl_b32 s20, s20, 19
	s_and_b32 s21, s4, 0x7ff
	s_add_i32 s20, s20, s21
	s_lshl_b32 s20, s20, 1
	s_add_u32 s0, s0, s20
	s_addc_u32 s1, s1, 0
	v_lshrrev_b32_e32 v138, 5, v198
	v_and_b32_e32 v139, 31, v198
	v_xor_b32_e32 v139, v139, v138
	v_mul_u32_u24_e32 v140, 4096, v138
	v_lshl_add_u32 v141, v139, 4, v140
	v_xor_b32_e32 v139, 16, v139
	v_lshl_add_u32 v142, v139, 4, v140
	v_add_u32_e32 v142, 0x10000, v142
	s_mov_b32 s5, 0x20000
	v_lshlrev_b32_e32 v143, 4, v198
	v_add_u32_e32 v144, 0x10000, v143
	s_waitcnt lgkmcnt(0)
	s_barrier
; template <bool NT = false>
; DEV void tile_rows_out(bf16_t* __restrict__ out0, const size_t ld, const int tid) {
; #pragma unroll
;   for (int i = 0; i < 16; ++i) {
;     const int id = i * 512 + tid, r = id >> 5, pos = id & 31, c = pos ^ (r & 31);
;     const u32x4 v = *(const u32x4*)(smem + r * 512 + pos * 16);
;     if (NT) __builtin_nontemporal_store(v, (u32x4*)(out0 + (size_t)r * ld + 8 * c)); else *(u32x4*)(out0 + (size_t)r * ld + 8 * c) = v;
;   }
;   DEV void operator()(f32x4 (&acc)[2][2][4][2], int brow, int bcol, int wr, int wc, int fr, int fq) const {
;     ...
;       tile_rows_out<true>(keT + ((size_t)((bt * 4 + hd) * 256)) * 2048 + tl0, 2048, (wr * 4 + wc) * 64 + fq * 16 + fr);
	ds_read_b128 v[0:3], v143
	ds_read_b128 v[4:7], v143 offset:8192
	ds_read_b128 v[8:11], v143 offset:16384
	ds_read_b128 v[12:15], v143 offset:24576
	ds_read_b128 v[16:19], v143 offset:32768
	ds_read_b128 v[20:23], v143 offset:40960
	ds_read_b128 v[24:27], v143 offset:49152
	ds_read_b128 v[28:31], v143 offset:57344
	ds_read_b128 v[32:35], v144
	ds_read_b128 v[36:39], v144 offset:8192
	ds_read_b128 v[40:43], v144 offset:16384
	ds_read_b128 v[44:47], v144 offset:24576
	ds_read_b128 v[48:51], v144 offset:32768
	ds_read_b128 v[52:55], v144 offset:40960
	ds_read_b128 v[56:59], v144 offset:49152
	ds_read_b128 v[60:63], v144 offset:57344
	s_waitcnt lgkmcnt(15)
	global_store_dwordx4 v141, v[0:3], s[0:1] nt
	v_add_u32_e32 v141, s5, v141
	s_waitcnt lgkmcnt(14)
	global_store_dwordx4 v142, v[4:7], s[0:1] nt
	v_add_u32_e32 v142, s5, v142
	s_waitcnt lgkmcnt(13)
	global_store_dwordx4 v141, v[8:11], s[0:1] nt
	v_add_u32_e32 v141, s5, v141
	s_waitcnt lgkmcnt(12)
	global_store_dwordx4 v142, v[12:15], s[0:1] nt
	v_add_u32_e32 v142, s5, v142
	s_waitcnt lgkmcnt(11)
	global_store_dwordx4 v141, v[16:19], s[0:1] nt
	v_add_u32_e32 v141, s5, v141
	s_waitcnt lgkmcnt(10)
	global_store_dwordx4 v142, v[20:23], s[0:1] nt
	v_add_u32_e32 v142, s5, v142
	s_waitcnt lgkmcnt(9)
	global_store_dwordx4 v141, v[24:27], s[0:1] nt
	v_add_u32_e32 v141, s5, v141
	s_waitcnt lgkmcnt(8)
	global_store_dwordx4 v142, v[28:31], s[0:1] nt
	v_add_u32_e32 v142, s5, v142
	s_waitcnt lgkmcnt(7)
	global_store_dwordx4 v141, v[32:35], s[0:1] nt
	v_add_u32_e32 v141, s5, v141
	s_waitcnt lgkmcnt(6)
	global_store_dwordx4 v142, v[36:39], s[0:1] nt
	v_add_u32_e32 v142, s5, v142
	s_waitcnt lgkmcnt(5)
	global_store_dwordx4 v141, v[40:43], s[0:1] nt
	v_add_u32_e32 v141, s5, v141
	s_waitcnt lgkmcnt(4)
	global_store_dwordx4 v142, v[44:47], s[0:1] nt
	v_add_u32_e32 v142, s5, v142
	s_waitcnt lgkmcnt(3)
	global_store_dwordx4 v141, v[48:51], s[0:1] nt
	v_add_u32_e32 v141, s5, v141
	s_waitcnt lgkmcnt(2)
	global_store_dwordx4 v142, v[52:55], s[0:1] nt
	v_add_u32_e32 v142, s5, v142
	s_waitcnt lgkmcnt(1)
	global_store_dwordx4 v141, v[56:59], s[0:1] nt
	s_waitcnt lgkmcnt(0)
	global_store_dwordx4 v142, v[60:63], s[0:1] nt
	s_branch .LBB0_1555
